# nt cache hint on the streaming stores of the resid passes (bf16 R, f32 out)
# baseline (speedup 1.0000x reference)
; __device__ __forceinline__ float bflo(unsigned w) { return __uint_as_float(w << 16); }
; __device__ __forceinline__ float bfhi(unsigned w) { return __uint_as_float(w & 0xffff0000u); }
; __device__ __forceinline__ void resid_rows(bf16_t* R, const bf16_t* Y, const float* ssqY, const float* g, float* rstd_out, float* outf, bool wf32, int row_lo, int row_hi, int yoff, int gw, int NGW, int lane) {
;     ...
;     for (int row0 = row_lo + gw; row0 < row_hi; row0 += RP * NGW) {
;         u32x4 rr[RP][2], oo[RP][2]; float ssv[RP];
; #pragma unroll
;         for (int k = 0; k < RP; ++k) { const int row = row0 + k * NGW; const bool ok = row < row_hi; const int rw = ok ? row : row0;
;             ssv[k] = ssqY[rw];
; #pragma unroll
;             for (int j = 0; j < 2; ++j) { const int c = 8 * lane + 512 * j; rr[k][j] = *(const u32x4*)(R + (size_t)rw * DM + c); oo[k][j] = *(const u32x4*)(Y + (size_t)(rw - yoff) * DM + c); } }
; #pragma unroll
;         for (int k = 0; k < RP; ++k) { const int row = row0 + k * NGW; if (row < row_hi) {
;             const float rs = __builtin_amdgcn_rsqf(ssv[k] * (1.0f / DM) + RMS_EPS); float s = 0.f;
; #pragma unroll
;             for (int j = 0; j < 2; ++j) { const int c = 8 * lane + 512 * j; const u32x4 r = rr[k][j], o = oo[k][j]; const f32x4 ga = gv[j][0], gb = gv[j][1];
;                 f32x4 ya, yb; ya[0] = bflo(r.x) + bflo(o.x) * rs * ga[0]; ya[1] = bfhi(r.x) + bfhi(o.x) * rs * ga[1]; ya[2] = bflo(r.y) + bflo(o.y) * rs * ga[2]; ya[3] = bfhi(r.y) + bfhi(o.y) * rs * ga[3];
;                 yb[0] = bflo(r.z) + bflo(o.z) * rs * gb[0]; yb[1] = bfhi(r.z) + bfhi(o.z) * rs * gb[1]; yb[2] = bflo(r.w) + bflo(o.w) * rs * gb[2]; yb[3] = bfhi(r.w) + bfhi(o.w) * rs * gb[3];
;                 if (wf32) { *(f32x4*)(outf + (size_t)row * DM + c) = ya; *(f32x4*)(outf + (size_t)row * DM + c + 4) = yb; }
;                 s += (ya[0] * ya[0] + ya[1] * ya[1]) + (ya[2] * ya[2] + ya[3] * ya[3]) + (yb[0] * yb[0] + yb[1] * yb[1]) + (yb[2] * yb[2] + yb[3] * yb[3]);
;                 u32x4 w; w.x = pk2(ya[0], ya[1]); w.y = pk2(ya[2], ya[3]); w.z = pk2(yb[0], yb[1]); w.w = pk2(yb[2], yb[3]); *(u32x4*)(R + (size_t)row * DM + c) = w; }
;             s = wave_sum(s); if (lane == 0) rstd_out[row] = __builtin_amdgcn_rsqf(s * (1.0f / DM) + RMS_EPS); } }
.LBB0_497:
	s_andn2_b64 vcc, exec, s[4:5]
	s_cbranch_vccnz .LBB0_566
	v_mov_b32_e32 v2, v0
	v_mov_b32_e32 v3, v0
	v_readlane_b32 s4, v255, 4
	v_ashrrev_i32_e32 v3, 6, v3
	s_mov_b64 s[6:7], s[0:1]
	v_add_u32_e32 v92, s4, v3
	s_mov_b64 s[4:5], s[0:1]
	s_mov_b64 s[8:9], s[0:1]
	s_mov_b64 s[14:15], s[0:1]
	v_cmp_gt_i32_e32 vcc, s45, v92
	s_and_saveexec_b64 s[12:13], vcc
	v_readlane_b32 s22, v255, 37
	v_readlane_b32 s23, v255, 38
	v_readlane_b32 s23, v255, 45
	s_cbranch_execz .LBB0_512
	v_lshrrev_b32_e32 v114, 6, v0
	v_readlane_b32 s14, v255, 49
	v_readlane_b32 s15, v255, 4
	v_readfirstlane_b32 s16, v114
	s_load_dwordx2 s[4:5], s[0:1], 0x98
	s_load_dwordx2 s[8:9], s[0:1], 0x20
	s_add_i32 s15, s15, s16
	v_and_b32_e32 v115, 63, v0
	v_lshlrev_b32_e32 v114, 4, v115
	v_lshlrev_b32_e32 v115, 5, v115
	s_lshl_b32 s16, s14, 12
	s_lshl_b32 s17, s14, 18
	s_bfm_b64 s[6:7], 1, 63
	s_waitcnt lgkmcnt(0)
	s_add_u32 s8, s8, s16
	s_addc_u32 s9, s9, 0
	global_load_dwordx4 v[2:5], v115, s[8:9] offset:2048
	global_load_dwordx4 v[6:9], v115, s[8:9] offset:2064
	global_load_dwordx4 v[10:13], v115, s[8:9]
	global_load_dwordx4 v[14:17], v115, s[8:9] offset:16
	s_lshl_b32 s16, s15, 11
	v_add_u32_e32 v18, s16, v114
	v_mov_b32_e32 v19, v18
	v_mov_b32_e32 v20, v18
	s_lshl_b32 s16, s15, 2
	v_mov_b32_e32 v22, s16
	s_add_i32 s16, s16, s17
	v_mov_b32_e32 v21, s16
	v_add_u32_e32 v18, 0x3001000, v18
	v_add_u32_e32 v20, 0x7800000, v20
	v_add_u32_e32 v21, 0x2d40000, v21
	global_load_dwordx4 v[24:27], v18, s[4:5]
	global_load_dwordx4 v[32:35], v20, s[4:5]
	global_load_dwordx4 v[28:31], v18, s[4:5] offset:1024
	global_load_dwordx4 v[36:39], v20, s[4:5] offset:1024
	global_load_dword v40, v21, s[4:5]
	v_add_u32_e32 v18, 0x400000, v18
	v_add_u32_e32 v20, 0x400000, v20
	v_add_u32_e32 v21, 0x2000, v21
	global_load_dwordx4 v[42:45], v18, s[4:5]
	global_load_dwordx4 v[50:53], v20, s[4:5]
	global_load_dwordx4 v[46:49], v18, s[4:5] offset:1024
	global_load_dwordx4 v[54:57], v20, s[4:5] offset:1024
	global_load_dword v58, v21, s[4:5]
	v_add_u32_e32 v18, 0x400000, v18
	v_add_u32_e32 v20, 0x400000, v20
	v_add_u32_e32 v21, 0x2000, v21
	global_load_dwordx4 v[60:63], v18, s[4:5]
	global_load_dwordx4 v[68:71], v20, s[4:5]
	global_load_dwordx4 v[64:67], v18, s[4:5] offset:1024
	global_load_dwordx4 v[72:75], v20, s[4:5] offset:1024
	global_load_dword v76, v21, s[4:5]
	v_add_u32_e32 v18, 0x400000, v18
	v_add_u32_e32 v20, 0x400000, v20
	v_add_u32_e32 v21, 0x2000, v21
	global_load_dwordx4 v[78:81], v18, s[4:5]
	global_load_dwordx4 v[86:89], v20, s[4:5]
	global_load_dwordx4 v[82:85], v18, s[4:5] offset:1024
	global_load_dwordx4 v[90:93], v20, s[4:5] offset:1024
	global_load_dword v94, v21, s[4:5]
	s_waitcnt vmcnt(15)
	v_fmamk_f32 v96, v40, 0x3a800000, v244
	v_rsq_f32_e32 v96, v96
	v_add_u32_e32 v19, 0x3001000, v19
	v_lshlrev_b32_e32 v106, 16, v32
	v_and_b32_e32 v107, 0xffff0000, v32
	v_lshlrev_b32_e32 v108, 16, v24
	v_and_b32_e32 v109, 0xffff0000, v24
	v_pk_mul_f32 v[106:107], v[96:97], v[106:107] op_sel_hi:[0,1]
	v_pk_fma_f32 v[98:99], v[10:11], v[106:107], v[108:109]
	v_lshlrev_b32_e32 v106, 16, v33
	v_and_b32_e32 v107, 0xffff0000, v33
	v_lshlrev_b32_e32 v108, 16, v25
	v_and_b32_e32 v109, 0xffff0000, v25
	v_pk_mul_f32 v[106:107], v[96:97], v[106:107] op_sel_hi:[0,1]
	v_pk_fma_f32 v[100:101], v[12:13], v[106:107], v[108:109]
	v_lshlrev_b32_e32 v106, 16, v34
	v_and_b32_e32 v107, 0xffff0000, v34
	v_lshlrev_b32_e32 v108, 16, v26
	v_and_b32_e32 v109, 0xffff0000, v26
	v_pk_mul_f32 v[106:107], v[96:97], v[106:107] op_sel_hi:[0,1]
	v_pk_fma_f32 v[102:103], v[14:15], v[106:107], v[108:109]
	v_lshlrev_b32_e32 v106, 16, v35
	v_and_b32_e32 v107, 0xffff0000, v35
	v_lshlrev_b32_e32 v108, 16, v27
	v_and_b32_e32 v109, 0xffff0000, v27
	v_pk_mul_f32 v[106:107], v[96:97], v[106:107] op_sel_hi:[0,1]
	v_pk_fma_f32 v[104:105], v[16:17], v[106:107], v[108:109]
	v_pk_mul_f32 v[110:111], v[98:99], v[98:99]
	v_pk_fma_f32 v[110:111], v[100:101], v[100:101], v[110:111]
	v_pk_fma_f32 v[110:111], v[102:103], v[102:103], v[110:111]
	v_pk_fma_f32 v[110:111], v[104:105], v[104:105], v[110:111]
	v_cvt_pk_bf16_f32 v24, v98, v99
	v_cvt_pk_bf16_f32 v25, v100, v101
	v_cvt_pk_bf16_f32 v26, v102, v103
	v_cvt_pk_bf16_f32 v27, v104, v105
	global_store_dwordx4 v19, v[24:27], s[4:5] nt
	v_lshlrev_b32_e32 v106, 16, v36
	v_and_b32_e32 v107, 0xffff0000, v36
	v_lshlrev_b32_e32 v108, 16, v28
	v_and_b32_e32 v109, 0xffff0000, v28
	v_pk_mul_f32 v[106:107], v[96:97], v[106:107] op_sel_hi:[0,1]
	v_pk_fma_f32 v[98:99], v[2:3], v[106:107], v[108:109]
	v_lshlrev_b32_e32 v106, 16, v37
	v_and_b32_e32 v107, 0xffff0000, v37
	v_lshlrev_b32_e32 v108, 16, v29
	v_and_b32_e32 v109, 0xffff0000, v29
	v_pk_mul_f32 v[106:107], v[96:97], v[106:107] op_sel_hi:[0,1]
	v_pk_fma_f32 v[100:101], v[4:5], v[106:107], v[108:109]
	v_lshlrev_b32_e32 v106, 16, v38
	v_and_b32_e32 v107, 0xffff0000, v38
	v_lshlrev_b32_e32 v108, 16, v30
	v_and_b32_e32 v109, 0xffff0000, v30
	v_pk_mul_f32 v[106:107], v[96:97], v[106:107] op_sel_hi:[0,1]
	v_pk_fma_f32 v[102:103], v[6:7], v[106:107], v[108:109]
	v_lshlrev_b32_e32 v106, 16, v39
	v_and_b32_e32 v107, 0xffff0000, v39
	v_lshlrev_b32_e32 v108, 16, v31
	v_and_b32_e32 v109, 0xffff0000, v31
	v_pk_mul_f32 v[106:107], v[96:97], v[106:107] op_sel_hi:[0,1]
	v_pk_fma_f32 v[104:105], v[8:9], v[106:107], v[108:109]
	v_pk_fma_f32 v[110:111], v[98:99], v[98:99], v[110:111]
	v_pk_fma_f32 v[110:111], v[100:101], v[100:101], v[110:111]
	v_pk_fma_f32 v[110:111], v[102:103], v[102:103], v[110:111]
	v_pk_fma_f32 v[110:111], v[104:105], v[104:105], v[110:111]
	v_cvt_pk_bf16_f32 v28, v98, v99
	v_cvt_pk_bf16_f32 v29, v100, v101
	v_cvt_pk_bf16_f32 v30, v102, v103
	v_cvt_pk_bf16_f32 v31, v104, v105
	global_store_dwordx4 v19, v[28:31], s[4:5] offset:1024 nt
	v_add_f32_e32 v112, v110, v111
	v_add_u32_e32 v22, 0x2d20000, v22
	s_nop 1
	v_add_f32_dpp v112, v112, v112 quad_perm:[1,0,3,2] row_mask:0xf bank_mask:0xf
	s_nop 1
	v_add_f32_dpp v112, v112, v112 quad_perm:[2,3,0,1] row_mask:0xf bank_mask:0xf
	s_nop 1
	v_add_f32_dpp v112, v112, v112 row_half_mirror row_mask:0xf bank_mask:0xf
	s_nop 1
	v_add_f32_dpp v112, v112, v112 row_mirror row_mask:0xf bank_mask:0xf
	s_nop 1
	v_add_f32_dpp v112, v112, v112 row_bcast:15 row_mask:0xa bank_mask:0xf
	s_nop 1
	v_add_f32_dpp v112, v112, v112 row_bcast:31 row_mask:0xc bank_mask:0xf
	v_fmamk_f32 v113, v112, 0x3a800000, v244
	v_rsq_f32_e32 v113, v113
	s_mov_b64 exec, s[6:7]
	global_store_dword v22, v113, s[4:5]
	s_mov_b64 exec, -1
	v_add_u32_e32 v18, 0x400000, v18
	v_add_u32_e32 v20, 0x400000, v20
	v_add_u32_e32 v21, 0x2000, v21
	global_load_dwordx4 v[24:27], v18, s[4:5]
	global_load_dwordx4 v[32:35], v20, s[4:5]
	global_load_dwordx4 v[28:31], v18, s[4:5] offset:1024
	global_load_dwordx4 v[36:39], v20, s[4:5] offset:1024
	global_load_dword v40, v21, s[4:5]
	s_waitcnt vmcnt(18)
; __device__ __forceinline__ float bflo(unsigned w) { return __uint_as_float(w << 16); }
; __device__ __forceinline__ float bfhi(unsigned w) { return __uint_as_float(w & 0xffff0000u); }
; __device__ __forceinline__ void resid_rows(bf16_t* R, const bf16_t* Y, const float* ssqY, const float* g, float* rstd_out, float* outf, bool wf32, int row_lo, int row_hi, int yoff, int gw, int NGW, int lane) {
;     ...
;     for (int row0 = row_lo + gw; row0 < row_hi; row0 += RP * NGW) {
;         u32x4 rr[RP][2], oo[RP][2]; float ssv[RP];
; #pragma unroll
;         for (int k = 0; k < RP; ++k) { const int row = row0 + k * NGW; const bool ok = row < row_hi; const int rw = ok ? row : row0;
;             ssv[k] = ssqY[rw];
; #pragma unroll
;             for (int j = 0; j < 2; ++j) { const int c = 8 * lane + 512 * j; rr[k][j] = *(const u32x4*)(R + (size_t)rw * DM + c); oo[k][j] = *(const u32x4*)(Y + (size_t)(rw - yoff) * DM + c); } }
; #pragma unroll
;         for (int k = 0; k < RP; ++k) { const int row = row0 + k * NGW; if (row < row_hi) {
;             const float rs = __builtin_amdgcn_rsqf(ssv[k] * (1.0f / DM) + RMS_EPS); float s = 0.f;
; #pragma unroll
;             for (int j = 0; j < 2; ++j) { const int c = 8 * lane + 512 * j; const u32x4 r = rr[k][j], o = oo[k][j]; const f32x4 ga = gv[j][0], gb = gv[j][1];
;                 f32x4 ya, yb; ya[0] = bflo(r.x) + bflo(o.x) * rs * ga[0]; ya[1] = bfhi(r.x) + bfhi(o.x) * rs * ga[1]; ya[2] = bflo(r.y) + bflo(o.y) * rs * ga[2]; ya[3] = bfhi(r.y) + bfhi(o.y) * rs * ga[3];
;                 yb[0] = bflo(r.z) + bflo(o.z) * rs * gb[0]; yb[1] = bfhi(r.z) + bfhi(o.z) * rs * gb[1]; yb[2] = bflo(r.w) + bflo(o.w) * rs * gb[2]; yb[3] = bfhi(r.w) + bfhi(o.w) * rs * gb[3];
;                 if (wf32) { *(f32x4*)(outf + (size_t)row * DM + c) = ya; *(f32x4*)(outf + (size_t)row * DM + c + 4) = yb; }
;                 s += (ya[0] * ya[0] + ya[1] * ya[1]) + (ya[2] * ya[2] + ya[3] * ya[3]) + (yb[0] * yb[0] + yb[1] * yb[1]) + (yb[2] * yb[2] + yb[3] * yb[3]);
;                 u32x4 w; w.x = pk2(ya[0], ya[1]); w.y = pk2(ya[2], ya[3]); w.z = pk2(yb[0], yb[1]); w.w = pk2(yb[2], yb[3]); *(u32x4*)(R + (size_t)row * DM + c) = w; }
;             s = wave_sum(s); if (lane == 0) rstd_out[row] = __builtin_amdgcn_rsqf(s * (1.0f / DM) + RMS_EPS); } }
	v_fmamk_f32 v96, v58, 0x3a800000, v244
	v_rsq_f32_e32 v96, v96
	v_add_u32_e32 v19, 0x400000, v19
	v_lshlrev_b32_e32 v106, 16, v50
	v_and_b32_e32 v107, 0xffff0000, v50
	v_lshlrev_b32_e32 v108, 16, v42
	v_and_b32_e32 v109, 0xffff0000, v42
	v_pk_mul_f32 v[106:107], v[96:97], v[106:107] op_sel_hi:[0,1]
	v_pk_fma_f32 v[98:99], v[10:11], v[106:107], v[108:109]
	v_lshlrev_b32_e32 v106, 16, v51
	v_and_b32_e32 v107, 0xffff0000, v51
	v_lshlrev_b32_e32 v108, 16, v43
	v_and_b32_e32 v109, 0xffff0000, v43
	v_pk_mul_f32 v[106:107], v[96:97], v[106:107] op_sel_hi:[0,1]
	v_pk_fma_f32 v[100:101], v[12:13], v[106:107], v[108:109]
	v_lshlrev_b32_e32 v106, 16, v52
	v_and_b32_e32 v107, 0xffff0000, v52
	v_lshlrev_b32_e32 v108, 16, v44
	v_and_b32_e32 v109, 0xffff0000, v44
	v_pk_mul_f32 v[106:107], v[96:97], v[106:107] op_sel_hi:[0,1]
	v_pk_fma_f32 v[102:103], v[14:15], v[106:107], v[108:109]
	v_lshlrev_b32_e32 v106, 16, v53
	v_and_b32_e32 v107, 0xffff0000, v53
	v_lshlrev_b32_e32 v108, 16, v45
	v_and_b32_e32 v109, 0xffff0000, v45
	v_pk_mul_f32 v[106:107], v[96:97], v[106:107] op_sel_hi:[0,1]
	v_pk_fma_f32 v[104:105], v[16:17], v[106:107], v[108:109]
	v_pk_mul_f32 v[110:111], v[98:99], v[98:99]
	v_pk_fma_f32 v[110:111], v[100:101], v[100:101], v[110:111]
	v_pk_fma_f32 v[110:111], v[102:103], v[102:103], v[110:111]
	v_pk_fma_f32 v[110:111], v[104:105], v[104:105], v[110:111]
	v_cvt_pk_bf16_f32 v42, v98, v99
	v_cvt_pk_bf16_f32 v43, v100, v101
	v_cvt_pk_bf16_f32 v44, v102, v103
	v_cvt_pk_bf16_f32 v45, v104, v105
	global_store_dwordx4 v19, v[42:45], s[4:5] nt
	v_lshlrev_b32_e32 v106, 16, v54
	v_and_b32_e32 v107, 0xffff0000, v54
	v_lshlrev_b32_e32 v108, 16, v46
	v_and_b32_e32 v109, 0xffff0000, v46
	v_pk_mul_f32 v[106:107], v[96:97], v[106:107] op_sel_hi:[0,1]
	v_pk_fma_f32 v[98:99], v[2:3], v[106:107], v[108:109]
	v_lshlrev_b32_e32 v106, 16, v55
	v_and_b32_e32 v107, 0xffff0000, v55
	v_lshlrev_b32_e32 v108, 16, v47
	v_and_b32_e32 v109, 0xffff0000, v47
	v_pk_mul_f32 v[106:107], v[96:97], v[106:107] op_sel_hi:[0,1]
	v_pk_fma_f32 v[100:101], v[4:5], v[106:107], v[108:109]
	v_lshlrev_b32_e32 v106, 16, v56
	v_and_b32_e32 v107, 0xffff0000, v56
	v_lshlrev_b32_e32 v108, 16, v48
	v_and_b32_e32 v109, 0xffff0000, v48
	v_pk_mul_f32 v[106:107], v[96:97], v[106:107] op_sel_hi:[0,1]
	v_pk_fma_f32 v[102:103], v[6:7], v[106:107], v[108:109]
	v_lshlrev_b32_e32 v106, 16, v57
	v_and_b32_e32 v107, 0xffff0000, v57
	v_lshlrev_b32_e32 v108, 16, v49
	v_and_b32_e32 v109, 0xffff0000, v49
	v_pk_mul_f32 v[106:107], v[96:97], v[106:107] op_sel_hi:[0,1]
	v_pk_fma_f32 v[104:105], v[8:9], v[106:107], v[108:109]
	v_pk_fma_f32 v[110:111], v[98:99], v[98:99], v[110:111]
	v_pk_fma_f32 v[110:111], v[100:101], v[100:101], v[110:111]
	v_pk_fma_f32 v[110:111], v[102:103], v[102:103], v[110:111]
	v_pk_fma_f32 v[110:111], v[104:105], v[104:105], v[110:111]
	v_cvt_pk_bf16_f32 v46, v98, v99
	v_cvt_pk_bf16_f32 v47, v100, v101
	v_cvt_pk_bf16_f32 v48, v102, v103
	v_cvt_pk_bf16_f32 v49, v104, v105
	global_store_dwordx4 v19, v[46:49], s[4:5] offset:1024 nt
	v_add_f32_e32 v112, v110, v111
	v_add_u32_e32 v22, 0x2000, v22
	s_nop 1
	v_add_f32_dpp v112, v112, v112 quad_perm:[1,0,3,2] row_mask:0xf bank_mask:0xf
	s_nop 1
	v_add_f32_dpp v112, v112, v112 quad_perm:[2,3,0,1] row_mask:0xf bank_mask:0xf
	s_nop 1
	v_add_f32_dpp v112, v112, v112 row_half_mirror row_mask:0xf bank_mask:0xf
	s_nop 1
	v_add_f32_dpp v112, v112, v112 row_mirror row_mask:0xf bank_mask:0xf
	s_nop 1
	v_add_f32_dpp v112, v112, v112 row_bcast:15 row_mask:0xa bank_mask:0xf
	s_nop 1
	v_add_f32_dpp v112, v112, v112 row_bcast:31 row_mask:0xc bank_mask:0xf
	v_fmamk_f32 v113, v112, 0x3a800000, v244
	v_rsq_f32_e32 v113, v113
	s_mov_b64 exec, s[6:7]
	global_store_dword v22, v113, s[4:5]
	s_mov_b64 exec, -1
	v_add_u32_e32 v18, 0x400000, v18
	v_add_u32_e32 v20, 0x400000, v20
	v_add_u32_e32 v21, 0x2000, v21
	global_load_dwordx4 v[42:45], v18, s[4:5]
	global_load_dwordx4 v[50:53], v20, s[4:5]
	global_load_dwordx4 v[46:49], v18, s[4:5] offset:1024
	global_load_dwordx4 v[54:57], v20, s[4:5] offset:1024
	global_load_dword v58, v21, s[4:5]
	s_waitcnt vmcnt(21)
	v_fmamk_f32 v96, v76, 0x3a800000, v244
	v_rsq_f32_e32 v96, v96
	v_add_u32_e32 v19, 0x400000, v19
	v_lshlrev_b32_e32 v106, 16, v68
	v_and_b32_e32 v107, 0xffff0000, v68
	v_lshlrev_b32_e32 v108, 16, v60
	v_and_b32_e32 v109, 0xffff0000, v60
	v_pk_mul_f32 v[106:107], v[96:97], v[106:107] op_sel_hi:[0,1]
	v_pk_fma_f32 v[98:99], v[10:11], v[106:107], v[108:109]
	v_lshlrev_b32_e32 v106, 16, v69
	v_and_b32_e32 v107, 0xffff0000, v69
	v_lshlrev_b32_e32 v108, 16, v61
	v_and_b32_e32 v109, 0xffff0000, v61
	v_pk_mul_f32 v[106:107], v[96:97], v[106:107] op_sel_hi:[0,1]
	v_pk_fma_f32 v[100:101], v[12:13], v[106:107], v[108:109]
	v_lshlrev_b32_e32 v106, 16, v70
	v_and_b32_e32 v107, 0xffff0000, v70
	v_lshlrev_b32_e32 v108, 16, v62
	v_and_b32_e32 v109, 0xffff0000, v62
	v_pk_mul_f32 v[106:107], v[96:97], v[106:107] op_sel_hi:[0,1]
	v_pk_fma_f32 v[102:103], v[14:15], v[106:107], v[108:109]
	v_lshlrev_b32_e32 v106, 16, v71
	v_and_b32_e32 v107, 0xffff0000, v71
	v_lshlrev_b32_e32 v108, 16, v63
	v_and_b32_e32 v109, 0xffff0000, v63
	v_pk_mul_f32 v[106:107], v[96:97], v[106:107] op_sel_hi:[0,1]
	v_pk_fma_f32 v[104:105], v[16:17], v[106:107], v[108:109]
	v_pk_mul_f32 v[110:111], v[98:99], v[98:99]
	v_pk_fma_f32 v[110:111], v[100:101], v[100:101], v[110:111]
	v_pk_fma_f32 v[110:111], v[102:103], v[102:103], v[110:111]
	v_pk_fma_f32 v[110:111], v[104:105], v[104:105], v[110:111]
	v_cvt_pk_bf16_f32 v60, v98, v99
	v_cvt_pk_bf16_f32 v61, v100, v101
	v_cvt_pk_bf16_f32 v62, v102, v103
	v_cvt_pk_bf16_f32 v63, v104, v105
	global_store_dwordx4 v19, v[60:63], s[4:5] nt
; __device__ __forceinline__ float bflo(unsigned w) { return __uint_as_float(w << 16); }
; __device__ __forceinline__ float bfhi(unsigned w) { return __uint_as_float(w & 0xffff0000u); }
; __device__ __forceinline__ void resid_rows(bf16_t* R, const bf16_t* Y, const float* ssqY, const float* g, float* rstd_out, float* outf, bool wf32, int row_lo, int row_hi, int yoff, int gw, int NGW, int lane) {
;     ...
;     for (int row0 = row_lo + gw; row0 < row_hi; row0 += RP * NGW) {
;         u32x4 rr[RP][2], oo[RP][2]; float ssv[RP];
; #pragma unroll
;         for (int k = 0; k < RP; ++k) { const int row = row0 + k * NGW; const bool ok = row < row_hi; const int rw = ok ? row : row0;
;             ssv[k] = ssqY[rw];
; #pragma unroll
;             for (int j = 0; j < 2; ++j) { const int c = 8 * lane + 512 * j; rr[k][j] = *(const u32x4*)(R + (size_t)rw * DM + c); oo[k][j] = *(const u32x4*)(Y + (size_t)(rw - yoff) * DM + c); } }
; #pragma unroll
;         for (int k = 0; k < RP; ++k) { const int row = row0 + k * NGW; if (row < row_hi) {
;             const float rs = __builtin_amdgcn_rsqf(ssv[k] * (1.0f / DM) + RMS_EPS); float s = 0.f;
; #pragma unroll
;             for (int j = 0; j < 2; ++j) { const int c = 8 * lane + 512 * j; const u32x4 r = rr[k][j], o = oo[k][j]; const f32x4 ga = gv[j][0], gb = gv[j][1];
;                 f32x4 ya, yb; ya[0] = bflo(r.x) + bflo(o.x) * rs * ga[0]; ya[1] = bfhi(r.x) + bfhi(o.x) * rs * ga[1]; ya[2] = bflo(r.y) + bflo(o.y) * rs * ga[2]; ya[3] = bfhi(r.y) + bfhi(o.y) * rs * ga[3];
;                 yb[0] = bflo(r.z) + bflo(o.z) * rs * gb[0]; yb[1] = bfhi(r.z) + bfhi(o.z) * rs * gb[1]; yb[2] = bflo(r.w) + bflo(o.w) * rs * gb[2]; yb[3] = bfhi(r.w) + bfhi(o.w) * rs * gb[3];
;                 if (wf32) { *(f32x4*)(outf + (size_t)row * DM + c) = ya; *(f32x4*)(outf + (size_t)row * DM + c + 4) = yb; }
;                 s += (ya[0] * ya[0] + ya[1] * ya[1]) + (ya[2] * ya[2] + ya[3] * ya[3]) + (yb[0] * yb[0] + yb[1] * yb[1]) + (yb[2] * yb[2] + yb[3] * yb[3]);
;                 u32x4 w; w.x = pk2(ya[0], ya[1]); w.y = pk2(ya[2], ya[3]); w.z = pk2(yb[0], yb[1]); w.w = pk2(yb[2], yb[3]); *(u32x4*)(R + (size_t)row * DM + c) = w; }
;             s = wave_sum(s); if (lane == 0) rstd_out[row] = __builtin_amdgcn_rsqf(s * (1.0f / DM) + RMS_EPS); } }
	v_lshlrev_b32_e32 v106, 16, v72
	v_and_b32_e32 v107, 0xffff0000, v72
	v_lshlrev_b32_e32 v108, 16, v64
	v_and_b32_e32 v109, 0xffff0000, v64
	v_pk_mul_f32 v[106:107], v[96:97], v[106:107] op_sel_hi:[0,1]
	v_pk_fma_f32 v[98:99], v[2:3], v[106:107], v[108:109]
	v_lshlrev_b32_e32 v106, 16, v73
	v_and_b32_e32 v107, 0xffff0000, v73
	v_lshlrev_b32_e32 v108, 16, v65
	v_and_b32_e32 v109, 0xffff0000, v65
	v_pk_mul_f32 v[106:107], v[96:97], v[106:107] op_sel_hi:[0,1]
	v_pk_fma_f32 v[100:101], v[4:5], v[106:107], v[108:109]
	v_lshlrev_b32_e32 v106, 16, v74
	v_and_b32_e32 v107, 0xffff0000, v74
	v_lshlrev_b32_e32 v108, 16, v66
	v_and_b32_e32 v109, 0xffff0000, v66
	v_pk_mul_f32 v[106:107], v[96:97], v[106:107] op_sel_hi:[0,1]
	v_pk_fma_f32 v[102:103], v[6:7], v[106:107], v[108:109]
	v_lshlrev_b32_e32 v106, 16, v75
	v_and_b32_e32 v107, 0xffff0000, v75
	v_lshlrev_b32_e32 v108, 16, v67
	v_and_b32_e32 v109, 0xffff0000, v67
	v_pk_mul_f32 v[106:107], v[96:97], v[106:107] op_sel_hi:[0,1]
	v_pk_fma_f32 v[104:105], v[8:9], v[106:107], v[108:109]
	v_pk_fma_f32 v[110:111], v[98:99], v[98:99], v[110:111]
	v_pk_fma_f32 v[110:111], v[100:101], v[100:101], v[110:111]
	v_pk_fma_f32 v[110:111], v[102:103], v[102:103], v[110:111]
	v_pk_fma_f32 v[110:111], v[104:105], v[104:105], v[110:111]
	v_cvt_pk_bf16_f32 v64, v98, v99
	v_cvt_pk_bf16_f32 v65, v100, v101
	v_cvt_pk_bf16_f32 v66, v102, v103
	v_cvt_pk_bf16_f32 v67, v104, v105
	global_store_dwordx4 v19, v[64:67], s[4:5] offset:1024 nt
	v_add_f32_e32 v112, v110, v111
	v_add_u32_e32 v22, 0x2000, v22
	s_nop 1
	v_add_f32_dpp v112, v112, v112 quad_perm:[1,0,3,2] row_mask:0xf bank_mask:0xf
	s_nop 1
	v_add_f32_dpp v112, v112, v112 quad_perm:[2,3,0,1] row_mask:0xf bank_mask:0xf
	s_nop 1
	v_add_f32_dpp v112, v112, v112 row_half_mirror row_mask:0xf bank_mask:0xf
	s_nop 1
	v_add_f32_dpp v112, v112, v112 row_mirror row_mask:0xf bank_mask:0xf
	s_nop 1
	v_add_f32_dpp v112, v112, v112 row_bcast:15 row_mask:0xa bank_mask:0xf
	s_nop 1
	v_add_f32_dpp v112, v112, v112 row_bcast:31 row_mask:0xc bank_mask:0xf
	v_fmamk_f32 v113, v112, 0x3a800000, v244
	v_rsq_f32_e32 v113, v113
	s_mov_b64 exec, s[6:7]
	global_store_dword v22, v113, s[4:5]
	s_mov_b64 exec, -1
	v_add_u32_e32 v18, 0x400000, v18
	v_add_u32_e32 v20, 0x400000, v20
	v_add_u32_e32 v21, 0x2000, v21
	global_load_dwordx4 v[60:63], v18, s[4:5]
	global_load_dwordx4 v[68:71], v20, s[4:5]
	global_load_dwordx4 v[64:67], v18, s[4:5] offset:1024
	global_load_dwordx4 v[72:75], v20, s[4:5] offset:1024
	global_load_dword v76, v21, s[4:5]
	s_waitcnt vmcnt(24)
	v_fmamk_f32 v96, v94, 0x3a800000, v244
	v_rsq_f32_e32 v96, v96
	v_add_u32_e32 v19, 0x400000, v19
	v_lshlrev_b32_e32 v106, 16, v86
	v_and_b32_e32 v107, 0xffff0000, v86
	v_lshlrev_b32_e32 v108, 16, v78
	v_and_b32_e32 v109, 0xffff0000, v78
	v_pk_mul_f32 v[106:107], v[96:97], v[106:107] op_sel_hi:[0,1]
	v_pk_fma_f32 v[98:99], v[10:11], v[106:107], v[108:109]
	v_lshlrev_b32_e32 v106, 16, v87
	v_and_b32_e32 v107, 0xffff0000, v87
	v_lshlrev_b32_e32 v108, 16, v79
	v_and_b32_e32 v109, 0xffff0000, v79
	v_pk_mul_f32 v[106:107], v[96:97], v[106:107] op_sel_hi:[0,1]
	v_pk_fma_f32 v[100:101], v[12:13], v[106:107], v[108:109]
	v_lshlrev_b32_e32 v106, 16, v88
	v_and_b32_e32 v107, 0xffff0000, v88
	v_lshlrev_b32_e32 v108, 16, v80
	v_and_b32_e32 v109, 0xffff0000, v80
	v_pk_mul_f32 v[106:107], v[96:97], v[106:107] op_sel_hi:[0,1]
	v_pk_fma_f32 v[102:103], v[14:15], v[106:107], v[108:109]
	v_lshlrev_b32_e32 v106, 16, v89
	v_and_b32_e32 v107, 0xffff0000, v89
	v_lshlrev_b32_e32 v108, 16, v81
	v_and_b32_e32 v109, 0xffff0000, v81
	v_pk_mul_f32 v[106:107], v[96:97], v[106:107] op_sel_hi:[0,1]
	v_pk_fma_f32 v[104:105], v[16:17], v[106:107], v[108:109]
	v_pk_mul_f32 v[110:111], v[98:99], v[98:99]
	v_pk_fma_f32 v[110:111], v[100:101], v[100:101], v[110:111]
	v_pk_fma_f32 v[110:111], v[102:103], v[102:103], v[110:111]
	v_pk_fma_f32 v[110:111], v[104:105], v[104:105], v[110:111]
	v_cvt_pk_bf16_f32 v78, v98, v99
	v_cvt_pk_bf16_f32 v79, v100, v101
	v_cvt_pk_bf16_f32 v80, v102, v103
	v_cvt_pk_bf16_f32 v81, v104, v105
	global_store_dwordx4 v19, v[78:81], s[4:5] nt
	v_lshlrev_b32_e32 v106, 16, v90
	v_and_b32_e32 v107, 0xffff0000, v90
	v_lshlrev_b32_e32 v108, 16, v82
	v_and_b32_e32 v109, 0xffff0000, v82
	v_pk_mul_f32 v[106:107], v[96:97], v[106:107] op_sel_hi:[0,1]
	v_pk_fma_f32 v[98:99], v[2:3], v[106:107], v[108:109]
	v_lshlrev_b32_e32 v106, 16, v91
	v_and_b32_e32 v107, 0xffff0000, v91
	v_lshlrev_b32_e32 v108, 16, v83
	v_and_b32_e32 v109, 0xffff0000, v83
	v_pk_mul_f32 v[106:107], v[96:97], v[106:107] op_sel_hi:[0,1]
	v_pk_fma_f32 v[100:101], v[4:5], v[106:107], v[108:109]
	v_lshlrev_b32_e32 v106, 16, v92
	v_and_b32_e32 v107, 0xffff0000, v92
	v_lshlrev_b32_e32 v108, 16, v84
	v_and_b32_e32 v109, 0xffff0000, v84
	v_pk_mul_f32 v[106:107], v[96:97], v[106:107] op_sel_hi:[0,1]
	v_pk_fma_f32 v[102:103], v[6:7], v[106:107], v[108:109]
	v_lshlrev_b32_e32 v106, 16, v93
	v_and_b32_e32 v107, 0xffff0000, v93
	v_lshlrev_b32_e32 v108, 16, v85
	v_and_b32_e32 v109, 0xffff0000, v85
	v_pk_mul_f32 v[106:107], v[96:97], v[106:107] op_sel_hi:[0,1]
	v_pk_fma_f32 v[104:105], v[8:9], v[106:107], v[108:109]
	v_pk_fma_f32 v[110:111], v[98:99], v[98:99], v[110:111]
	v_pk_fma_f32 v[110:111], v[100:101], v[100:101], v[110:111]
	v_pk_fma_f32 v[110:111], v[102:103], v[102:103], v[110:111]
	v_pk_fma_f32 v[110:111], v[104:105], v[104:105], v[110:111]
	v_cvt_pk_bf16_f32 v82, v98, v99
	v_cvt_pk_bf16_f32 v83, v100, v101
	v_cvt_pk_bf16_f32 v84, v102, v103
	v_cvt_pk_bf16_f32 v85, v104, v105
	global_store_dwordx4 v19, v[82:85], s[4:5] offset:1024 nt
	v_add_f32_e32 v112, v110, v111
	v_add_u32_e32 v22, 0x2000, v22
	s_nop 1
	v_add_f32_dpp v112, v112, v112 quad_perm:[1,0,3,2] row_mask:0xf bank_mask:0xf
	s_nop 1
	v_add_f32_dpp v112, v112, v112 quad_perm:[2,3,0,1] row_mask:0xf bank_mask:0xf
	s_nop 1
	v_add_f32_dpp v112, v112, v112 row_half_mirror row_mask:0xf bank_mask:0xf
	s_nop 1
	v_add_f32_dpp v112, v112, v112 row_mirror row_mask:0xf bank_mask:0xf
	s_nop 1
	v_add_f32_dpp v112, v112, v112 row_bcast:15 row_mask:0xa bank_mask:0xf
	s_nop 1
	v_add_f32_dpp v112, v112, v112 row_bcast:31 row_mask:0xc bank_mask:0xf
	v_fmamk_f32 v113, v112, 0x3a800000, v244
	v_rsq_f32_e32 v113, v113
	s_mov_b64 exec, s[6:7]
	global_store_dword v22, v113, s[4:5]
	s_mov_b64 exec, -1
	v_add_u32_e32 v18, 0x400000, v18
	v_add_u32_e32 v20, 0x400000, v20
	v_add_u32_e32 v21, 0x2000, v21
	global_load_dwordx4 v[78:81], v18, s[4:5]
	global_load_dwordx4 v[86:89], v20, s[4:5]
	global_load_dwordx4 v[82:85], v18, s[4:5] offset:1024
	global_load_dwordx4 v[90:93], v20, s[4:5] offset:1024
	global_load_dword v94, v21, s[4:5]
	s_waitcnt vmcnt(24)
; __device__ __forceinline__ float bflo(unsigned w) { return __uint_as_float(w << 16); }
; __device__ __forceinline__ float bfhi(unsigned w) { return __uint_as_float(w & 0xffff0000u); }
; __device__ __forceinline__ void resid_rows(bf16_t* R, const bf16_t* Y, const float* ssqY, const float* g, float* rstd_out, float* outf, bool wf32, int row_lo, int row_hi, int yoff, int gw, int NGW, int lane) {
;     ...
;     for (int row0 = row_lo + gw; row0 < row_hi; row0 += RP * NGW) {
;         u32x4 rr[RP][2], oo[RP][2]; float ssv[RP];
; #pragma unroll
;         for (int k = 0; k < RP; ++k) { const int row = row0 + k * NGW; const bool ok = row < row_hi; const int rw = ok ? row : row0;
;             ssv[k] = ssqY[rw];
; #pragma unroll
;             for (int j = 0; j < 2; ++j) { const int c = 8 * lane + 512 * j; rr[k][j] = *(const u32x4*)(R + (size_t)rw * DM + c); oo[k][j] = *(const u32x4*)(Y + (size_t)(rw - yoff) * DM + c); } }
; #pragma unroll
;         for (int k = 0; k < RP; ++k) { const int row = row0 + k * NGW; if (row < row_hi) {
;             const float rs = __builtin_amdgcn_rsqf(ssv[k] * (1.0f / DM) + RMS_EPS); float s = 0.f;
; #pragma unroll
;             for (int j = 0; j < 2; ++j) { const int c = 8 * lane + 512 * j; const u32x4 r = rr[k][j], o = oo[k][j]; const f32x4 ga = gv[j][0], gb = gv[j][1];
;                 f32x4 ya, yb; ya[0] = bflo(r.x) + bflo(o.x) * rs * ga[0]; ya[1] = bfhi(r.x) + bfhi(o.x) * rs * ga[1]; ya[2] = bflo(r.y) + bflo(o.y) * rs * ga[2]; ya[3] = bfhi(r.y) + bfhi(o.y) * rs * ga[3];
;                 yb[0] = bflo(r.z) + bflo(o.z) * rs * gb[0]; yb[1] = bfhi(r.z) + bfhi(o.z) * rs * gb[1]; yb[2] = bflo(r.w) + bflo(o.w) * rs * gb[2]; yb[3] = bfhi(r.w) + bfhi(o.w) * rs * gb[3];
;                 if (wf32) { *(f32x4*)(outf + (size_t)row * DM + c) = ya; *(f32x4*)(outf + (size_t)row * DM + c + 4) = yb; }
;                 s += (ya[0] * ya[0] + ya[1] * ya[1]) + (ya[2] * ya[2] + ya[3] * ya[3]) + (yb[0] * yb[0] + yb[1] * yb[1]) + (yb[2] * yb[2] + yb[3] * yb[3]);
;                 u32x4 w; w.x = pk2(ya[0], ya[1]); w.y = pk2(ya[2], ya[3]); w.z = pk2(yb[0], yb[1]); w.w = pk2(yb[2], yb[3]); *(u32x4*)(R + (size_t)row * DM + c) = w; }
;             s = wave_sum(s); if (lane == 0) rstd_out[row] = __builtin_amdgcn_rsqf(s * (1.0f / DM) + RMS_EPS); } }
	v_fmamk_f32 v96, v40, 0x3a800000, v244
	v_rsq_f32_e32 v96, v96
	v_add_u32_e32 v19, 0x400000, v19
	v_lshlrev_b32_e32 v106, 16, v32
	v_and_b32_e32 v107, 0xffff0000, v32
	v_lshlrev_b32_e32 v108, 16, v24
	v_and_b32_e32 v109, 0xffff0000, v24
	v_pk_mul_f32 v[106:107], v[96:97], v[106:107] op_sel_hi:[0,1]
	v_pk_fma_f32 v[98:99], v[10:11], v[106:107], v[108:109]
	v_lshlrev_b32_e32 v106, 16, v33
	v_and_b32_e32 v107, 0xffff0000, v33
	v_lshlrev_b32_e32 v108, 16, v25
	v_and_b32_e32 v109, 0xffff0000, v25
	v_pk_mul_f32 v[106:107], v[96:97], v[106:107] op_sel_hi:[0,1]
	v_pk_fma_f32 v[100:101], v[12:13], v[106:107], v[108:109]
	v_lshlrev_b32_e32 v106, 16, v34
	v_and_b32_e32 v107, 0xffff0000, v34
	v_lshlrev_b32_e32 v108, 16, v26
	v_and_b32_e32 v109, 0xffff0000, v26
	v_pk_mul_f32 v[106:107], v[96:97], v[106:107] op_sel_hi:[0,1]
	v_pk_fma_f32 v[102:103], v[14:15], v[106:107], v[108:109]
	v_lshlrev_b32_e32 v106, 16, v35
	v_and_b32_e32 v107, 0xffff0000, v35
	v_lshlrev_b32_e32 v108, 16, v27
	v_and_b32_e32 v109, 0xffff0000, v27
	v_pk_mul_f32 v[106:107], v[96:97], v[106:107] op_sel_hi:[0,1]
	v_pk_fma_f32 v[104:105], v[16:17], v[106:107], v[108:109]
	v_pk_mul_f32 v[110:111], v[98:99], v[98:99]
	v_pk_fma_f32 v[110:111], v[100:101], v[100:101], v[110:111]
	v_pk_fma_f32 v[110:111], v[102:103], v[102:103], v[110:111]
	v_pk_fma_f32 v[110:111], v[104:105], v[104:105], v[110:111]
	v_cvt_pk_bf16_f32 v24, v98, v99
	v_cvt_pk_bf16_f32 v25, v100, v101
	v_cvt_pk_bf16_f32 v26, v102, v103
	v_cvt_pk_bf16_f32 v27, v104, v105
	global_store_dwordx4 v19, v[24:27], s[4:5] nt
	v_lshlrev_b32_e32 v106, 16, v36
	v_and_b32_e32 v107, 0xffff0000, v36
	v_lshlrev_b32_e32 v108, 16, v28
	v_and_b32_e32 v109, 0xffff0000, v28
	v_pk_mul_f32 v[106:107], v[96:97], v[106:107] op_sel_hi:[0,1]
	v_pk_fma_f32 v[98:99], v[2:3], v[106:107], v[108:109]
	v_lshlrev_b32_e32 v106, 16, v37
	v_and_b32_e32 v107, 0xffff0000, v37
	v_lshlrev_b32_e32 v108, 16, v29
	v_and_b32_e32 v109, 0xffff0000, v29
	v_pk_mul_f32 v[106:107], v[96:97], v[106:107] op_sel_hi:[0,1]
	v_pk_fma_f32 v[100:101], v[4:5], v[106:107], v[108:109]
	v_lshlrev_b32_e32 v106, 16, v38
	v_and_b32_e32 v107, 0xffff0000, v38
	v_lshlrev_b32_e32 v108, 16, v30
	v_and_b32_e32 v109, 0xffff0000, v30
	v_pk_mul_f32 v[106:107], v[96:97], v[106:107] op_sel_hi:[0,1]
	v_pk_fma_f32 v[102:103], v[6:7], v[106:107], v[108:109]
	v_lshlrev_b32_e32 v106, 16, v39
	v_and_b32_e32 v107, 0xffff0000, v39
	v_lshlrev_b32_e32 v108, 16, v31
	v_and_b32_e32 v109, 0xffff0000, v31
	v_pk_mul_f32 v[106:107], v[96:97], v[106:107] op_sel_hi:[0,1]
	v_pk_fma_f32 v[104:105], v[8:9], v[106:107], v[108:109]
	v_pk_fma_f32 v[110:111], v[98:99], v[98:99], v[110:111]
	v_pk_fma_f32 v[110:111], v[100:101], v[100:101], v[110:111]
	v_pk_fma_f32 v[110:111], v[102:103], v[102:103], v[110:111]
	v_pk_fma_f32 v[110:111], v[104:105], v[104:105], v[110:111]
	v_cvt_pk_bf16_f32 v28, v98, v99
	v_cvt_pk_bf16_f32 v29, v100, v101
	v_cvt_pk_bf16_f32 v30, v102, v103
	v_cvt_pk_bf16_f32 v31, v104, v105
	global_store_dwordx4 v19, v[28:31], s[4:5] offset:1024 nt
	v_add_f32_e32 v112, v110, v111
	v_add_u32_e32 v22, 0x2000, v22
	s_nop 1
	v_add_f32_dpp v112, v112, v112 quad_perm:[1,0,3,2] row_mask:0xf bank_mask:0xf
	s_nop 1
	v_add_f32_dpp v112, v112, v112 quad_perm:[2,3,0,1] row_mask:0xf bank_mask:0xf
	s_nop 1
	v_add_f32_dpp v112, v112, v112 row_half_mirror row_mask:0xf bank_mask:0xf
	s_nop 1
	v_add_f32_dpp v112, v112, v112 row_mirror row_mask:0xf bank_mask:0xf
	s_nop 1
	v_add_f32_dpp v112, v112, v112 row_bcast:15 row_mask:0xa bank_mask:0xf
	s_nop 1
	v_add_f32_dpp v112, v112, v112 row_bcast:31 row_mask:0xc bank_mask:0xf
	v_fmamk_f32 v113, v112, 0x3a800000, v244
	v_rsq_f32_e32 v113, v113
	s_mov_b64 exec, s[6:7]
	global_store_dword v22, v113, s[4:5]
	s_mov_b64 exec, -1
	v_add_u32_e32 v18, 0x400000, v18
	v_add_u32_e32 v20, 0x400000, v20
	v_add_u32_e32 v21, 0x2000, v21
	global_load_dwordx4 v[24:27], v18, s[4:5]
	global_load_dwordx4 v[32:35], v20, s[4:5]
	global_load_dwordx4 v[28:31], v18, s[4:5] offset:1024
	global_load_dwordx4 v[36:39], v20, s[4:5] offset:1024
	global_load_dword v40, v21, s[4:5]
	s_waitcnt vmcnt(24)
	v_fmamk_f32 v96, v58, 0x3a800000, v244
	v_rsq_f32_e32 v96, v96
	v_add_u32_e32 v19, 0x400000, v19
	v_lshlrev_b32_e32 v106, 16, v50
	v_and_b32_e32 v107, 0xffff0000, v50
	v_lshlrev_b32_e32 v108, 16, v42
	v_and_b32_e32 v109, 0xffff0000, v42
	v_pk_mul_f32 v[106:107], v[96:97], v[106:107] op_sel_hi:[0,1]
	v_pk_fma_f32 v[98:99], v[10:11], v[106:107], v[108:109]
	v_lshlrev_b32_e32 v106, 16, v51
	v_and_b32_e32 v107, 0xffff0000, v51
	v_lshlrev_b32_e32 v108, 16, v43
	v_and_b32_e32 v109, 0xffff0000, v43
	v_pk_mul_f32 v[106:107], v[96:97], v[106:107] op_sel_hi:[0,1]
	v_pk_fma_f32 v[100:101], v[12:13], v[106:107], v[108:109]
	v_lshlrev_b32_e32 v106, 16, v52
	v_and_b32_e32 v107, 0xffff0000, v52
	v_lshlrev_b32_e32 v108, 16, v44
	v_and_b32_e32 v109, 0xffff0000, v44
	v_pk_mul_f32 v[106:107], v[96:97], v[106:107] op_sel_hi:[0,1]
	v_pk_fma_f32 v[102:103], v[14:15], v[106:107], v[108:109]
	v_lshlrev_b32_e32 v106, 16, v53
	v_and_b32_e32 v107, 0xffff0000, v53
	v_lshlrev_b32_e32 v108, 16, v45
	v_and_b32_e32 v109, 0xffff0000, v45
	v_pk_mul_f32 v[106:107], v[96:97], v[106:107] op_sel_hi:[0,1]
	v_pk_fma_f32 v[104:105], v[16:17], v[106:107], v[108:109]
	v_pk_mul_f32 v[110:111], v[98:99], v[98:99]
	v_pk_fma_f32 v[110:111], v[100:101], v[100:101], v[110:111]
	v_pk_fma_f32 v[110:111], v[102:103], v[102:103], v[110:111]
	v_pk_fma_f32 v[110:111], v[104:105], v[104:105], v[110:111]
	v_cvt_pk_bf16_f32 v42, v98, v99
	v_cvt_pk_bf16_f32 v43, v100, v101
	v_cvt_pk_bf16_f32 v44, v102, v103
	v_cvt_pk_bf16_f32 v45, v104, v105
	global_store_dwordx4 v19, v[42:45], s[4:5] nt
; __device__ __forceinline__ float bflo(unsigned w) { return __uint_as_float(w << 16); }
; __device__ __forceinline__ float bfhi(unsigned w) { return __uint_as_float(w & 0xffff0000u); }
; __device__ __forceinline__ void resid_rows(bf16_t* R, const bf16_t* Y, const float* ssqY, const float* g, float* rstd_out, float* outf, bool wf32, int row_lo, int row_hi, int yoff, int gw, int NGW, int lane) {
;     ...
;     for (int row0 = row_lo + gw; row0 < row_hi; row0 += RP * NGW) {
;         u32x4 rr[RP][2], oo[RP][2]; float ssv[RP];
; #pragma unroll
;         for (int k = 0; k < RP; ++k) { const int row = row0 + k * NGW; const bool ok = row < row_hi; const int rw = ok ? row : row0;
;             ssv[k] = ssqY[rw];
; #pragma unroll
;             for (int j = 0; j < 2; ++j) { const int c = 8 * lane + 512 * j; rr[k][j] = *(const u32x4*)(R + (size_t)rw * DM + c); oo[k][j] = *(const u32x4*)(Y + (size_t)(rw - yoff) * DM + c); } }
; #pragma unroll
;         for (int k = 0; k < RP; ++k) { const int row = row0 + k * NGW; if (row < row_hi) {
;             const float rs = __builtin_amdgcn_rsqf(ssv[k] * (1.0f / DM) + RMS_EPS); float s = 0.f;
; #pragma unroll
;             for (int j = 0; j < 2; ++j) { const int c = 8 * lane + 512 * j; const u32x4 r = rr[k][j], o = oo[k][j]; const f32x4 ga = gv[j][0], gb = gv[j][1];
;                 f32x4 ya, yb; ya[0] = bflo(r.x) + bflo(o.x) * rs * ga[0]; ya[1] = bfhi(r.x) + bfhi(o.x) * rs * ga[1]; ya[2] = bflo(r.y) + bflo(o.y) * rs * ga[2]; ya[3] = bfhi(r.y) + bfhi(o.y) * rs * ga[3];
;                 yb[0] = bflo(r.z) + bflo(o.z) * rs * gb[0]; yb[1] = bfhi(r.z) + bfhi(o.z) * rs * gb[1]; yb[2] = bflo(r.w) + bflo(o.w) * rs * gb[2]; yb[3] = bfhi(r.w) + bfhi(o.w) * rs * gb[3];
;                 if (wf32) { *(f32x4*)(outf + (size_t)row * DM + c) = ya; *(f32x4*)(outf + (size_t)row * DM + c + 4) = yb; }
;                 s += (ya[0] * ya[0] + ya[1] * ya[1]) + (ya[2] * ya[2] + ya[3] * ya[3]) + (yb[0] * yb[0] + yb[1] * yb[1]) + (yb[2] * yb[2] + yb[3] * yb[3]);
;                 u32x4 w; w.x = pk2(ya[0], ya[1]); w.y = pk2(ya[2], ya[3]); w.z = pk2(yb[0], yb[1]); w.w = pk2(yb[2], yb[3]); *(u32x4*)(R + (size_t)row * DM + c) = w; }
;             s = wave_sum(s); if (lane == 0) rstd_out[row] = __builtin_amdgcn_rsqf(s * (1.0f / DM) + RMS_EPS); } }
	v_lshlrev_b32_e32 v106, 16, v54
	v_and_b32_e32 v107, 0xffff0000, v54
	v_lshlrev_b32_e32 v108, 16, v46
	v_and_b32_e32 v109, 0xffff0000, v46
	v_pk_mul_f32 v[106:107], v[96:97], v[106:107] op_sel_hi:[0,1]
	v_pk_fma_f32 v[98:99], v[2:3], v[106:107], v[108:109]
	v_lshlrev_b32_e32 v106, 16, v55
	v_and_b32_e32 v107, 0xffff0000, v55
	v_lshlrev_b32_e32 v108, 16, v47
	v_and_b32_e32 v109, 0xffff0000, v47
	v_pk_mul_f32 v[106:107], v[96:97], v[106:107] op_sel_hi:[0,1]
	v_pk_fma_f32 v[100:101], v[4:5], v[106:107], v[108:109]
	v_lshlrev_b32_e32 v106, 16, v56
	v_and_b32_e32 v107, 0xffff0000, v56
	v_lshlrev_b32_e32 v108, 16, v48
	v_and_b32_e32 v109, 0xffff0000, v48
	v_pk_mul_f32 v[106:107], v[96:97], v[106:107] op_sel_hi:[0,1]
	v_pk_fma_f32 v[102:103], v[6:7], v[106:107], v[108:109]
	v_lshlrev_b32_e32 v106, 16, v57
	v_and_b32_e32 v107, 0xffff0000, v57
	v_lshlrev_b32_e32 v108, 16, v49
	v_and_b32_e32 v109, 0xffff0000, v49
	v_pk_mul_f32 v[106:107], v[96:97], v[106:107] op_sel_hi:[0,1]
	v_pk_fma_f32 v[104:105], v[8:9], v[106:107], v[108:109]
	v_pk_fma_f32 v[110:111], v[98:99], v[98:99], v[110:111]
	v_pk_fma_f32 v[110:111], v[100:101], v[100:101], v[110:111]
	v_pk_fma_f32 v[110:111], v[102:103], v[102:103], v[110:111]
	v_pk_fma_f32 v[110:111], v[104:105], v[104:105], v[110:111]
	v_cvt_pk_bf16_f32 v46, v98, v99
	v_cvt_pk_bf16_f32 v47, v100, v101
	v_cvt_pk_bf16_f32 v48, v102, v103
	v_cvt_pk_bf16_f32 v49, v104, v105
	global_store_dwordx4 v19, v[46:49], s[4:5] offset:1024 nt
	v_add_f32_e32 v112, v110, v111
	v_add_u32_e32 v22, 0x2000, v22
	s_nop 1
	v_add_f32_dpp v112, v112, v112 quad_perm:[1,0,3,2] row_mask:0xf bank_mask:0xf
	s_nop 1
	v_add_f32_dpp v112, v112, v112 quad_perm:[2,3,0,1] row_mask:0xf bank_mask:0xf
	s_nop 1
	v_add_f32_dpp v112, v112, v112 row_half_mirror row_mask:0xf bank_mask:0xf
	s_nop 1
	v_add_f32_dpp v112, v112, v112 row_mirror row_mask:0xf bank_mask:0xf
	s_nop 1
	v_add_f32_dpp v112, v112, v112 row_bcast:15 row_mask:0xa bank_mask:0xf
	s_nop 1
	v_add_f32_dpp v112, v112, v112 row_bcast:31 row_mask:0xc bank_mask:0xf
	v_fmamk_f32 v113, v112, 0x3a800000, v244
	v_rsq_f32_e32 v113, v113
	s_mov_b64 exec, s[6:7]
	global_store_dword v22, v113, s[4:5]
	s_mov_b64 exec, -1
	v_add_u32_e32 v18, 0x400000, v18
	v_add_u32_e32 v20, 0x400000, v20
	v_add_u32_e32 v21, 0x2000, v21
	global_load_dwordx4 v[42:45], v18, s[4:5]
	global_load_dwordx4 v[50:53], v20, s[4:5]
	global_load_dwordx4 v[46:49], v18, s[4:5] offset:1024
	global_load_dwordx4 v[54:57], v20, s[4:5] offset:1024
	global_load_dword v58, v21, s[4:5]
	s_waitcnt vmcnt(24)
	v_fmamk_f32 v96, v76, 0x3a800000, v244
	v_rsq_f32_e32 v96, v96
	v_add_u32_e32 v19, 0x400000, v19
	v_lshlrev_b32_e32 v106, 16, v68
	v_and_b32_e32 v107, 0xffff0000, v68
	v_lshlrev_b32_e32 v108, 16, v60
	v_and_b32_e32 v109, 0xffff0000, v60
	v_pk_mul_f32 v[106:107], v[96:97], v[106:107] op_sel_hi:[0,1]
	v_pk_fma_f32 v[98:99], v[10:11], v[106:107], v[108:109]
	v_lshlrev_b32_e32 v106, 16, v69
	v_and_b32_e32 v107, 0xffff0000, v69
	v_lshlrev_b32_e32 v108, 16, v61
	v_and_b32_e32 v109, 0xffff0000, v61
	v_pk_mul_f32 v[106:107], v[96:97], v[106:107] op_sel_hi:[0,1]
	v_pk_fma_f32 v[100:101], v[12:13], v[106:107], v[108:109]
	v_lshlrev_b32_e32 v106, 16, v70
	v_and_b32_e32 v107, 0xffff0000, v70
	v_lshlrev_b32_e32 v108, 16, v62
	v_and_b32_e32 v109, 0xffff0000, v62
	v_pk_mul_f32 v[106:107], v[96:97], v[106:107] op_sel_hi:[0,1]
	v_pk_fma_f32 v[102:103], v[14:15], v[106:107], v[108:109]
	v_lshlrev_b32_e32 v106, 16, v71
	v_and_b32_e32 v107, 0xffff0000, v71
	v_lshlrev_b32_e32 v108, 16, v63
	v_and_b32_e32 v109, 0xffff0000, v63
	v_pk_mul_f32 v[106:107], v[96:97], v[106:107] op_sel_hi:[0,1]
	v_pk_fma_f32 v[104:105], v[16:17], v[106:107], v[108:109]
	v_pk_mul_f32 v[110:111], v[98:99], v[98:99]
	v_pk_fma_f32 v[110:111], v[100:101], v[100:101], v[110:111]
	v_pk_fma_f32 v[110:111], v[102:103], v[102:103], v[110:111]
	v_pk_fma_f32 v[110:111], v[104:105], v[104:105], v[110:111]
	v_cvt_pk_bf16_f32 v60, v98, v99
	v_cvt_pk_bf16_f32 v61, v100, v101
	v_cvt_pk_bf16_f32 v62, v102, v103
	v_cvt_pk_bf16_f32 v63, v104, v105
	global_store_dwordx4 v19, v[60:63], s[4:5] nt
	v_lshlrev_b32_e32 v106, 16, v72
	v_and_b32_e32 v107, 0xffff0000, v72
	v_lshlrev_b32_e32 v108, 16, v64
	v_and_b32_e32 v109, 0xffff0000, v64
	v_pk_mul_f32 v[106:107], v[96:97], v[106:107] op_sel_hi:[0,1]
	v_pk_fma_f32 v[98:99], v[2:3], v[106:107], v[108:109]
	v_lshlrev_b32_e32 v106, 16, v73
	v_and_b32_e32 v107, 0xffff0000, v73
	v_lshlrev_b32_e32 v108, 16, v65
	v_and_b32_e32 v109, 0xffff0000, v65
	v_pk_mul_f32 v[106:107], v[96:97], v[106:107] op_sel_hi:[0,1]
	v_pk_fma_f32 v[100:101], v[4:5], v[106:107], v[108:109]
	v_lshlrev_b32_e32 v106, 16, v74
	v_and_b32_e32 v107, 0xffff0000, v74
	v_lshlrev_b32_e32 v108, 16, v66
	v_and_b32_e32 v109, 0xffff0000, v66
	v_pk_mul_f32 v[106:107], v[96:97], v[106:107] op_sel_hi:[0,1]
	v_pk_fma_f32 v[102:103], v[6:7], v[106:107], v[108:109]
	v_lshlrev_b32_e32 v106, 16, v75
	v_and_b32_e32 v107, 0xffff0000, v75
	v_lshlrev_b32_e32 v108, 16, v67
	v_and_b32_e32 v109, 0xffff0000, v67
	v_pk_mul_f32 v[106:107], v[96:97], v[106:107] op_sel_hi:[0,1]
	v_pk_fma_f32 v[104:105], v[8:9], v[106:107], v[108:109]
	v_pk_fma_f32 v[110:111], v[98:99], v[98:99], v[110:111]
	v_pk_fma_f32 v[110:111], v[100:101], v[100:101], v[110:111]
	v_pk_fma_f32 v[110:111], v[102:103], v[102:103], v[110:111]
	v_pk_fma_f32 v[110:111], v[104:105], v[104:105], v[110:111]
	v_cvt_pk_bf16_f32 v64, v98, v99
	v_cvt_pk_bf16_f32 v65, v100, v101
	v_cvt_pk_bf16_f32 v66, v102, v103
	v_cvt_pk_bf16_f32 v67, v104, v105
	global_store_dwordx4 v19, v[64:67], s[4:5] offset:1024 nt
	v_add_f32_e32 v112, v110, v111
	v_add_u32_e32 v22, 0x2000, v22
	s_nop 1
	v_add_f32_dpp v112, v112, v112 quad_perm:[1,0,3,2] row_mask:0xf bank_mask:0xf
	s_nop 1
	v_add_f32_dpp v112, v112, v112 quad_perm:[2,3,0,1] row_mask:0xf bank_mask:0xf
	s_nop 1
	v_add_f32_dpp v112, v112, v112 row_half_mirror row_mask:0xf bank_mask:0xf
	s_nop 1
	v_add_f32_dpp v112, v112, v112 row_mirror row_mask:0xf bank_mask:0xf
	s_nop 1
	v_add_f32_dpp v112, v112, v112 row_bcast:15 row_mask:0xa bank_mask:0xf
	s_nop 1
	v_add_f32_dpp v112, v112, v112 row_bcast:31 row_mask:0xc bank_mask:0xf
	v_fmamk_f32 v113, v112, 0x3a800000, v244
	v_rsq_f32_e32 v113, v113
	s_mov_b64 exec, s[6:7]
	global_store_dword v22, v113, s[4:5]
	s_mov_b64 exec, -1
	v_add_u32_e32 v18, 0x400000, v18
	v_add_u32_e32 v20, 0x400000, v20
	v_add_u32_e32 v21, 0x2000, v21
	global_load_dwordx4 v[60:63], v18, s[4:5]
	global_load_dwordx4 v[68:71], v20, s[4:5]
	global_load_dwordx4 v[64:67], v18, s[4:5] offset:1024
	global_load_dwordx4 v[72:75], v20, s[4:5] offset:1024
	global_load_dword v76, v21, s[4:5]
	s_waitcnt vmcnt(24)
; __device__ __forceinline__ float bflo(unsigned w) { return __uint_as_float(w << 16); }
; __device__ __forceinline__ float bfhi(unsigned w) { return __uint_as_float(w & 0xffff0000u); }
; __device__ __forceinline__ void resid_rows(bf16_t* R, const bf16_t* Y, const float* ssqY, const float* g, float* rstd_out, float* outf, bool wf32, int row_lo, int row_hi, int yoff, int gw, int NGW, int lane) {
;     ...
;     for (int row0 = row_lo + gw; row0 < row_hi; row0 += RP * NGW) {
;         u32x4 rr[RP][2], oo[RP][2]; float ssv[RP];
; #pragma unroll
;         for (int k = 0; k < RP; ++k) { const int row = row0 + k * NGW; const bool ok = row < row_hi; const int rw = ok ? row : row0;
;             ssv[k] = ssqY[rw];
; #pragma unroll
;             for (int j = 0; j < 2; ++j) { const int c = 8 * lane + 512 * j; rr[k][j] = *(const u32x4*)(R + (size_t)rw * DM + c); oo[k][j] = *(const u32x4*)(Y + (size_t)(rw - yoff) * DM + c); } }
; #pragma unroll
;         for (int k = 0; k < RP; ++k) { const int row = row0 + k * NGW; if (row < row_hi) {
;             const float rs = __builtin_amdgcn_rsqf(ssv[k] * (1.0f / DM) + RMS_EPS); float s = 0.f;
; #pragma unroll
;             for (int j = 0; j < 2; ++j) { const int c = 8 * lane + 512 * j; const u32x4 r = rr[k][j], o = oo[k][j]; const f32x4 ga = gv[j][0], gb = gv[j][1];
;                 f32x4 ya, yb; ya[0] = bflo(r.x) + bflo(o.x) * rs * ga[0]; ya[1] = bfhi(r.x) + bfhi(o.x) * rs * ga[1]; ya[2] = bflo(r.y) + bflo(o.y) * rs * ga[2]; ya[3] = bfhi(r.y) + bfhi(o.y) * rs * ga[3];
;                 yb[0] = bflo(r.z) + bflo(o.z) * rs * gb[0]; yb[1] = bfhi(r.z) + bfhi(o.z) * rs * gb[1]; yb[2] = bflo(r.w) + bflo(o.w) * rs * gb[2]; yb[3] = bfhi(r.w) + bfhi(o.w) * rs * gb[3];
;                 if (wf32) { *(f32x4*)(outf + (size_t)row * DM + c) = ya; *(f32x4*)(outf + (size_t)row * DM + c + 4) = yb; }
;                 s += (ya[0] * ya[0] + ya[1] * ya[1]) + (ya[2] * ya[2] + ya[3] * ya[3]) + (yb[0] * yb[0] + yb[1] * yb[1]) + (yb[2] * yb[2] + yb[3] * yb[3]);
;                 u32x4 w; w.x = pk2(ya[0], ya[1]); w.y = pk2(ya[2], ya[3]); w.z = pk2(yb[0], yb[1]); w.w = pk2(yb[2], yb[3]); *(u32x4*)(R + (size_t)row * DM + c) = w; }
;             s = wave_sum(s); if (lane == 0) rstd_out[row] = __builtin_amdgcn_rsqf(s * (1.0f / DM) + RMS_EPS); } }
	v_fmamk_f32 v96, v94, 0x3a800000, v244
	v_rsq_f32_e32 v96, v96
	v_add_u32_e32 v19, 0x400000, v19
	v_lshlrev_b32_e32 v106, 16, v86
	v_and_b32_e32 v107, 0xffff0000, v86
	v_lshlrev_b32_e32 v108, 16, v78
	v_and_b32_e32 v109, 0xffff0000, v78
	v_pk_mul_f32 v[106:107], v[96:97], v[106:107] op_sel_hi:[0,1]
	v_pk_fma_f32 v[98:99], v[10:11], v[106:107], v[108:109]
	v_lshlrev_b32_e32 v106, 16, v87
	v_and_b32_e32 v107, 0xffff0000, v87
	v_lshlrev_b32_e32 v108, 16, v79
	v_and_b32_e32 v109, 0xffff0000, v79
	v_pk_mul_f32 v[106:107], v[96:97], v[106:107] op_sel_hi:[0,1]
	v_pk_fma_f32 v[100:101], v[12:13], v[106:107], v[108:109]
	v_lshlrev_b32_e32 v106, 16, v88
	v_and_b32_e32 v107, 0xffff0000, v88
	v_lshlrev_b32_e32 v108, 16, v80
	v_and_b32_e32 v109, 0xffff0000, v80
	v_pk_mul_f32 v[106:107], v[96:97], v[106:107] op_sel_hi:[0,1]
	v_pk_fma_f32 v[102:103], v[14:15], v[106:107], v[108:109]
	v_lshlrev_b32_e32 v106, 16, v89
	v_and_b32_e32 v107, 0xffff0000, v89
	v_lshlrev_b32_e32 v108, 16, v81
	v_and_b32_e32 v109, 0xffff0000, v81
	v_pk_mul_f32 v[106:107], v[96:97], v[106:107] op_sel_hi:[0,1]
	v_pk_fma_f32 v[104:105], v[16:17], v[106:107], v[108:109]
	v_pk_mul_f32 v[110:111], v[98:99], v[98:99]
	v_pk_fma_f32 v[110:111], v[100:101], v[100:101], v[110:111]
	v_pk_fma_f32 v[110:111], v[102:103], v[102:103], v[110:111]
	v_pk_fma_f32 v[110:111], v[104:105], v[104:105], v[110:111]
	v_cvt_pk_bf16_f32 v78, v98, v99
	v_cvt_pk_bf16_f32 v79, v100, v101
	v_cvt_pk_bf16_f32 v80, v102, v103
	v_cvt_pk_bf16_f32 v81, v104, v105
	global_store_dwordx4 v19, v[78:81], s[4:5] nt
	v_lshlrev_b32_e32 v106, 16, v90
	v_and_b32_e32 v107, 0xffff0000, v90
	v_lshlrev_b32_e32 v108, 16, v82
	v_and_b32_e32 v109, 0xffff0000, v82
	v_pk_mul_f32 v[106:107], v[96:97], v[106:107] op_sel_hi:[0,1]
	v_pk_fma_f32 v[98:99], v[2:3], v[106:107], v[108:109]
	v_lshlrev_b32_e32 v106, 16, v91
	v_and_b32_e32 v107, 0xffff0000, v91
	v_lshlrev_b32_e32 v108, 16, v83
	v_and_b32_e32 v109, 0xffff0000, v83
	v_pk_mul_f32 v[106:107], v[96:97], v[106:107] op_sel_hi:[0,1]
	v_pk_fma_f32 v[100:101], v[4:5], v[106:107], v[108:109]
	v_lshlrev_b32_e32 v106, 16, v92
	v_and_b32_e32 v107, 0xffff0000, v92
	v_lshlrev_b32_e32 v108, 16, v84
	v_and_b32_e32 v109, 0xffff0000, v84
	v_pk_mul_f32 v[106:107], v[96:97], v[106:107] op_sel_hi:[0,1]
	v_pk_fma_f32 v[102:103], v[6:7], v[106:107], v[108:109]
	v_lshlrev_b32_e32 v106, 16, v93
	v_and_b32_e32 v107, 0xffff0000, v93
	v_lshlrev_b32_e32 v108, 16, v85
	v_and_b32_e32 v109, 0xffff0000, v85
	v_pk_mul_f32 v[106:107], v[96:97], v[106:107] op_sel_hi:[0,1]
	v_pk_fma_f32 v[104:105], v[8:9], v[106:107], v[108:109]
	v_pk_fma_f32 v[110:111], v[98:99], v[98:99], v[110:111]
	v_pk_fma_f32 v[110:111], v[100:101], v[100:101], v[110:111]
	v_pk_fma_f32 v[110:111], v[102:103], v[102:103], v[110:111]
	v_pk_fma_f32 v[110:111], v[104:105], v[104:105], v[110:111]
	v_cvt_pk_bf16_f32 v82, v98, v99
	v_cvt_pk_bf16_f32 v83, v100, v101
	v_cvt_pk_bf16_f32 v84, v102, v103
	v_cvt_pk_bf16_f32 v85, v104, v105
	global_store_dwordx4 v19, v[82:85], s[4:5] offset:1024 nt
	v_add_f32_e32 v112, v110, v111
	v_add_u32_e32 v22, 0x2000, v22
	s_nop 1
	v_add_f32_dpp v112, v112, v112 quad_perm:[1,0,3,2] row_mask:0xf bank_mask:0xf
	s_nop 1
	v_add_f32_dpp v112, v112, v112 quad_perm:[2,3,0,1] row_mask:0xf bank_mask:0xf
	s_nop 1
	v_add_f32_dpp v112, v112, v112 row_half_mirror row_mask:0xf bank_mask:0xf
	s_nop 1
	v_add_f32_dpp v112, v112, v112 row_mirror row_mask:0xf bank_mask:0xf
	s_nop 1
	v_add_f32_dpp v112, v112, v112 row_bcast:15 row_mask:0xa bank_mask:0xf
	s_nop 1
	v_add_f32_dpp v112, v112, v112 row_bcast:31 row_mask:0xc bank_mask:0xf
	v_fmamk_f32 v113, v112, 0x3a800000, v244
	v_rsq_f32_e32 v113, v113
	s_mov_b64 exec, s[6:7]
	global_store_dword v22, v113, s[4:5]
	s_mov_b64 exec, -1
	v_add_u32_e32 v18, 0x400000, v18
	v_add_u32_e32 v20, 0x400000, v20
	v_add_u32_e32 v21, 0x2000, v21
	global_load_dwordx4 v[78:81], v18, s[4:5]
	global_load_dwordx4 v[86:89], v20, s[4:5]
	global_load_dwordx4 v[82:85], v18, s[4:5] offset:1024
	global_load_dwordx4 v[90:93], v20, s[4:5] offset:1024
	global_load_dword v94, v21, s[4:5]
	s_waitcnt vmcnt(24)
	v_fmamk_f32 v96, v40, 0x3a800000, v244
	v_rsq_f32_e32 v96, v96
	v_add_u32_e32 v19, 0x400000, v19
	v_lshlrev_b32_e32 v106, 16, v32
	v_and_b32_e32 v107, 0xffff0000, v32
	v_lshlrev_b32_e32 v108, 16, v24
	v_and_b32_e32 v109, 0xffff0000, v24
	v_pk_mul_f32 v[106:107], v[96:97], v[106:107] op_sel_hi:[0,1]
	v_pk_fma_f32 v[98:99], v[10:11], v[106:107], v[108:109]
	v_lshlrev_b32_e32 v106, 16, v33
	v_and_b32_e32 v107, 0xffff0000, v33
	v_lshlrev_b32_e32 v108, 16, v25
	v_and_b32_e32 v109, 0xffff0000, v25
	v_pk_mul_f32 v[106:107], v[96:97], v[106:107] op_sel_hi:[0,1]
	v_pk_fma_f32 v[100:101], v[12:13], v[106:107], v[108:109]
	v_lshlrev_b32_e32 v106, 16, v34
	v_and_b32_e32 v107, 0xffff0000, v34
	v_lshlrev_b32_e32 v108, 16, v26
	v_and_b32_e32 v109, 0xffff0000, v26
	v_pk_mul_f32 v[106:107], v[96:97], v[106:107] op_sel_hi:[0,1]
	v_pk_fma_f32 v[102:103], v[14:15], v[106:107], v[108:109]
	v_lshlrev_b32_e32 v106, 16, v35
	v_and_b32_e32 v107, 0xffff0000, v35
	v_lshlrev_b32_e32 v108, 16, v27
	v_and_b32_e32 v109, 0xffff0000, v27
	v_pk_mul_f32 v[106:107], v[96:97], v[106:107] op_sel_hi:[0,1]
	v_pk_fma_f32 v[104:105], v[16:17], v[106:107], v[108:109]
	v_pk_mul_f32 v[110:111], v[98:99], v[98:99]
	v_pk_fma_f32 v[110:111], v[100:101], v[100:101], v[110:111]
	v_pk_fma_f32 v[110:111], v[102:103], v[102:103], v[110:111]
	v_pk_fma_f32 v[110:111], v[104:105], v[104:105], v[110:111]
	v_cvt_pk_bf16_f32 v24, v98, v99
	v_cvt_pk_bf16_f32 v25, v100, v101
	v_cvt_pk_bf16_f32 v26, v102, v103
	v_cvt_pk_bf16_f32 v27, v104, v105
	global_store_dwordx4 v19, v[24:27], s[4:5] nt
; __device__ __forceinline__ float bflo(unsigned w) { return __uint_as_float(w << 16); }
; __device__ __forceinline__ float bfhi(unsigned w) { return __uint_as_float(w & 0xffff0000u); }
; __device__ __forceinline__ void resid_rows(bf16_t* R, const bf16_t* Y, const float* ssqY, const float* g, float* rstd_out, float* outf, bool wf32, int row_lo, int row_hi, int yoff, int gw, int NGW, int lane) {
;     ...
;     for (int row0 = row_lo + gw; row0 < row_hi; row0 += RP * NGW) {
;         u32x4 rr[RP][2], oo[RP][2]; float ssv[RP];
; #pragma unroll
;         for (int k = 0; k < RP; ++k) { const int row = row0 + k * NGW; const bool ok = row < row_hi; const int rw = ok ? row : row0;
;             ssv[k] = ssqY[rw];
; #pragma unroll
;             for (int j = 0; j < 2; ++j) { const int c = 8 * lane + 512 * j; rr[k][j] = *(const u32x4*)(R + (size_t)rw * DM + c); oo[k][j] = *(const u32x4*)(Y + (size_t)(rw - yoff) * DM + c); } }
; #pragma unroll
;         for (int k = 0; k < RP; ++k) { const int row = row0 + k * NGW; if (row < row_hi) {
;             const float rs = __builtin_amdgcn_rsqf(ssv[k] * (1.0f / DM) + RMS_EPS); float s = 0.f;
; #pragma unroll
;             for (int j = 0; j < 2; ++j) { const int c = 8 * lane + 512 * j; const u32x4 r = rr[k][j], o = oo[k][j]; const f32x4 ga = gv[j][0], gb = gv[j][1];
;                 f32x4 ya, yb; ya[0] = bflo(r.x) + bflo(o.x) * rs * ga[0]; ya[1] = bfhi(r.x) + bfhi(o.x) * rs * ga[1]; ya[2] = bflo(r.y) + bflo(o.y) * rs * ga[2]; ya[3] = bfhi(r.y) + bfhi(o.y) * rs * ga[3];
;                 yb[0] = bflo(r.z) + bflo(o.z) * rs * gb[0]; yb[1] = bfhi(r.z) + bfhi(o.z) * rs * gb[1]; yb[2] = bflo(r.w) + bflo(o.w) * rs * gb[2]; yb[3] = bfhi(r.w) + bfhi(o.w) * rs * gb[3];
;                 if (wf32) { *(f32x4*)(outf + (size_t)row * DM + c) = ya; *(f32x4*)(outf + (size_t)row * DM + c + 4) = yb; }
;                 s += (ya[0] * ya[0] + ya[1] * ya[1]) + (ya[2] * ya[2] + ya[3] * ya[3]) + (yb[0] * yb[0] + yb[1] * yb[1]) + (yb[2] * yb[2] + yb[3] * yb[3]);
;                 u32x4 w; w.x = pk2(ya[0], ya[1]); w.y = pk2(ya[2], ya[3]); w.z = pk2(yb[0], yb[1]); w.w = pk2(yb[2], yb[3]); *(u32x4*)(R + (size_t)row * DM + c) = w; }
;             s = wave_sum(s); if (lane == 0) rstd_out[row] = __builtin_amdgcn_rsqf(s * (1.0f / DM) + RMS_EPS); } }
	v_lshlrev_b32_e32 v106, 16, v36
	v_and_b32_e32 v107, 0xffff0000, v36
	v_lshlrev_b32_e32 v108, 16, v28
	v_and_b32_e32 v109, 0xffff0000, v28
	v_pk_mul_f32 v[106:107], v[96:97], v[106:107] op_sel_hi:[0,1]
	v_pk_fma_f32 v[98:99], v[2:3], v[106:107], v[108:109]
	v_lshlrev_b32_e32 v106, 16, v37
	v_and_b32_e32 v107, 0xffff0000, v37
	v_lshlrev_b32_e32 v108, 16, v29
	v_and_b32_e32 v109, 0xffff0000, v29
	v_pk_mul_f32 v[106:107], v[96:97], v[106:107] op_sel_hi:[0,1]
	v_pk_fma_f32 v[100:101], v[4:5], v[106:107], v[108:109]
	v_lshlrev_b32_e32 v106, 16, v38
	v_and_b32_e32 v107, 0xffff0000, v38
	v_lshlrev_b32_e32 v108, 16, v30
	v_and_b32_e32 v109, 0xffff0000, v30
	v_pk_mul_f32 v[106:107], v[96:97], v[106:107] op_sel_hi:[0,1]
	v_pk_fma_f32 v[102:103], v[6:7], v[106:107], v[108:109]
	v_lshlrev_b32_e32 v106, 16, v39
	v_and_b32_e32 v107, 0xffff0000, v39
	v_lshlrev_b32_e32 v108, 16, v31
	v_and_b32_e32 v109, 0xffff0000, v31
	v_pk_mul_f32 v[106:107], v[96:97], v[106:107] op_sel_hi:[0,1]
	v_pk_fma_f32 v[104:105], v[8:9], v[106:107], v[108:109]
	v_pk_fma_f32 v[110:111], v[98:99], v[98:99], v[110:111]
	v_pk_fma_f32 v[110:111], v[100:101], v[100:101], v[110:111]
	v_pk_fma_f32 v[110:111], v[102:103], v[102:103], v[110:111]
	v_pk_fma_f32 v[110:111], v[104:105], v[104:105], v[110:111]
	v_cvt_pk_bf16_f32 v28, v98, v99
	v_cvt_pk_bf16_f32 v29, v100, v101
	v_cvt_pk_bf16_f32 v30, v102, v103
	v_cvt_pk_bf16_f32 v31, v104, v105
	global_store_dwordx4 v19, v[28:31], s[4:5] offset:1024 nt
	v_add_f32_e32 v112, v110, v111
	v_add_u32_e32 v22, 0x2000, v22
	s_nop 1
	v_add_f32_dpp v112, v112, v112 quad_perm:[1,0,3,2] row_mask:0xf bank_mask:0xf
	s_nop 1
	v_add_f32_dpp v112, v112, v112 quad_perm:[2,3,0,1] row_mask:0xf bank_mask:0xf
	s_nop 1
	v_add_f32_dpp v112, v112, v112 row_half_mirror row_mask:0xf bank_mask:0xf
	s_nop 1
	v_add_f32_dpp v112, v112, v112 row_mirror row_mask:0xf bank_mask:0xf
	s_nop 1
	v_add_f32_dpp v112, v112, v112 row_bcast:15 row_mask:0xa bank_mask:0xf
	s_nop 1
	v_add_f32_dpp v112, v112, v112 row_bcast:31 row_mask:0xc bank_mask:0xf
	v_fmamk_f32 v113, v112, 0x3a800000, v244
	v_rsq_f32_e32 v113, v113
	s_mov_b64 exec, s[6:7]
	global_store_dword v22, v113, s[4:5]
	s_mov_b64 exec, -1
	v_add_u32_e32 v18, 0x400000, v18
	v_add_u32_e32 v20, 0x400000, v20
	v_add_u32_e32 v21, 0x2000, v21
	global_load_dwordx4 v[24:27], v18, s[4:5]
	global_load_dwordx4 v[32:35], v20, s[4:5]
	global_load_dwordx4 v[28:31], v18, s[4:5] offset:1024
	global_load_dwordx4 v[36:39], v20, s[4:5] offset:1024
	global_load_dword v40, v21, s[4:5]
	s_waitcnt vmcnt(24)
	v_fmamk_f32 v96, v58, 0x3a800000, v244
	v_rsq_f32_e32 v96, v96
	v_add_u32_e32 v19, 0x400000, v19
	v_lshlrev_b32_e32 v106, 16, v50
	v_and_b32_e32 v107, 0xffff0000, v50
	v_lshlrev_b32_e32 v108, 16, v42
	v_and_b32_e32 v109, 0xffff0000, v42
	v_pk_mul_f32 v[106:107], v[96:97], v[106:107] op_sel_hi:[0,1]
	v_pk_fma_f32 v[98:99], v[10:11], v[106:107], v[108:109]
	v_lshlrev_b32_e32 v106, 16, v51
	v_and_b32_e32 v107, 0xffff0000, v51
	v_lshlrev_b32_e32 v108, 16, v43
	v_and_b32_e32 v109, 0xffff0000, v43
	v_pk_mul_f32 v[106:107], v[96:97], v[106:107] op_sel_hi:[0,1]
	v_pk_fma_f32 v[100:101], v[12:13], v[106:107], v[108:109]
	v_lshlrev_b32_e32 v106, 16, v52
	v_and_b32_e32 v107, 0xffff0000, v52
	v_lshlrev_b32_e32 v108, 16, v44
	v_and_b32_e32 v109, 0xffff0000, v44
	v_pk_mul_f32 v[106:107], v[96:97], v[106:107] op_sel_hi:[0,1]
	v_pk_fma_f32 v[102:103], v[14:15], v[106:107], v[108:109]
	v_lshlrev_b32_e32 v106, 16, v53
	v_and_b32_e32 v107, 0xffff0000, v53
	v_lshlrev_b32_e32 v108, 16, v45
	v_and_b32_e32 v109, 0xffff0000, v45
	v_pk_mul_f32 v[106:107], v[96:97], v[106:107] op_sel_hi:[0,1]
	v_pk_fma_f32 v[104:105], v[16:17], v[106:107], v[108:109]
	v_pk_mul_f32 v[110:111], v[98:99], v[98:99]
	v_pk_fma_f32 v[110:111], v[100:101], v[100:101], v[110:111]
	v_pk_fma_f32 v[110:111], v[102:103], v[102:103], v[110:111]
	v_pk_fma_f32 v[110:111], v[104:105], v[104:105], v[110:111]
	v_cvt_pk_bf16_f32 v42, v98, v99
	v_cvt_pk_bf16_f32 v43, v100, v101
	v_cvt_pk_bf16_f32 v44, v102, v103
	v_cvt_pk_bf16_f32 v45, v104, v105
	global_store_dwordx4 v19, v[42:45], s[4:5] nt
	v_lshlrev_b32_e32 v106, 16, v54
	v_and_b32_e32 v107, 0xffff0000, v54
	v_lshlrev_b32_e32 v108, 16, v46
	v_and_b32_e32 v109, 0xffff0000, v46
	v_pk_mul_f32 v[106:107], v[96:97], v[106:107] op_sel_hi:[0,1]
	v_pk_fma_f32 v[98:99], v[2:3], v[106:107], v[108:109]
	v_lshlrev_b32_e32 v106, 16, v55
	v_and_b32_e32 v107, 0xffff0000, v55
	v_lshlrev_b32_e32 v108, 16, v47
	v_and_b32_e32 v109, 0xffff0000, v47
	v_pk_mul_f32 v[106:107], v[96:97], v[106:107] op_sel_hi:[0,1]
	v_pk_fma_f32 v[100:101], v[4:5], v[106:107], v[108:109]
	v_lshlrev_b32_e32 v106, 16, v56
	v_and_b32_e32 v107, 0xffff0000, v56
	v_lshlrev_b32_e32 v108, 16, v48
	v_and_b32_e32 v109, 0xffff0000, v48
	v_pk_mul_f32 v[106:107], v[96:97], v[106:107] op_sel_hi:[0,1]
	v_pk_fma_f32 v[102:103], v[6:7], v[106:107], v[108:109]
	v_lshlrev_b32_e32 v106, 16, v57
	v_and_b32_e32 v107, 0xffff0000, v57
	v_lshlrev_b32_e32 v108, 16, v49
	v_and_b32_e32 v109, 0xffff0000, v49
	v_pk_mul_f32 v[106:107], v[96:97], v[106:107] op_sel_hi:[0,1]
	v_pk_fma_f32 v[104:105], v[8:9], v[106:107], v[108:109]
	v_pk_fma_f32 v[110:111], v[98:99], v[98:99], v[110:111]
	v_pk_fma_f32 v[110:111], v[100:101], v[100:101], v[110:111]
	v_pk_fma_f32 v[110:111], v[102:103], v[102:103], v[110:111]
	v_pk_fma_f32 v[110:111], v[104:105], v[104:105], v[110:111]
	v_cvt_pk_bf16_f32 v46, v98, v99
	v_cvt_pk_bf16_f32 v47, v100, v101
	v_cvt_pk_bf16_f32 v48, v102, v103
	v_cvt_pk_bf16_f32 v49, v104, v105
	global_store_dwordx4 v19, v[46:49], s[4:5] offset:1024 nt
	v_add_f32_e32 v112, v110, v111
	v_add_u32_e32 v22, 0x2000, v22
	s_nop 1
	v_add_f32_dpp v112, v112, v112 quad_perm:[1,0,3,2] row_mask:0xf bank_mask:0xf
	s_nop 1
	v_add_f32_dpp v112, v112, v112 quad_perm:[2,3,0,1] row_mask:0xf bank_mask:0xf
	s_nop 1
	v_add_f32_dpp v112, v112, v112 row_half_mirror row_mask:0xf bank_mask:0xf
	s_nop 1
	v_add_f32_dpp v112, v112, v112 row_mirror row_mask:0xf bank_mask:0xf
	s_nop 1
	v_add_f32_dpp v112, v112, v112 row_bcast:15 row_mask:0xa bank_mask:0xf
	s_nop 1
	v_add_f32_dpp v112, v112, v112 row_bcast:31 row_mask:0xc bank_mask:0xf
	v_fmamk_f32 v113, v112, 0x3a800000, v244
	v_rsq_f32_e32 v113, v113
	s_mov_b64 exec, s[6:7]
	global_store_dword v22, v113, s[4:5]
	s_mov_b64 exec, -1
	v_add_u32_e32 v18, 0x400000, v18
	v_add_u32_e32 v20, 0x400000, v20
	v_add_u32_e32 v21, 0x2000, v21
	global_load_dwordx4 v[42:45], v18, s[4:5]
	global_load_dwordx4 v[50:53], v20, s[4:5]
	global_load_dwordx4 v[46:49], v18, s[4:5] offset:1024
	global_load_dwordx4 v[54:57], v20, s[4:5] offset:1024
	global_load_dword v58, v21, s[4:5]
	s_waitcnt vmcnt(24)
; __device__ __forceinline__ float bflo(unsigned w) { return __uint_as_float(w << 16); }
; __device__ __forceinline__ float bfhi(unsigned w) { return __uint_as_float(w & 0xffff0000u); }
; __device__ __forceinline__ void resid_rows(bf16_t* R, const bf16_t* Y, const float* ssqY, const float* g, float* rstd_out, float* outf, bool wf32, int row_lo, int row_hi, int yoff, int gw, int NGW, int lane) {
;     ...
;     for (int row0 = row_lo + gw; row0 < row_hi; row0 += RP * NGW) {
;         u32x4 rr[RP][2], oo[RP][2]; float ssv[RP];
; #pragma unroll
;         for (int k = 0; k < RP; ++k) { const int row = row0 + k * NGW; const bool ok = row < row_hi; const int rw = ok ? row : row0;
;             ssv[k] = ssqY[rw];
; #pragma unroll
;             for (int j = 0; j < 2; ++j) { const int c = 8 * lane + 512 * j; rr[k][j] = *(const u32x4*)(R + (size_t)rw * DM + c); oo[k][j] = *(const u32x4*)(Y + (size_t)(rw - yoff) * DM + c); } }
; #pragma unroll
;         for (int k = 0; k < RP; ++k) { const int row = row0 + k * NGW; if (row < row_hi) {
;             const float rs = __builtin_amdgcn_rsqf(ssv[k] * (1.0f / DM) + RMS_EPS); float s = 0.f;
; #pragma unroll
;             for (int j = 0; j < 2; ++j) { const int c = 8 * lane + 512 * j; const u32x4 r = rr[k][j], o = oo[k][j]; const f32x4 ga = gv[j][0], gb = gv[j][1];
;                 f32x4 ya, yb; ya[0] = bflo(r.x) + bflo(o.x) * rs * ga[0]; ya[1] = bfhi(r.x) + bfhi(o.x) * rs * ga[1]; ya[2] = bflo(r.y) + bflo(o.y) * rs * ga[2]; ya[3] = bfhi(r.y) + bfhi(o.y) * rs * ga[3];
;                 yb[0] = bflo(r.z) + bflo(o.z) * rs * gb[0]; yb[1] = bfhi(r.z) + bfhi(o.z) * rs * gb[1]; yb[2] = bflo(r.w) + bflo(o.w) * rs * gb[2]; yb[3] = bfhi(r.w) + bfhi(o.w) * rs * gb[3];
;                 if (wf32) { *(f32x4*)(outf + (size_t)row * DM + c) = ya; *(f32x4*)(outf + (size_t)row * DM + c + 4) = yb; }
;                 s += (ya[0] * ya[0] + ya[1] * ya[1]) + (ya[2] * ya[2] + ya[3] * ya[3]) + (yb[0] * yb[0] + yb[1] * yb[1]) + (yb[2] * yb[2] + yb[3] * yb[3]);
;                 u32x4 w; w.x = pk2(ya[0], ya[1]); w.y = pk2(ya[2], ya[3]); w.z = pk2(yb[0], yb[1]); w.w = pk2(yb[2], yb[3]); *(u32x4*)(R + (size_t)row * DM + c) = w; }
;             s = wave_sum(s); if (lane == 0) rstd_out[row] = __builtin_amdgcn_rsqf(s * (1.0f / DM) + RMS_EPS); } }
	v_fmamk_f32 v96, v76, 0x3a800000, v244
	v_rsq_f32_e32 v96, v96
	v_add_u32_e32 v19, 0x400000, v19
	v_lshlrev_b32_e32 v106, 16, v68
	v_and_b32_e32 v107, 0xffff0000, v68
	v_lshlrev_b32_e32 v108, 16, v60
	v_and_b32_e32 v109, 0xffff0000, v60
	v_pk_mul_f32 v[106:107], v[96:97], v[106:107] op_sel_hi:[0,1]
	v_pk_fma_f32 v[98:99], v[10:11], v[106:107], v[108:109]
	v_lshlrev_b32_e32 v106, 16, v69
	v_and_b32_e32 v107, 0xffff0000, v69
	v_lshlrev_b32_e32 v108, 16, v61
	v_and_b32_e32 v109, 0xffff0000, v61
	v_pk_mul_f32 v[106:107], v[96:97], v[106:107] op_sel_hi:[0,1]
	v_pk_fma_f32 v[100:101], v[12:13], v[106:107], v[108:109]
	v_lshlrev_b32_e32 v106, 16, v70
	v_and_b32_e32 v107, 0xffff0000, v70
	v_lshlrev_b32_e32 v108, 16, v62
	v_and_b32_e32 v109, 0xffff0000, v62
	v_pk_mul_f32 v[106:107], v[96:97], v[106:107] op_sel_hi:[0,1]
	v_pk_fma_f32 v[102:103], v[14:15], v[106:107], v[108:109]
	v_lshlrev_b32_e32 v106, 16, v71
	v_and_b32_e32 v107, 0xffff0000, v71
	v_lshlrev_b32_e32 v108, 16, v63
	v_and_b32_e32 v109, 0xffff0000, v63
	v_pk_mul_f32 v[106:107], v[96:97], v[106:107] op_sel_hi:[0,1]
	v_pk_fma_f32 v[104:105], v[16:17], v[106:107], v[108:109]
	v_pk_mul_f32 v[110:111], v[98:99], v[98:99]
	v_pk_fma_f32 v[110:111], v[100:101], v[100:101], v[110:111]
	v_pk_fma_f32 v[110:111], v[102:103], v[102:103], v[110:111]
	v_pk_fma_f32 v[110:111], v[104:105], v[104:105], v[110:111]
	v_cvt_pk_bf16_f32 v60, v98, v99
	v_cvt_pk_bf16_f32 v61, v100, v101
	v_cvt_pk_bf16_f32 v62, v102, v103
	v_cvt_pk_bf16_f32 v63, v104, v105
	global_store_dwordx4 v19, v[60:63], s[4:5] nt
	v_lshlrev_b32_e32 v106, 16, v72
	v_and_b32_e32 v107, 0xffff0000, v72
	v_lshlrev_b32_e32 v108, 16, v64
	v_and_b32_e32 v109, 0xffff0000, v64
	v_pk_mul_f32 v[106:107], v[96:97], v[106:107] op_sel_hi:[0,1]
	v_pk_fma_f32 v[98:99], v[2:3], v[106:107], v[108:109]
	v_lshlrev_b32_e32 v106, 16, v73
	v_and_b32_e32 v107, 0xffff0000, v73
	v_lshlrev_b32_e32 v108, 16, v65
	v_and_b32_e32 v109, 0xffff0000, v65
	v_pk_mul_f32 v[106:107], v[96:97], v[106:107] op_sel_hi:[0,1]
	v_pk_fma_f32 v[100:101], v[4:5], v[106:107], v[108:109]
	v_lshlrev_b32_e32 v106, 16, v74
	v_and_b32_e32 v107, 0xffff0000, v74
	v_lshlrev_b32_e32 v108, 16, v66
	v_and_b32_e32 v109, 0xffff0000, v66
	v_pk_mul_f32 v[106:107], v[96:97], v[106:107] op_sel_hi:[0,1]
	v_pk_fma_f32 v[102:103], v[6:7], v[106:107], v[108:109]
	v_lshlrev_b32_e32 v106, 16, v75
	v_and_b32_e32 v107, 0xffff0000, v75
	v_lshlrev_b32_e32 v108, 16, v67
	v_and_b32_e32 v109, 0xffff0000, v67
	v_pk_mul_f32 v[106:107], v[96:97], v[106:107] op_sel_hi:[0,1]
	v_pk_fma_f32 v[104:105], v[8:9], v[106:107], v[108:109]
	v_pk_fma_f32 v[110:111], v[98:99], v[98:99], v[110:111]
	v_pk_fma_f32 v[110:111], v[100:101], v[100:101], v[110:111]
	v_pk_fma_f32 v[110:111], v[102:103], v[102:103], v[110:111]
	v_pk_fma_f32 v[110:111], v[104:105], v[104:105], v[110:111]
	v_cvt_pk_bf16_f32 v64, v98, v99
	v_cvt_pk_bf16_f32 v65, v100, v101
	v_cvt_pk_bf16_f32 v66, v102, v103
	v_cvt_pk_bf16_f32 v67, v104, v105
	global_store_dwordx4 v19, v[64:67], s[4:5] offset:1024 nt
	v_add_f32_e32 v112, v110, v111
	v_add_u32_e32 v22, 0x2000, v22
	s_nop 1
	v_add_f32_dpp v112, v112, v112 quad_perm:[1,0,3,2] row_mask:0xf bank_mask:0xf
	s_nop 1
	v_add_f32_dpp v112, v112, v112 quad_perm:[2,3,0,1] row_mask:0xf bank_mask:0xf
	s_nop 1
	v_add_f32_dpp v112, v112, v112 row_half_mirror row_mask:0xf bank_mask:0xf
	s_nop 1
	v_add_f32_dpp v112, v112, v112 row_mirror row_mask:0xf bank_mask:0xf
	s_nop 1
	v_add_f32_dpp v112, v112, v112 row_bcast:15 row_mask:0xa bank_mask:0xf
	s_nop 1
	v_add_f32_dpp v112, v112, v112 row_bcast:31 row_mask:0xc bank_mask:0xf
	v_fmamk_f32 v113, v112, 0x3a800000, v244
	v_rsq_f32_e32 v113, v113
	s_mov_b64 exec, s[6:7]
	global_store_dword v22, v113, s[4:5]
	s_mov_b64 exec, -1
	v_add_u32_e32 v18, 0x400000, v18
	v_add_u32_e32 v20, 0x400000, v20
	v_add_u32_e32 v21, 0x2000, v21
	global_load_dwordx4 v[60:63], v18, s[4:5]
	global_load_dwordx4 v[68:71], v20, s[4:5]
	global_load_dwordx4 v[64:67], v18, s[4:5] offset:1024
	global_load_dwordx4 v[72:75], v20, s[4:5] offset:1024
	global_load_dword v76, v21, s[4:5]
	s_waitcnt vmcnt(24)
	v_fmamk_f32 v96, v94, 0x3a800000, v244
	v_rsq_f32_e32 v96, v96
	v_add_u32_e32 v19, 0x400000, v19
	v_lshlrev_b32_e32 v106, 16, v86
	v_and_b32_e32 v107, 0xffff0000, v86
	v_lshlrev_b32_e32 v108, 16, v78
	v_and_b32_e32 v109, 0xffff0000, v78
	v_pk_mul_f32 v[106:107], v[96:97], v[106:107] op_sel_hi:[0,1]
	v_pk_fma_f32 v[98:99], v[10:11], v[106:107], v[108:109]
	v_lshlrev_b32_e32 v106, 16, v87
	v_and_b32_e32 v107, 0xffff0000, v87
	v_lshlrev_b32_e32 v108, 16, v79
	v_and_b32_e32 v109, 0xffff0000, v79
	v_pk_mul_f32 v[106:107], v[96:97], v[106:107] op_sel_hi:[0,1]
	v_pk_fma_f32 v[100:101], v[12:13], v[106:107], v[108:109]
	v_lshlrev_b32_e32 v106, 16, v88
	v_and_b32_e32 v107, 0xffff0000, v88
	v_lshlrev_b32_e32 v108, 16, v80
	v_and_b32_e32 v109, 0xffff0000, v80
	v_pk_mul_f32 v[106:107], v[96:97], v[106:107] op_sel_hi:[0,1]
	v_pk_fma_f32 v[102:103], v[14:15], v[106:107], v[108:109]
	v_lshlrev_b32_e32 v106, 16, v89
	v_and_b32_e32 v107, 0xffff0000, v89
	v_lshlrev_b32_e32 v108, 16, v81
	v_and_b32_e32 v109, 0xffff0000, v81
	v_pk_mul_f32 v[106:107], v[96:97], v[106:107] op_sel_hi:[0,1]
	v_pk_fma_f32 v[104:105], v[16:17], v[106:107], v[108:109]
	v_pk_mul_f32 v[110:111], v[98:99], v[98:99]
	v_pk_fma_f32 v[110:111], v[100:101], v[100:101], v[110:111]
	v_pk_fma_f32 v[110:111], v[102:103], v[102:103], v[110:111]
	v_pk_fma_f32 v[110:111], v[104:105], v[104:105], v[110:111]
	v_cvt_pk_bf16_f32 v78, v98, v99
	v_cvt_pk_bf16_f32 v79, v100, v101
	v_cvt_pk_bf16_f32 v80, v102, v103
	v_cvt_pk_bf16_f32 v81, v104, v105
	global_store_dwordx4 v19, v[78:81], s[4:5] nt
; __device__ __forceinline__ float bflo(unsigned w) { return __uint_as_float(w << 16); }
; __device__ __forceinline__ float bfhi(unsigned w) { return __uint_as_float(w & 0xffff0000u); }
; __device__ __forceinline__ void resid_rows(bf16_t* R, const bf16_t* Y, const float* ssqY, const float* g, float* rstd_out, float* outf, bool wf32, int row_lo, int row_hi, int yoff, int gw, int NGW, int lane) {
;     ...
;     for (int row0 = row_lo + gw; row0 < row_hi; row0 += RP * NGW) {
;         u32x4 rr[RP][2], oo[RP][2]; float ssv[RP];
; #pragma unroll
;         for (int k = 0; k < RP; ++k) { const int row = row0 + k * NGW; const bool ok = row < row_hi; const int rw = ok ? row : row0;
;             ssv[k] = ssqY[rw];
; #pragma unroll
;             for (int j = 0; j < 2; ++j) { const int c = 8 * lane + 512 * j; rr[k][j] = *(const u32x4*)(R + (size_t)rw * DM + c); oo[k][j] = *(const u32x4*)(Y + (size_t)(rw - yoff) * DM + c); } }
; #pragma unroll
;         for (int k = 0; k < RP; ++k) { const int row = row0 + k * NGW; if (row < row_hi) {
;             const float rs = __builtin_amdgcn_rsqf(ssv[k] * (1.0f / DM) + RMS_EPS); float s = 0.f;
; #pragma unroll
;             for (int j = 0; j < 2; ++j) { const int c = 8 * lane + 512 * j; const u32x4 r = rr[k][j], o = oo[k][j]; const f32x4 ga = gv[j][0], gb = gv[j][1];
;                 f32x4 ya, yb; ya[0] = bflo(r.x) + bflo(o.x) * rs * ga[0]; ya[1] = bfhi(r.x) + bfhi(o.x) * rs * ga[1]; ya[2] = bflo(r.y) + bflo(o.y) * rs * ga[2]; ya[3] = bfhi(r.y) + bfhi(o.y) * rs * ga[3];
;                 yb[0] = bflo(r.z) + bflo(o.z) * rs * gb[0]; yb[1] = bfhi(r.z) + bfhi(o.z) * rs * gb[1]; yb[2] = bflo(r.w) + bflo(o.w) * rs * gb[2]; yb[3] = bfhi(r.w) + bfhi(o.w) * rs * gb[3];
;                 if (wf32) { *(f32x4*)(outf + (size_t)row * DM + c) = ya; *(f32x4*)(outf + (size_t)row * DM + c + 4) = yb; }
;                 s += (ya[0] * ya[0] + ya[1] * ya[1]) + (ya[2] * ya[2] + ya[3] * ya[3]) + (yb[0] * yb[0] + yb[1] * yb[1]) + (yb[2] * yb[2] + yb[3] * yb[3]);
;                 u32x4 w; w.x = pk2(ya[0], ya[1]); w.y = pk2(ya[2], ya[3]); w.z = pk2(yb[0], yb[1]); w.w = pk2(yb[2], yb[3]); *(u32x4*)(R + (size_t)row * DM + c) = w; }
;             s = wave_sum(s); if (lane == 0) rstd_out[row] = __builtin_amdgcn_rsqf(s * (1.0f / DM) + RMS_EPS); } }
	v_lshlrev_b32_e32 v106, 16, v90
	v_and_b32_e32 v107, 0xffff0000, v90
	v_lshlrev_b32_e32 v108, 16, v82
	v_and_b32_e32 v109, 0xffff0000, v82
	v_pk_mul_f32 v[106:107], v[96:97], v[106:107] op_sel_hi:[0,1]
	v_pk_fma_f32 v[98:99], v[2:3], v[106:107], v[108:109]
	v_lshlrev_b32_e32 v106, 16, v91
	v_and_b32_e32 v107, 0xffff0000, v91
	v_lshlrev_b32_e32 v108, 16, v83
	v_and_b32_e32 v109, 0xffff0000, v83
	v_pk_mul_f32 v[106:107], v[96:97], v[106:107] op_sel_hi:[0,1]
	v_pk_fma_f32 v[100:101], v[4:5], v[106:107], v[108:109]
	v_lshlrev_b32_e32 v106, 16, v92
	v_and_b32_e32 v107, 0xffff0000, v92
	v_lshlrev_b32_e32 v108, 16, v84
	v_and_b32_e32 v109, 0xffff0000, v84
	v_pk_mul_f32 v[106:107], v[96:97], v[106:107] op_sel_hi:[0,1]
	v_pk_fma_f32 v[102:103], v[6:7], v[106:107], v[108:109]
	v_lshlrev_b32_e32 v106, 16, v93
	v_and_b32_e32 v107, 0xffff0000, v93
	v_lshlrev_b32_e32 v108, 16, v85
	v_and_b32_e32 v109, 0xffff0000, v85
	v_pk_mul_f32 v[106:107], v[96:97], v[106:107] op_sel_hi:[0,1]
	v_pk_fma_f32 v[104:105], v[8:9], v[106:107], v[108:109]
	v_pk_fma_f32 v[110:111], v[98:99], v[98:99], v[110:111]
	v_pk_fma_f32 v[110:111], v[100:101], v[100:101], v[110:111]
	v_pk_fma_f32 v[110:111], v[102:103], v[102:103], v[110:111]
	v_pk_fma_f32 v[110:111], v[104:105], v[104:105], v[110:111]
	v_cvt_pk_bf16_f32 v82, v98, v99
	v_cvt_pk_bf16_f32 v83, v100, v101
	v_cvt_pk_bf16_f32 v84, v102, v103
	v_cvt_pk_bf16_f32 v85, v104, v105
	global_store_dwordx4 v19, v[82:85], s[4:5] offset:1024 nt
	v_add_f32_e32 v112, v110, v111
	v_add_u32_e32 v22, 0x2000, v22
	s_nop 1
	v_add_f32_dpp v112, v112, v112 quad_perm:[1,0,3,2] row_mask:0xf bank_mask:0xf
	s_nop 1
	v_add_f32_dpp v112, v112, v112 quad_perm:[2,3,0,1] row_mask:0xf bank_mask:0xf
	s_nop 1
	v_add_f32_dpp v112, v112, v112 row_half_mirror row_mask:0xf bank_mask:0xf
	s_nop 1
	v_add_f32_dpp v112, v112, v112 row_mirror row_mask:0xf bank_mask:0xf
	s_nop 1
	v_add_f32_dpp v112, v112, v112 row_bcast:15 row_mask:0xa bank_mask:0xf
	s_nop 1
	v_add_f32_dpp v112, v112, v112 row_bcast:31 row_mask:0xc bank_mask:0xf
	v_fmamk_f32 v113, v112, 0x3a800000, v244
	v_rsq_f32_e32 v113, v113
	s_mov_b64 exec, s[6:7]
	global_store_dword v22, v113, s[4:5]
	s_mov_b64 exec, -1
	v_add_u32_e32 v18, 0x400000, v18
	v_add_u32_e32 v20, 0x400000, v20
	v_add_u32_e32 v21, 0x2000, v21
	global_load_dwordx4 v[78:81], v18, s[4:5]
	global_load_dwordx4 v[86:89], v20, s[4:5]
	global_load_dwordx4 v[82:85], v18, s[4:5] offset:1024
	global_load_dwordx4 v[90:93], v20, s[4:5] offset:1024
	global_load_dword v94, v21, s[4:5]
	s_waitcnt vmcnt(24)
	v_fmamk_f32 v96, v40, 0x3a800000, v244
	v_rsq_f32_e32 v96, v96
	v_add_u32_e32 v19, 0x400000, v19
	v_lshlrev_b32_e32 v106, 16, v32
	v_and_b32_e32 v107, 0xffff0000, v32
	v_lshlrev_b32_e32 v108, 16, v24
	v_and_b32_e32 v109, 0xffff0000, v24
	v_pk_mul_f32 v[106:107], v[96:97], v[106:107] op_sel_hi:[0,1]
	v_pk_fma_f32 v[98:99], v[10:11], v[106:107], v[108:109]
	v_lshlrev_b32_e32 v106, 16, v33
	v_and_b32_e32 v107, 0xffff0000, v33
	v_lshlrev_b32_e32 v108, 16, v25
	v_and_b32_e32 v109, 0xffff0000, v25
	v_pk_mul_f32 v[106:107], v[96:97], v[106:107] op_sel_hi:[0,1]
	v_pk_fma_f32 v[100:101], v[12:13], v[106:107], v[108:109]
	v_lshlrev_b32_e32 v106, 16, v34
	v_and_b32_e32 v107, 0xffff0000, v34
	v_lshlrev_b32_e32 v108, 16, v26
	v_and_b32_e32 v109, 0xffff0000, v26
	v_pk_mul_f32 v[106:107], v[96:97], v[106:107] op_sel_hi:[0,1]
	v_pk_fma_f32 v[102:103], v[14:15], v[106:107], v[108:109]
	v_lshlrev_b32_e32 v106, 16, v35
	v_and_b32_e32 v107, 0xffff0000, v35
	v_lshlrev_b32_e32 v108, 16, v27
	v_and_b32_e32 v109, 0xffff0000, v27
	v_pk_mul_f32 v[106:107], v[96:97], v[106:107] op_sel_hi:[0,1]
	v_pk_fma_f32 v[104:105], v[16:17], v[106:107], v[108:109]
	v_pk_mul_f32 v[110:111], v[98:99], v[98:99]
	v_pk_fma_f32 v[110:111], v[100:101], v[100:101], v[110:111]
	v_pk_fma_f32 v[110:111], v[102:103], v[102:103], v[110:111]
	v_pk_fma_f32 v[110:111], v[104:105], v[104:105], v[110:111]
	v_cvt_pk_bf16_f32 v24, v98, v99
	v_cvt_pk_bf16_f32 v25, v100, v101
	v_cvt_pk_bf16_f32 v26, v102, v103
	v_cvt_pk_bf16_f32 v27, v104, v105
	global_store_dwordx4 v19, v[24:27], s[4:5] nt
	v_lshlrev_b32_e32 v106, 16, v36
	v_and_b32_e32 v107, 0xffff0000, v36
	v_lshlrev_b32_e32 v108, 16, v28
	v_and_b32_e32 v109, 0xffff0000, v28
	v_pk_mul_f32 v[106:107], v[96:97], v[106:107] op_sel_hi:[0,1]
	v_pk_fma_f32 v[98:99], v[2:3], v[106:107], v[108:109]
	v_lshlrev_b32_e32 v106, 16, v37
	v_and_b32_e32 v107, 0xffff0000, v37
	v_lshlrev_b32_e32 v108, 16, v29
	v_and_b32_e32 v109, 0xffff0000, v29
	v_pk_mul_f32 v[106:107], v[96:97], v[106:107] op_sel_hi:[0,1]
	v_pk_fma_f32 v[100:101], v[4:5], v[106:107], v[108:109]
	v_lshlrev_b32_e32 v106, 16, v38
	v_and_b32_e32 v107, 0xffff0000, v38
	v_lshlrev_b32_e32 v108, 16, v30
	v_and_b32_e32 v109, 0xffff0000, v30
	v_pk_mul_f32 v[106:107], v[96:97], v[106:107] op_sel_hi:[0,1]
	v_pk_fma_f32 v[102:103], v[6:7], v[106:107], v[108:109]
	v_lshlrev_b32_e32 v106, 16, v39
	v_and_b32_e32 v107, 0xffff0000, v39
	v_lshlrev_b32_e32 v108, 16, v31
	v_and_b32_e32 v109, 0xffff0000, v31
	v_pk_mul_f32 v[106:107], v[96:97], v[106:107] op_sel_hi:[0,1]
	v_pk_fma_f32 v[104:105], v[8:9], v[106:107], v[108:109]
	v_pk_fma_f32 v[110:111], v[98:99], v[98:99], v[110:111]
	v_pk_fma_f32 v[110:111], v[100:101], v[100:101], v[110:111]
	v_pk_fma_f32 v[110:111], v[102:103], v[102:103], v[110:111]
	v_pk_fma_f32 v[110:111], v[104:105], v[104:105], v[110:111]
	v_cvt_pk_bf16_f32 v28, v98, v99
	v_cvt_pk_bf16_f32 v29, v100, v101
	v_cvt_pk_bf16_f32 v30, v102, v103
	v_cvt_pk_bf16_f32 v31, v104, v105
	global_store_dwordx4 v19, v[28:31], s[4:5] offset:1024 nt
	v_add_f32_e32 v112, v110, v111
	v_add_u32_e32 v22, 0x2000, v22
	s_nop 1
	v_add_f32_dpp v112, v112, v112 quad_perm:[1,0,3,2] row_mask:0xf bank_mask:0xf
	s_nop 1
	v_add_f32_dpp v112, v112, v112 quad_perm:[2,3,0,1] row_mask:0xf bank_mask:0xf
	s_nop 1
	v_add_f32_dpp v112, v112, v112 row_half_mirror row_mask:0xf bank_mask:0xf
	s_nop 1
	v_add_f32_dpp v112, v112, v112 row_mirror row_mask:0xf bank_mask:0xf
	s_nop 1
	v_add_f32_dpp v112, v112, v112 row_bcast:15 row_mask:0xa bank_mask:0xf
	s_nop 1
	v_add_f32_dpp v112, v112, v112 row_bcast:31 row_mask:0xc bank_mask:0xf
	v_fmamk_f32 v113, v112, 0x3a800000, v244
	v_rsq_f32_e32 v113, v113
	s_mov_b64 exec, s[6:7]
	global_store_dword v22, v113, s[4:5]
	s_mov_b64 exec, -1
	s_waitcnt vmcnt(19)
; __device__ __forceinline__ float bflo(unsigned w) { return __uint_as_float(w << 16); }
; __device__ __forceinline__ float bfhi(unsigned w) { return __uint_as_float(w & 0xffff0000u); }
; __device__ __forceinline__ void resid_rows(bf16_t* R, const bf16_t* Y, const float* ssqY, const float* g, float* rstd_out, float* outf, bool wf32, int row_lo, int row_hi, int yoff, int gw, int NGW, int lane) {
;     ...
;     for (int row0 = row_lo + gw; row0 < row_hi; row0 += RP * NGW) {
;         u32x4 rr[RP][2], oo[RP][2]; float ssv[RP];
; #pragma unroll
;         for (int k = 0; k < RP; ++k) { const int row = row0 + k * NGW; const bool ok = row < row_hi; const int rw = ok ? row : row0;
;             ssv[k] = ssqY[rw];
; #pragma unroll
;             for (int j = 0; j < 2; ++j) { const int c = 8 * lane + 512 * j; rr[k][j] = *(const u32x4*)(R + (size_t)rw * DM + c); oo[k][j] = *(const u32x4*)(Y + (size_t)(rw - yoff) * DM + c); } }
; #pragma unroll
;         for (int k = 0; k < RP; ++k) { const int row = row0 + k * NGW; if (row < row_hi) {
;             const float rs = __builtin_amdgcn_rsqf(ssv[k] * (1.0f / DM) + RMS_EPS); float s = 0.f;
; #pragma unroll
;             for (int j = 0; j < 2; ++j) { const int c = 8 * lane + 512 * j; const u32x4 r = rr[k][j], o = oo[k][j]; const f32x4 ga = gv[j][0], gb = gv[j][1];
;                 f32x4 ya, yb; ya[0] = bflo(r.x) + bflo(o.x) * rs * ga[0]; ya[1] = bfhi(r.x) + bfhi(o.x) * rs * ga[1]; ya[2] = bflo(r.y) + bflo(o.y) * rs * ga[2]; ya[3] = bfhi(r.y) + bfhi(o.y) * rs * ga[3];
;                 yb[0] = bflo(r.z) + bflo(o.z) * rs * gb[0]; yb[1] = bfhi(r.z) + bfhi(o.z) * rs * gb[1]; yb[2] = bflo(r.w) + bflo(o.w) * rs * gb[2]; yb[3] = bfhi(r.w) + bfhi(o.w) * rs * gb[3];
;                 if (wf32) { *(f32x4*)(outf + (size_t)row * DM + c) = ya; *(f32x4*)(outf + (size_t)row * DM + c + 4) = yb; }
;                 s += (ya[0] * ya[0] + ya[1] * ya[1]) + (ya[2] * ya[2] + ya[3] * ya[3]) + (yb[0] * yb[0] + yb[1] * yb[1]) + (yb[2] * yb[2] + yb[3] * yb[3]);
;                 u32x4 w; w.x = pk2(ya[0], ya[1]); w.y = pk2(ya[2], ya[3]); w.z = pk2(yb[0], yb[1]); w.w = pk2(yb[2], yb[3]); *(u32x4*)(R + (size_t)row * DM + c) = w; }
;             s = wave_sum(s); if (lane == 0) rstd_out[row] = __builtin_amdgcn_rsqf(s * (1.0f / DM) + RMS_EPS); } }
	v_fmamk_f32 v96, v58, 0x3a800000, v244
	v_rsq_f32_e32 v96, v96
	v_add_u32_e32 v19, 0x400000, v19
	v_lshlrev_b32_e32 v106, 16, v50
	v_and_b32_e32 v107, 0xffff0000, v50
	v_lshlrev_b32_e32 v108, 16, v42
	v_and_b32_e32 v109, 0xffff0000, v42
	v_pk_mul_f32 v[106:107], v[96:97], v[106:107] op_sel_hi:[0,1]
	v_pk_fma_f32 v[98:99], v[10:11], v[106:107], v[108:109]
	v_lshlrev_b32_e32 v106, 16, v51
	v_and_b32_e32 v107, 0xffff0000, v51
	v_lshlrev_b32_e32 v108, 16, v43
	v_and_b32_e32 v109, 0xffff0000, v43
	v_pk_mul_f32 v[106:107], v[96:97], v[106:107] op_sel_hi:[0,1]
	v_pk_fma_f32 v[100:101], v[12:13], v[106:107], v[108:109]
	v_lshlrev_b32_e32 v106, 16, v52
	v_and_b32_e32 v107, 0xffff0000, v52
	v_lshlrev_b32_e32 v108, 16, v44
	v_and_b32_e32 v109, 0xffff0000, v44
	v_pk_mul_f32 v[106:107], v[96:97], v[106:107] op_sel_hi:[0,1]
	v_pk_fma_f32 v[102:103], v[14:15], v[106:107], v[108:109]
	v_lshlrev_b32_e32 v106, 16, v53
	v_and_b32_e32 v107, 0xffff0000, v53
	v_lshlrev_b32_e32 v108, 16, v45
	v_and_b32_e32 v109, 0xffff0000, v45
	v_pk_mul_f32 v[106:107], v[96:97], v[106:107] op_sel_hi:[0,1]
	v_pk_fma_f32 v[104:105], v[16:17], v[106:107], v[108:109]
	v_pk_mul_f32 v[110:111], v[98:99], v[98:99]
	v_pk_fma_f32 v[110:111], v[100:101], v[100:101], v[110:111]
	v_pk_fma_f32 v[110:111], v[102:103], v[102:103], v[110:111]
	v_pk_fma_f32 v[110:111], v[104:105], v[104:105], v[110:111]
	v_cvt_pk_bf16_f32 v42, v98, v99
	v_cvt_pk_bf16_f32 v43, v100, v101
	v_cvt_pk_bf16_f32 v44, v102, v103
	v_cvt_pk_bf16_f32 v45, v104, v105
	global_store_dwordx4 v19, v[42:45], s[4:5] nt
	v_lshlrev_b32_e32 v106, 16, v54
	v_and_b32_e32 v107, 0xffff0000, v54
	v_lshlrev_b32_e32 v108, 16, v46
	v_and_b32_e32 v109, 0xffff0000, v46
	v_pk_mul_f32 v[106:107], v[96:97], v[106:107] op_sel_hi:[0,1]
	v_pk_fma_f32 v[98:99], v[2:3], v[106:107], v[108:109]
	v_lshlrev_b32_e32 v106, 16, v55
	v_and_b32_e32 v107, 0xffff0000, v55
	v_lshlrev_b32_e32 v108, 16, v47
	v_and_b32_e32 v109, 0xffff0000, v47
	v_pk_mul_f32 v[106:107], v[96:97], v[106:107] op_sel_hi:[0,1]
	v_pk_fma_f32 v[100:101], v[4:5], v[106:107], v[108:109]
	v_lshlrev_b32_e32 v106, 16, v56
	v_and_b32_e32 v107, 0xffff0000, v56
	v_lshlrev_b32_e32 v108, 16, v48
	v_and_b32_e32 v109, 0xffff0000, v48
	v_pk_mul_f32 v[106:107], v[96:97], v[106:107] op_sel_hi:[0,1]
	v_pk_fma_f32 v[102:103], v[6:7], v[106:107], v[108:109]
	v_lshlrev_b32_e32 v106, 16, v57
	v_and_b32_e32 v107, 0xffff0000, v57
	v_lshlrev_b32_e32 v108, 16, v49
	v_and_b32_e32 v109, 0xffff0000, v49
	v_pk_mul_f32 v[106:107], v[96:97], v[106:107] op_sel_hi:[0,1]
	v_pk_fma_f32 v[104:105], v[8:9], v[106:107], v[108:109]
	v_pk_fma_f32 v[110:111], v[98:99], v[98:99], v[110:111]
	v_pk_fma_f32 v[110:111], v[100:101], v[100:101], v[110:111]
	v_pk_fma_f32 v[110:111], v[102:103], v[102:103], v[110:111]
	v_pk_fma_f32 v[110:111], v[104:105], v[104:105], v[110:111]
	v_cvt_pk_bf16_f32 v46, v98, v99
	v_cvt_pk_bf16_f32 v47, v100, v101
	v_cvt_pk_bf16_f32 v48, v102, v103
	v_cvt_pk_bf16_f32 v49, v104, v105
	global_store_dwordx4 v19, v[46:49], s[4:5] offset:1024 nt
	v_add_f32_e32 v112, v110, v111
	v_add_u32_e32 v22, 0x2000, v22
	s_nop 1
	v_add_f32_dpp v112, v112, v112 quad_perm:[1,0,3,2] row_mask:0xf bank_mask:0xf
	s_nop 1
	v_add_f32_dpp v112, v112, v112 quad_perm:[2,3,0,1] row_mask:0xf bank_mask:0xf
	s_nop 1
	v_add_f32_dpp v112, v112, v112 row_half_mirror row_mask:0xf bank_mask:0xf
	s_nop 1
	v_add_f32_dpp v112, v112, v112 row_mirror row_mask:0xf bank_mask:0xf
	s_nop 1
	v_add_f32_dpp v112, v112, v112 row_bcast:15 row_mask:0xa bank_mask:0xf
	s_nop 1
	v_add_f32_dpp v112, v112, v112 row_bcast:31 row_mask:0xc bank_mask:0xf
	v_fmamk_f32 v113, v112, 0x3a800000, v244
	v_rsq_f32_e32 v113, v113
	s_mov_b64 exec, s[6:7]
	global_store_dword v22, v113, s[4:5]
	s_mov_b64 exec, -1
	s_waitcnt vmcnt(14)
	v_fmamk_f32 v96, v76, 0x3a800000, v244
	v_rsq_f32_e32 v96, v96
	v_add_u32_e32 v19, 0x400000, v19
	v_lshlrev_b32_e32 v106, 16, v68
	v_and_b32_e32 v107, 0xffff0000, v68
	v_lshlrev_b32_e32 v108, 16, v60
	v_and_b32_e32 v109, 0xffff0000, v60
	v_pk_mul_f32 v[106:107], v[96:97], v[106:107] op_sel_hi:[0,1]
	v_pk_fma_f32 v[98:99], v[10:11], v[106:107], v[108:109]
	v_lshlrev_b32_e32 v106, 16, v69
	v_and_b32_e32 v107, 0xffff0000, v69
	v_lshlrev_b32_e32 v108, 16, v61
	v_and_b32_e32 v109, 0xffff0000, v61
	v_pk_mul_f32 v[106:107], v[96:97], v[106:107] op_sel_hi:[0,1]
	v_pk_fma_f32 v[100:101], v[12:13], v[106:107], v[108:109]
	v_lshlrev_b32_e32 v106, 16, v70
	v_and_b32_e32 v107, 0xffff0000, v70
	v_lshlrev_b32_e32 v108, 16, v62
	v_and_b32_e32 v109, 0xffff0000, v62
	v_pk_mul_f32 v[106:107], v[96:97], v[106:107] op_sel_hi:[0,1]
	v_pk_fma_f32 v[102:103], v[14:15], v[106:107], v[108:109]
	v_lshlrev_b32_e32 v106, 16, v71
	v_and_b32_e32 v107, 0xffff0000, v71
	v_lshlrev_b32_e32 v108, 16, v63
	v_and_b32_e32 v109, 0xffff0000, v63
	v_pk_mul_f32 v[106:107], v[96:97], v[106:107] op_sel_hi:[0,1]
	v_pk_fma_f32 v[104:105], v[16:17], v[106:107], v[108:109]
	v_pk_mul_f32 v[110:111], v[98:99], v[98:99]
	v_pk_fma_f32 v[110:111], v[100:101], v[100:101], v[110:111]
	v_pk_fma_f32 v[110:111], v[102:103], v[102:103], v[110:111]
	v_pk_fma_f32 v[110:111], v[104:105], v[104:105], v[110:111]
	v_cvt_pk_bf16_f32 v60, v98, v99
	v_cvt_pk_bf16_f32 v61, v100, v101
	v_cvt_pk_bf16_f32 v62, v102, v103
	v_cvt_pk_bf16_f32 v63, v104, v105
	global_store_dwordx4 v19, v[60:63], s[4:5] nt
	v_lshlrev_b32_e32 v106, 16, v72
	v_and_b32_e32 v107, 0xffff0000, v72
	v_lshlrev_b32_e32 v108, 16, v64
	v_and_b32_e32 v109, 0xffff0000, v64
	v_pk_mul_f32 v[106:107], v[96:97], v[106:107] op_sel_hi:[0,1]
	v_pk_fma_f32 v[98:99], v[2:3], v[106:107], v[108:109]
	v_lshlrev_b32_e32 v106, 16, v73
	v_and_b32_e32 v107, 0xffff0000, v73
; __device__ __forceinline__ float bflo(unsigned w) { return __uint_as_float(w << 16); }
; __device__ __forceinline__ float bfhi(unsigned w) { return __uint_as_float(w & 0xffff0000u); }
; __device__ __forceinline__ void resid_rows(bf16_t* R, const bf16_t* Y, const float* ssqY, const float* g, float* rstd_out, float* outf, bool wf32, int row_lo, int row_hi, int yoff, int gw, int NGW, int lane) {
;     ...
;     for (int row0 = row_lo + gw; row0 < row_hi; row0 += RP * NGW) {
;         u32x4 rr[RP][2], oo[RP][2]; float ssv[RP];
; #pragma unroll
;         for (int k = 0; k < RP; ++k) { const int row = row0 + k * NGW; const bool ok = row < row_hi; const int rw = ok ? row : row0;
;             ssv[k] = ssqY[rw];
; #pragma unroll
;             for (int j = 0; j < 2; ++j) { const int c = 8 * lane + 512 * j; rr[k][j] = *(const u32x4*)(R + (size_t)rw * DM + c); oo[k][j] = *(const u32x4*)(Y + (size_t)(rw - yoff) * DM + c); } }
; #pragma unroll
;         for (int k = 0; k < RP; ++k) { const int row = row0 + k * NGW; if (row < row_hi) {
;             const float rs = __builtin_amdgcn_rsqf(ssv[k] * (1.0f / DM) + RMS_EPS); float s = 0.f;
; #pragma unroll
;             for (int j = 0; j < 2; ++j) { const int c = 8 * lane + 512 * j; const u32x4 r = rr[k][j], o = oo[k][j]; const f32x4 ga = gv[j][0], gb = gv[j][1];
;                 f32x4 ya, yb; ya[0] = bflo(r.x) + bflo(o.x) * rs * ga[0]; ya[1] = bfhi(r.x) + bfhi(o.x) * rs * ga[1]; ya[2] = bflo(r.y) + bflo(o.y) * rs * ga[2]; ya[3] = bfhi(r.y) + bfhi(o.y) * rs * ga[3];
;                 yb[0] = bflo(r.z) + bflo(o.z) * rs * gb[0]; yb[1] = bfhi(r.z) + bfhi(o.z) * rs * gb[1]; yb[2] = bflo(r.w) + bflo(o.w) * rs * gb[2]; yb[3] = bfhi(r.w) + bfhi(o.w) * rs * gb[3];
;                 if (wf32) { *(f32x4*)(outf + (size_t)row * DM + c) = ya; *(f32x4*)(outf + (size_t)row * DM + c + 4) = yb; }
;                 s += (ya[0] * ya[0] + ya[1] * ya[1]) + (ya[2] * ya[2] + ya[3] * ya[3]) + (yb[0] * yb[0] + yb[1] * yb[1]) + (yb[2] * yb[2] + yb[3] * yb[3]);
;                 u32x4 w; w.x = pk2(ya[0], ya[1]); w.y = pk2(ya[2], ya[3]); w.z = pk2(yb[0], yb[1]); w.w = pk2(yb[2], yb[3]); *(u32x4*)(R + (size_t)row * DM + c) = w; }
;             s = wave_sum(s); if (lane == 0) rstd_out[row] = __builtin_amdgcn_rsqf(s * (1.0f / DM) + RMS_EPS); } }
	v_lshlrev_b32_e32 v108, 16, v65
	v_and_b32_e32 v109, 0xffff0000, v65
	v_pk_mul_f32 v[106:107], v[96:97], v[106:107] op_sel_hi:[0,1]
	v_pk_fma_f32 v[100:101], v[4:5], v[106:107], v[108:109]
	v_lshlrev_b32_e32 v106, 16, v74
	v_and_b32_e32 v107, 0xffff0000, v74
	v_lshlrev_b32_e32 v108, 16, v66
	v_and_b32_e32 v109, 0xffff0000, v66
	v_pk_mul_f32 v[106:107], v[96:97], v[106:107] op_sel_hi:[0,1]
	v_pk_fma_f32 v[102:103], v[6:7], v[106:107], v[108:109]
	v_lshlrev_b32_e32 v106, 16, v75
	v_and_b32_e32 v107, 0xffff0000, v75
	v_lshlrev_b32_e32 v108, 16, v67
	v_and_b32_e32 v109, 0xffff0000, v67
	v_pk_mul_f32 v[106:107], v[96:97], v[106:107] op_sel_hi:[0,1]
	v_pk_fma_f32 v[104:105], v[8:9], v[106:107], v[108:109]
	v_pk_fma_f32 v[110:111], v[98:99], v[98:99], v[110:111]
	v_pk_fma_f32 v[110:111], v[100:101], v[100:101], v[110:111]
	v_pk_fma_f32 v[110:111], v[102:103], v[102:103], v[110:111]
	v_pk_fma_f32 v[110:111], v[104:105], v[104:105], v[110:111]
	v_cvt_pk_bf16_f32 v64, v98, v99
	v_cvt_pk_bf16_f32 v65, v100, v101
	v_cvt_pk_bf16_f32 v66, v102, v103
	v_cvt_pk_bf16_f32 v67, v104, v105
	global_store_dwordx4 v19, v[64:67], s[4:5] offset:1024 nt
	v_add_f32_e32 v112, v110, v111
	v_add_u32_e32 v22, 0x2000, v22
	s_nop 1
	v_add_f32_dpp v112, v112, v112 quad_perm:[1,0,3,2] row_mask:0xf bank_mask:0xf
	s_nop 1
	v_add_f32_dpp v112, v112, v112 quad_perm:[2,3,0,1] row_mask:0xf bank_mask:0xf
	s_nop 1
	v_add_f32_dpp v112, v112, v112 row_half_mirror row_mask:0xf bank_mask:0xf
	s_nop 1
	v_add_f32_dpp v112, v112, v112 row_mirror row_mask:0xf bank_mask:0xf
	s_nop 1
	v_add_f32_dpp v112, v112, v112 row_bcast:15 row_mask:0xa bank_mask:0xf
	s_nop 1
	v_add_f32_dpp v112, v112, v112 row_bcast:31 row_mask:0xc bank_mask:0xf
	v_fmamk_f32 v113, v112, 0x3a800000, v244
	v_rsq_f32_e32 v113, v113
	s_mov_b64 exec, s[6:7]
	global_store_dword v22, v113, s[4:5]
	s_mov_b64 exec, -1
	s_waitcnt vmcnt(9)
	v_fmamk_f32 v96, v94, 0x3a800000, v244
	v_rsq_f32_e32 v96, v96
	v_add_u32_e32 v19, 0x400000, v19
	v_lshlrev_b32_e32 v106, 16, v86
	v_and_b32_e32 v107, 0xffff0000, v86
	v_lshlrev_b32_e32 v108, 16, v78
	v_and_b32_e32 v109, 0xffff0000, v78
	v_pk_mul_f32 v[106:107], v[96:97], v[106:107] op_sel_hi:[0,1]
	v_pk_fma_f32 v[98:99], v[10:11], v[106:107], v[108:109]
	v_lshlrev_b32_e32 v106, 16, v87
	v_and_b32_e32 v107, 0xffff0000, v87
	v_lshlrev_b32_e32 v108, 16, v79
	v_and_b32_e32 v109, 0xffff0000, v79
	v_pk_mul_f32 v[106:107], v[96:97], v[106:107] op_sel_hi:[0,1]
	v_pk_fma_f32 v[100:101], v[12:13], v[106:107], v[108:109]
	v_lshlrev_b32_e32 v106, 16, v88
	v_and_b32_e32 v107, 0xffff0000, v88
	v_lshlrev_b32_e32 v108, 16, v80
	v_and_b32_e32 v109, 0xffff0000, v80
	v_pk_mul_f32 v[106:107], v[96:97], v[106:107] op_sel_hi:[0,1]
	v_pk_fma_f32 v[102:103], v[14:15], v[106:107], v[108:109]
	v_lshlrev_b32_e32 v106, 16, v89
	v_and_b32_e32 v107, 0xffff0000, v89
	v_lshlrev_b32_e32 v108, 16, v81
	v_and_b32_e32 v109, 0xffff0000, v81
	v_pk_mul_f32 v[106:107], v[96:97], v[106:107] op_sel_hi:[0,1]
	v_pk_fma_f32 v[104:105], v[16:17], v[106:107], v[108:109]
	v_pk_mul_f32 v[110:111], v[98:99], v[98:99]
	v_pk_fma_f32 v[110:111], v[100:101], v[100:101], v[110:111]
	v_pk_fma_f32 v[110:111], v[102:103], v[102:103], v[110:111]
	v_pk_fma_f32 v[110:111], v[104:105], v[104:105], v[110:111]
	v_cvt_pk_bf16_f32 v78, v98, v99
	v_cvt_pk_bf16_f32 v79, v100, v101
	v_cvt_pk_bf16_f32 v80, v102, v103
	v_cvt_pk_bf16_f32 v81, v104, v105
	global_store_dwordx4 v19, v[78:81], s[4:5] nt
	v_lshlrev_b32_e32 v106, 16, v90
	v_and_b32_e32 v107, 0xffff0000, v90
	v_lshlrev_b32_e32 v108, 16, v82
	v_and_b32_e32 v109, 0xffff0000, v82
	v_pk_mul_f32 v[106:107], v[96:97], v[106:107] op_sel_hi:[0,1]
	v_pk_fma_f32 v[98:99], v[2:3], v[106:107], v[108:109]
	v_lshlrev_b32_e32 v106, 16, v91
	v_and_b32_e32 v107, 0xffff0000, v91
	v_lshlrev_b32_e32 v108, 16, v83
	v_and_b32_e32 v109, 0xffff0000, v83
	v_pk_mul_f32 v[106:107], v[96:97], v[106:107] op_sel_hi:[0,1]
	v_pk_fma_f32 v[100:101], v[4:5], v[106:107], v[108:109]
	v_lshlrev_b32_e32 v106, 16, v92
	v_and_b32_e32 v107, 0xffff0000, v92
	v_lshlrev_b32_e32 v108, 16, v84
	v_and_b32_e32 v109, 0xffff0000, v84
	v_pk_mul_f32 v[106:107], v[96:97], v[106:107] op_sel_hi:[0,1]
	v_pk_fma_f32 v[102:103], v[6:7], v[106:107], v[108:109]
	v_lshlrev_b32_e32 v106, 16, v93
	v_and_b32_e32 v107, 0xffff0000, v93
	v_lshlrev_b32_e32 v108, 16, v85
	v_and_b32_e32 v109, 0xffff0000, v85
	v_pk_mul_f32 v[106:107], v[96:97], v[106:107] op_sel_hi:[0,1]
	v_pk_fma_f32 v[104:105], v[8:9], v[106:107], v[108:109]
	v_pk_fma_f32 v[110:111], v[98:99], v[98:99], v[110:111]
	v_pk_fma_f32 v[110:111], v[100:101], v[100:101], v[110:111]
	v_pk_fma_f32 v[110:111], v[102:103], v[102:103], v[110:111]
	v_pk_fma_f32 v[110:111], v[104:105], v[104:105], v[110:111]
	v_cvt_pk_bf16_f32 v82, v98, v99
	v_cvt_pk_bf16_f32 v83, v100, v101
	v_cvt_pk_bf16_f32 v84, v102, v103
	v_cvt_pk_bf16_f32 v85, v104, v105
	global_store_dwordx4 v19, v[82:85], s[4:5] offset:1024 nt
	v_add_f32_e32 v112, v110, v111
	v_add_u32_e32 v22, 0x2000, v22
	s_nop 1
	v_add_f32_dpp v112, v112, v112 quad_perm:[1,0,3,2] row_mask:0xf bank_mask:0xf
	s_nop 1
	v_add_f32_dpp v112, v112, v112 quad_perm:[2,3,0,1] row_mask:0xf bank_mask:0xf
	s_nop 1
	v_add_f32_dpp v112, v112, v112 row_half_mirror row_mask:0xf bank_mask:0xf
	s_nop 1
	v_add_f32_dpp v112, v112, v112 row_mirror row_mask:0xf bank_mask:0xf
	s_nop 1
	v_add_f32_dpp v112, v112, v112 row_bcast:15 row_mask:0xa bank_mask:0xf
	s_nop 1
	v_add_f32_dpp v112, v112, v112 row_bcast:31 row_mask:0xc bank_mask:0xf
	v_fmamk_f32 v113, v112, 0x3a800000, v244
	v_rsq_f32_e32 v113, v113
	s_mov_b64 exec, s[6:7]
	global_store_dword v22, v113, s[4:5]
	s_mov_b64 exec, -1

; __device__ __forceinline__ int otid() { int t = threadIdx.x; asm volatile("" : "+v"(t)); return t; }
; #define PIN(i) karg_ptr(8 * (i))
; __device__ __forceinline__ void resid_rows(bf16_t* R, const bf16_t* Y, const float* ssqY, const float* g, float* rstd_out, float* outf, bool wf32, int row_lo, int row_hi, int yoff, int gw, int NGW, int lane) {
;     ...
;     for (int row0 = row_lo + gw; row0 < row_hi; row0 += RP * NGW) {
;         u32x4 rr[RP][2], oo[RP][2]; float ssv[RP];
; #pragma unroll
;         for (int k = 0; k < RP; ++k) { const int row = row0 + k * NGW; const bool ok = row < row_hi; const int rw = ok ? row : row0;
;             ssv[k] = ssqY[rw];
; #pragma unroll
;             for (int j = 0; j < 2; ++j) { const int c = 8 * lane + 512 * j; rr[k][j] = *(const u32x4*)(R + (size_t)rw * DM + c); oo[k][j] = *(const u32x4*)(Y + (size_t)(rw - yoff) * DM + c); } }
; __global__ void __launch_bounds__(512, 2) fwd_megakernel(Params P) {
;     ...
;             const bool lastl = (l == NLAYER - 1);
;             { const int lane = otid() & 63, gw = bx * 8 + (otid() >> 6);
;               resid_rows(XB, FH1, ssqF, PIN(I_LNFPOST) + l * DM, rstdA, out, lastl, HALF_TOK, MTOK, HALF_TOK, gw, NGW, lane); }
.LBB0_792:
	s_cmp_le_i32 s88, s30
	s_cselect_b64 s[6:7], -1, 0
	s_and_b64 s[4:5], s[6:7], s[4:5]
	s_andn2_b64 vcc, exec, s[4:5]
	v_readlane_b32 s30, v255, 39
	v_readlane_b32 s31, v255, 40
	s_cbranch_vccnz .Ltr_145
	v_readlane_b32 s8, v255, 49
	v_mov_b32_e32 v2, v0
	v_mov_b32_e32 v3, v0
	v_readlane_b32 s9, v255, 50
	v_readlane_b32 s4, v255, 4
	v_ashrrev_i32_e32 v20, 6, v3
	s_mov_b32 s9, s49
	v_add_u32_e32 v18, s4, v20
	s_mov_b64 s[4:5], s[0:1]
	s_mov_b64 s[6:7], s[0:1]
	s_mov_b64 s[10:11], s[0:1]
	s_mov_b64 s[72:73], s[8:9]
	s_lshl_b32 s48, s8, 10
	s_mov_b64 s[12:13], s[0:1]
	s_mov_b64 s[8:9], s[0:1]
	v_cmp_gt_i32_e32 vcc, s47, v18
	s_and_saveexec_b64 s[16:17], vcc
	s_cbranch_execz .LBB0_823
	v_readlane_b32 s12, v255, 49
	s_cmp_eq_u32 s12, 1
	s_cbranch_scc1 .Lrs2_last1
	v_lshrrev_b32_e32 v114, 6, v0
	v_readlane_b32 s12, v255, 49
	v_readlane_b32 s13, v255, 4
	v_readfirstlane_b32 s18, v114
	s_load_dwordx2 s[4:5], s[0:1], 0x98
	s_load_dwordx2 s[10:11], s[0:1], 0x68
	s_load_dwordx2 s[6:7], s[0:1], 0x90
	s_add_i32 s13, s13, s18
	v_and_b32_e32 v115, 63, v0
	v_lshlrev_b32_e32 v114, 4, v115
	v_lshlrev_b32_e32 v115, 5, v115
	s_lshl_b32 s18, s12, 12
	s_lshl_b32 s19, s12, 18
	s_bfm_b64 s[8:9], 1, 63
	s_waitcnt lgkmcnt(0)
	s_add_u32 s10, s10, s18
	s_addc_u32 s11, s11, 0
	global_load_dwordx4 v[2:5], v115, s[10:11] offset:2048
	global_load_dwordx4 v[6:9], v115, s[10:11] offset:2064
	global_load_dwordx4 v[10:13], v115, s[10:11]
	global_load_dwordx4 v[14:17], v115, s[10:11] offset:16
	s_lshl_b32 s18, s13, 11
	v_add_u32_e32 v18, s18, v114
	v_mov_b32_e32 v19, v18
	v_mov_b32_e32 v20, v18
	s_lshl_b32 s18, s13, 2
	v_mov_b32_e32 v22, s18
	s_add_i32 s18, s18, s19
	v_mov_b32_e32 v21, s18
	s_lshl_b32 s18, s13, 12
	v_add_u32_e32 v23, s18, v115
	v_add_u32_e32 v18, 0x5001000, v18
	v_add_u32_e32 v21, 0x2d70000, v21
	global_load_dwordx4 v[24:27], v18, s[4:5]
	global_load_dwordx4 v[32:35], v20, s[6:7]
	global_load_dwordx4 v[28:31], v18, s[4:5] offset:1024
	global_load_dwordx4 v[36:39], v20, s[6:7] offset:1024
	global_load_dword v40, v21, s[4:5]
	v_add_u32_e32 v18, 0x400000, v18
	v_add_u32_e32 v20, 0x400000, v20
	v_add_u32_e32 v21, 0x2000, v21
	global_load_dwordx4 v[42:45], v18, s[4:5]
	global_load_dwordx4 v[50:53], v20, s[6:7]
	global_load_dwordx4 v[46:49], v18, s[4:5] offset:1024
	global_load_dwordx4 v[54:57], v20, s[6:7] offset:1024
	global_load_dword v58, v21, s[4:5]
	v_add_u32_e32 v18, 0x400000, v18
	v_add_u32_e32 v20, 0x400000, v20
	v_add_u32_e32 v21, 0x2000, v21
	global_load_dwordx4 v[60:63], v18, s[4:5]
	global_load_dwordx4 v[68:71], v20, s[6:7]
	global_load_dwordx4 v[64:67], v18, s[4:5] offset:1024
	global_load_dwordx4 v[72:75], v20, s[6:7] offset:1024
	global_load_dword v76, v21, s[4:5]
	v_add_u32_e32 v18, 0x400000, v18
	v_add_u32_e32 v20, 0x400000, v20
	v_add_u32_e32 v21, 0x2000, v21
	global_load_dwordx4 v[78:81], v18, s[4:5]
	global_load_dwordx4 v[86:89], v20, s[6:7]
	global_load_dwordx4 v[82:85], v18, s[4:5] offset:1024
	global_load_dwordx4 v[90:93], v20, s[6:7] offset:1024
	global_load_dword v94, v21, s[4:5]
	s_waitcnt vmcnt(15)
	v_fmamk_f32 v96, v40, 0x3a800000, v244
	v_rsq_f32_e32 v96, v96
	v_add_u32_e32 v19, 0x5001000, v19
	v_lshlrev_b32_e32 v106, 16, v32
	v_and_b32_e32 v107, 0xffff0000, v32
	v_lshlrev_b32_e32 v108, 16, v24
	v_and_b32_e32 v109, 0xffff0000, v24
	v_pk_mul_f32 v[106:107], v[96:97], v[106:107] op_sel_hi:[0,1]
	v_pk_fma_f32 v[98:99], v[10:11], v[106:107], v[108:109]
	v_lshlrev_b32_e32 v106, 16, v33
	v_and_b32_e32 v107, 0xffff0000, v33
	v_lshlrev_b32_e32 v108, 16, v25
	v_and_b32_e32 v109, 0xffff0000, v25
	v_pk_mul_f32 v[106:107], v[96:97], v[106:107] op_sel_hi:[0,1]
	v_pk_fma_f32 v[100:101], v[12:13], v[106:107], v[108:109]
	v_lshlrev_b32_e32 v106, 16, v34
	v_and_b32_e32 v107, 0xffff0000, v34
	v_lshlrev_b32_e32 v108, 16, v26
	v_and_b32_e32 v109, 0xffff0000, v26
	v_pk_mul_f32 v[106:107], v[96:97], v[106:107] op_sel_hi:[0,1]
	v_pk_fma_f32 v[102:103], v[14:15], v[106:107], v[108:109]
	v_lshlrev_b32_e32 v106, 16, v35
	v_and_b32_e32 v107, 0xffff0000, v35
	v_lshlrev_b32_e32 v108, 16, v27
	v_and_b32_e32 v109, 0xffff0000, v27
	v_pk_mul_f32 v[106:107], v[96:97], v[106:107] op_sel_hi:[0,1]
	v_pk_fma_f32 v[104:105], v[16:17], v[106:107], v[108:109]
	v_pk_mul_f32 v[110:111], v[98:99], v[98:99]
	v_pk_fma_f32 v[110:111], v[100:101], v[100:101], v[110:111]
	v_pk_fma_f32 v[110:111], v[102:103], v[102:103], v[110:111]
	v_pk_fma_f32 v[110:111], v[104:105], v[104:105], v[110:111]
	v_cvt_pk_bf16_f32 v24, v98, v99
	v_cvt_pk_bf16_f32 v25, v100, v101
	v_cvt_pk_bf16_f32 v26, v102, v103
	v_cvt_pk_bf16_f32 v27, v104, v105
	global_store_dwordx4 v19, v[24:27], s[4:5] nt
	v_lshlrev_b32_e32 v106, 16, v36
	v_and_b32_e32 v107, 0xffff0000, v36
	v_lshlrev_b32_e32 v108, 16, v28
	v_and_b32_e32 v109, 0xffff0000, v28
	v_pk_mul_f32 v[106:107], v[96:97], v[106:107] op_sel_hi:[0,1]
	v_pk_fma_f32 v[98:99], v[2:3], v[106:107], v[108:109]
	v_lshlrev_b32_e32 v106, 16, v37
	v_and_b32_e32 v107, 0xffff0000, v37
	v_lshlrev_b32_e32 v108, 16, v29
	v_and_b32_e32 v109, 0xffff0000, v29
	v_pk_mul_f32 v[106:107], v[96:97], v[106:107] op_sel_hi:[0,1]
	v_pk_fma_f32 v[100:101], v[4:5], v[106:107], v[108:109]
	v_lshlrev_b32_e32 v106, 16, v38
	v_and_b32_e32 v107, 0xffff0000, v38
	v_lshlrev_b32_e32 v108, 16, v30
	v_and_b32_e32 v109, 0xffff0000, v30
	v_pk_mul_f32 v[106:107], v[96:97], v[106:107] op_sel_hi:[0,1]
	v_pk_fma_f32 v[102:103], v[6:7], v[106:107], v[108:109]
	v_lshlrev_b32_e32 v106, 16, v39
	v_and_b32_e32 v107, 0xffff0000, v39
	v_lshlrev_b32_e32 v108, 16, v31
	v_and_b32_e32 v109, 0xffff0000, v31
	v_pk_mul_f32 v[106:107], v[96:97], v[106:107] op_sel_hi:[0,1]
	v_pk_fma_f32 v[104:105], v[8:9], v[106:107], v[108:109]
; __device__ __forceinline__ float bflo(unsigned w) { return __uint_as_float(w << 16); }
; __device__ __forceinline__ float bfhi(unsigned w) { return __uint_as_float(w & 0xffff0000u); }
; __device__ __forceinline__ void resid_rows(bf16_t* R, const bf16_t* Y, const float* ssqY, const float* g, float* rstd_out, float* outf, bool wf32, int row_lo, int row_hi, int yoff, int gw, int NGW, int lane) {
;     ...
;     for (int row0 = row_lo + gw; row0 < row_hi; row0 += RP * NGW) {
;         u32x4 rr[RP][2], oo[RP][2]; float ssv[RP];
; #pragma unroll
;         for (int k = 0; k < RP; ++k) { const int row = row0 + k * NGW; const bool ok = row < row_hi; const int rw = ok ? row : row0;
;             ssv[k] = ssqY[rw];
; #pragma unroll
;             for (int j = 0; j < 2; ++j) { const int c = 8 * lane + 512 * j; rr[k][j] = *(const u32x4*)(R + (size_t)rw * DM + c); oo[k][j] = *(const u32x4*)(Y + (size_t)(rw - yoff) * DM + c); } }
; #pragma unroll
;         for (int k = 0; k < RP; ++k) { const int row = row0 + k * NGW; if (row < row_hi) {
;             const float rs = __builtin_amdgcn_rsqf(ssv[k] * (1.0f / DM) + RMS_EPS); float s = 0.f;
; #pragma unroll
;             for (int j = 0; j < 2; ++j) { const int c = 8 * lane + 512 * j; const u32x4 r = rr[k][j], o = oo[k][j]; const f32x4 ga = gv[j][0], gb = gv[j][1];
;                 f32x4 ya, yb; ya[0] = bflo(r.x) + bflo(o.x) * rs * ga[0]; ya[1] = bfhi(r.x) + bfhi(o.x) * rs * ga[1]; ya[2] = bflo(r.y) + bflo(o.y) * rs * ga[2]; ya[3] = bfhi(r.y) + bfhi(o.y) * rs * ga[3];
;                 yb[0] = bflo(r.z) + bflo(o.z) * rs * gb[0]; yb[1] = bfhi(r.z) + bfhi(o.z) * rs * gb[1]; yb[2] = bflo(r.w) + bflo(o.w) * rs * gb[2]; yb[3] = bfhi(r.w) + bfhi(o.w) * rs * gb[3];
;                 if (wf32) { *(f32x4*)(outf + (size_t)row * DM + c) = ya; *(f32x4*)(outf + (size_t)row * DM + c + 4) = yb; }
;                 s += (ya[0] * ya[0] + ya[1] * ya[1]) + (ya[2] * ya[2] + ya[3] * ya[3]) + (yb[0] * yb[0] + yb[1] * yb[1]) + (yb[2] * yb[2] + yb[3] * yb[3]);
;                 u32x4 w; w.x = pk2(ya[0], ya[1]); w.y = pk2(ya[2], ya[3]); w.z = pk2(yb[0], yb[1]); w.w = pk2(yb[2], yb[3]); *(u32x4*)(R + (size_t)row * DM + c) = w; }
;             s = wave_sum(s); if (lane == 0) rstd_out[row] = __builtin_amdgcn_rsqf(s * (1.0f / DM) + RMS_EPS); } }
	v_pk_fma_f32 v[110:111], v[98:99], v[98:99], v[110:111]
	v_pk_fma_f32 v[110:111], v[100:101], v[100:101], v[110:111]
	v_pk_fma_f32 v[110:111], v[102:103], v[102:103], v[110:111]
	v_pk_fma_f32 v[110:111], v[104:105], v[104:105], v[110:111]
	v_cvt_pk_bf16_f32 v28, v98, v99
	v_cvt_pk_bf16_f32 v29, v100, v101
	v_cvt_pk_bf16_f32 v30, v102, v103
	v_cvt_pk_bf16_f32 v31, v104, v105
	global_store_dwordx4 v19, v[28:31], s[4:5] offset:1024 nt
	v_add_f32_e32 v112, v110, v111
	v_add_u32_e32 v22, 0x2d10000, v22
	s_nop 1
	v_add_f32_dpp v112, v112, v112 quad_perm:[1,0,3,2] row_mask:0xf bank_mask:0xf
	s_nop 1
	v_add_f32_dpp v112, v112, v112 quad_perm:[2,3,0,1] row_mask:0xf bank_mask:0xf
	s_nop 1
	v_add_f32_dpp v112, v112, v112 row_half_mirror row_mask:0xf bank_mask:0xf
	s_nop 1
	v_add_f32_dpp v112, v112, v112 row_mirror row_mask:0xf bank_mask:0xf
	s_nop 1
	v_add_f32_dpp v112, v112, v112 row_bcast:15 row_mask:0xa bank_mask:0xf
	s_nop 1
	v_add_f32_dpp v112, v112, v112 row_bcast:31 row_mask:0xc bank_mask:0xf
	v_fmamk_f32 v113, v112, 0x3a800000, v244
	v_rsq_f32_e32 v113, v113
	s_mov_b64 exec, s[8:9]
	global_store_dword v22, v113, s[4:5]
	s_mov_b64 exec, -1
	v_add_u32_e32 v18, 0x400000, v18
	v_add_u32_e32 v20, 0x400000, v20
	v_add_u32_e32 v21, 0x2000, v21
	global_load_dwordx4 v[24:27], v18, s[4:5]
	global_load_dwordx4 v[32:35], v20, s[6:7]
	global_load_dwordx4 v[28:31], v18, s[4:5] offset:1024
	global_load_dwordx4 v[36:39], v20, s[6:7] offset:1024
	global_load_dword v40, v21, s[4:5]
	s_waitcnt vmcnt(18)
	v_fmamk_f32 v96, v58, 0x3a800000, v244
	v_rsq_f32_e32 v96, v96
	v_add_u32_e32 v19, 0x400000, v19
	v_lshlrev_b32_e32 v106, 16, v50
	v_and_b32_e32 v107, 0xffff0000, v50
	v_lshlrev_b32_e32 v108, 16, v42
	v_and_b32_e32 v109, 0xffff0000, v42
	v_pk_mul_f32 v[106:107], v[96:97], v[106:107] op_sel_hi:[0,1]
	v_pk_fma_f32 v[98:99], v[10:11], v[106:107], v[108:109]
	v_lshlrev_b32_e32 v106, 16, v51
	v_and_b32_e32 v107, 0xffff0000, v51
	v_lshlrev_b32_e32 v108, 16, v43
	v_and_b32_e32 v109, 0xffff0000, v43
	v_pk_mul_f32 v[106:107], v[96:97], v[106:107] op_sel_hi:[0,1]
	v_pk_fma_f32 v[100:101], v[12:13], v[106:107], v[108:109]
	v_lshlrev_b32_e32 v106, 16, v52
	v_and_b32_e32 v107, 0xffff0000, v52
	v_lshlrev_b32_e32 v108, 16, v44
	v_and_b32_e32 v109, 0xffff0000, v44
	v_pk_mul_f32 v[106:107], v[96:97], v[106:107] op_sel_hi:[0,1]
	v_pk_fma_f32 v[102:103], v[14:15], v[106:107], v[108:109]
	v_lshlrev_b32_e32 v106, 16, v53
	v_and_b32_e32 v107, 0xffff0000, v53
	v_lshlrev_b32_e32 v108, 16, v45
	v_and_b32_e32 v109, 0xffff0000, v45
	v_pk_mul_f32 v[106:107], v[96:97], v[106:107] op_sel_hi:[0,1]
	v_pk_fma_f32 v[104:105], v[16:17], v[106:107], v[108:109]
	v_pk_mul_f32 v[110:111], v[98:99], v[98:99]
	v_pk_fma_f32 v[110:111], v[100:101], v[100:101], v[110:111]
	v_pk_fma_f32 v[110:111], v[102:103], v[102:103], v[110:111]
	v_pk_fma_f32 v[110:111], v[104:105], v[104:105], v[110:111]
	v_cvt_pk_bf16_f32 v42, v98, v99
	v_cvt_pk_bf16_f32 v43, v100, v101
	v_cvt_pk_bf16_f32 v44, v102, v103
	v_cvt_pk_bf16_f32 v45, v104, v105
	global_store_dwordx4 v19, v[42:45], s[4:5] nt
	v_lshlrev_b32_e32 v106, 16, v54
	v_and_b32_e32 v107, 0xffff0000, v54
	v_lshlrev_b32_e32 v108, 16, v46
	v_and_b32_e32 v109, 0xffff0000, v46
	v_pk_mul_f32 v[106:107], v[96:97], v[106:107] op_sel_hi:[0,1]
	v_pk_fma_f32 v[98:99], v[2:3], v[106:107], v[108:109]
	v_lshlrev_b32_e32 v106, 16, v55
	v_and_b32_e32 v107, 0xffff0000, v55
	v_lshlrev_b32_e32 v108, 16, v47
	v_and_b32_e32 v109, 0xffff0000, v47
	v_pk_mul_f32 v[106:107], v[96:97], v[106:107] op_sel_hi:[0,1]
	v_pk_fma_f32 v[100:101], v[4:5], v[106:107], v[108:109]
	v_lshlrev_b32_e32 v106, 16, v56
	v_and_b32_e32 v107, 0xffff0000, v56
	v_lshlrev_b32_e32 v108, 16, v48
	v_and_b32_e32 v109, 0xffff0000, v48
	v_pk_mul_f32 v[106:107], v[96:97], v[106:107] op_sel_hi:[0,1]
	v_pk_fma_f32 v[102:103], v[6:7], v[106:107], v[108:109]
	v_lshlrev_b32_e32 v106, 16, v57
	v_and_b32_e32 v107, 0xffff0000, v57
	v_lshlrev_b32_e32 v108, 16, v49
	v_and_b32_e32 v109, 0xffff0000, v49
	v_pk_mul_f32 v[106:107], v[96:97], v[106:107] op_sel_hi:[0,1]
	v_pk_fma_f32 v[104:105], v[8:9], v[106:107], v[108:109]
	v_pk_fma_f32 v[110:111], v[98:99], v[98:99], v[110:111]
	v_pk_fma_f32 v[110:111], v[100:101], v[100:101], v[110:111]
	v_pk_fma_f32 v[110:111], v[102:103], v[102:103], v[110:111]
	v_pk_fma_f32 v[110:111], v[104:105], v[104:105], v[110:111]
	v_cvt_pk_bf16_f32 v46, v98, v99
	v_cvt_pk_bf16_f32 v47, v100, v101
	v_cvt_pk_bf16_f32 v48, v102, v103
	v_cvt_pk_bf16_f32 v49, v104, v105
	global_store_dwordx4 v19, v[46:49], s[4:5] offset:1024 nt
	v_add_f32_e32 v112, v110, v111
	v_add_u32_e32 v22, 0x2000, v22
	s_nop 1
	v_add_f32_dpp v112, v112, v112 quad_perm:[1,0,3,2] row_mask:0xf bank_mask:0xf
	s_nop 1
	v_add_f32_dpp v112, v112, v112 quad_perm:[2,3,0,1] row_mask:0xf bank_mask:0xf
	s_nop 1
	v_add_f32_dpp v112, v112, v112 row_half_mirror row_mask:0xf bank_mask:0xf
	s_nop 1
	v_add_f32_dpp v112, v112, v112 row_mirror row_mask:0xf bank_mask:0xf
	s_nop 1
	v_add_f32_dpp v112, v112, v112 row_bcast:15 row_mask:0xa bank_mask:0xf
	s_nop 1
	v_add_f32_dpp v112, v112, v112 row_bcast:31 row_mask:0xc bank_mask:0xf
	v_fmamk_f32 v113, v112, 0x3a800000, v244
	v_rsq_f32_e32 v113, v113
	s_mov_b64 exec, s[8:9]
	global_store_dword v22, v113, s[4:5]
	s_mov_b64 exec, -1
	v_add_u32_e32 v18, 0x400000, v18
	v_add_u32_e32 v20, 0x400000, v20
	v_add_u32_e32 v21, 0x2000, v21
	global_load_dwordx4 v[42:45], v18, s[4:5]
	global_load_dwordx4 v[50:53], v20, s[6:7]
	global_load_dwordx4 v[46:49], v18, s[4:5] offset:1024
	global_load_dwordx4 v[54:57], v20, s[6:7] offset:1024
	global_load_dword v58, v21, s[4:5]
	s_waitcnt vmcnt(21)
; __device__ __forceinline__ float bflo(unsigned w) { return __uint_as_float(w << 16); }
; __device__ __forceinline__ float bfhi(unsigned w) { return __uint_as_float(w & 0xffff0000u); }
; __device__ __forceinline__ void resid_rows(bf16_t* R, const bf16_t* Y, const float* ssqY, const float* g, float* rstd_out, float* outf, bool wf32, int row_lo, int row_hi, int yoff, int gw, int NGW, int lane) {
;     ...
;     for (int row0 = row_lo + gw; row0 < row_hi; row0 += RP * NGW) {
;         u32x4 rr[RP][2], oo[RP][2]; float ssv[RP];
; #pragma unroll
;         for (int k = 0; k < RP; ++k) { const int row = row0 + k * NGW; const bool ok = row < row_hi; const int rw = ok ? row : row0;
;             ssv[k] = ssqY[rw];
; #pragma unroll
;             for (int j = 0; j < 2; ++j) { const int c = 8 * lane + 512 * j; rr[k][j] = *(const u32x4*)(R + (size_t)rw * DM + c); oo[k][j] = *(const u32x4*)(Y + (size_t)(rw - yoff) * DM + c); } }
; #pragma unroll
;         for (int k = 0; k < RP; ++k) { const int row = row0 + k * NGW; if (row < row_hi) {
;             const float rs = __builtin_amdgcn_rsqf(ssv[k] * (1.0f / DM) + RMS_EPS); float s = 0.f;
; #pragma unroll
;             for (int j = 0; j < 2; ++j) { const int c = 8 * lane + 512 * j; const u32x4 r = rr[k][j], o = oo[k][j]; const f32x4 ga = gv[j][0], gb = gv[j][1];
;                 f32x4 ya, yb; ya[0] = bflo(r.x) + bflo(o.x) * rs * ga[0]; ya[1] = bfhi(r.x) + bfhi(o.x) * rs * ga[1]; ya[2] = bflo(r.y) + bflo(o.y) * rs * ga[2]; ya[3] = bfhi(r.y) + bfhi(o.y) * rs * ga[3];
;                 yb[0] = bflo(r.z) + bflo(o.z) * rs * gb[0]; yb[1] = bfhi(r.z) + bfhi(o.z) * rs * gb[1]; yb[2] = bflo(r.w) + bflo(o.w) * rs * gb[2]; yb[3] = bfhi(r.w) + bfhi(o.w) * rs * gb[3];
;                 if (wf32) { *(f32x4*)(outf + (size_t)row * DM + c) = ya; *(f32x4*)(outf + (size_t)row * DM + c + 4) = yb; }
;                 s += (ya[0] * ya[0] + ya[1] * ya[1]) + (ya[2] * ya[2] + ya[3] * ya[3]) + (yb[0] * yb[0] + yb[1] * yb[1]) + (yb[2] * yb[2] + yb[3] * yb[3]);
;                 u32x4 w; w.x = pk2(ya[0], ya[1]); w.y = pk2(ya[2], ya[3]); w.z = pk2(yb[0], yb[1]); w.w = pk2(yb[2], yb[3]); *(u32x4*)(R + (size_t)row * DM + c) = w; }
;             s = wave_sum(s); if (lane == 0) rstd_out[row] = __builtin_amdgcn_rsqf(s * (1.0f / DM) + RMS_EPS); } }
	v_fmamk_f32 v96, v76, 0x3a800000, v244
	v_rsq_f32_e32 v96, v96
	v_add_u32_e32 v19, 0x400000, v19
	v_lshlrev_b32_e32 v106, 16, v68
	v_and_b32_e32 v107, 0xffff0000, v68
	v_lshlrev_b32_e32 v108, 16, v60
	v_and_b32_e32 v109, 0xffff0000, v60
	v_pk_mul_f32 v[106:107], v[96:97], v[106:107] op_sel_hi:[0,1]
	v_pk_fma_f32 v[98:99], v[10:11], v[106:107], v[108:109]
	v_lshlrev_b32_e32 v106, 16, v69
	v_and_b32_e32 v107, 0xffff0000, v69
	v_lshlrev_b32_e32 v108, 16, v61
	v_and_b32_e32 v109, 0xffff0000, v61
	v_pk_mul_f32 v[106:107], v[96:97], v[106:107] op_sel_hi:[0,1]
	v_pk_fma_f32 v[100:101], v[12:13], v[106:107], v[108:109]
	v_lshlrev_b32_e32 v106, 16, v70
	v_and_b32_e32 v107, 0xffff0000, v70
	v_lshlrev_b32_e32 v108, 16, v62
	v_and_b32_e32 v109, 0xffff0000, v62
	v_pk_mul_f32 v[106:107], v[96:97], v[106:107] op_sel_hi:[0,1]
	v_pk_fma_f32 v[102:103], v[14:15], v[106:107], v[108:109]
	v_lshlrev_b32_e32 v106, 16, v71
	v_and_b32_e32 v107, 0xffff0000, v71
	v_lshlrev_b32_e32 v108, 16, v63
	v_and_b32_e32 v109, 0xffff0000, v63
	v_pk_mul_f32 v[106:107], v[96:97], v[106:107] op_sel_hi:[0,1]
	v_pk_fma_f32 v[104:105], v[16:17], v[106:107], v[108:109]
	v_pk_mul_f32 v[110:111], v[98:99], v[98:99]
	v_pk_fma_f32 v[110:111], v[100:101], v[100:101], v[110:111]
	v_pk_fma_f32 v[110:111], v[102:103], v[102:103], v[110:111]
	v_pk_fma_f32 v[110:111], v[104:105], v[104:105], v[110:111]
	v_cvt_pk_bf16_f32 v60, v98, v99
	v_cvt_pk_bf16_f32 v61, v100, v101
	v_cvt_pk_bf16_f32 v62, v102, v103
	v_cvt_pk_bf16_f32 v63, v104, v105
	global_store_dwordx4 v19, v[60:63], s[4:5] nt
	v_lshlrev_b32_e32 v106, 16, v72
	v_and_b32_e32 v107, 0xffff0000, v72
	v_lshlrev_b32_e32 v108, 16, v64
	v_and_b32_e32 v109, 0xffff0000, v64
	v_pk_mul_f32 v[106:107], v[96:97], v[106:107] op_sel_hi:[0,1]
	v_pk_fma_f32 v[98:99], v[2:3], v[106:107], v[108:109]
	v_lshlrev_b32_e32 v106, 16, v73
	v_and_b32_e32 v107, 0xffff0000, v73
	v_lshlrev_b32_e32 v108, 16, v65
	v_and_b32_e32 v109, 0xffff0000, v65
	v_pk_mul_f32 v[106:107], v[96:97], v[106:107] op_sel_hi:[0,1]
	v_pk_fma_f32 v[100:101], v[4:5], v[106:107], v[108:109]
	v_lshlrev_b32_e32 v106, 16, v74
	v_and_b32_e32 v107, 0xffff0000, v74
	v_lshlrev_b32_e32 v108, 16, v66
	v_and_b32_e32 v109, 0xffff0000, v66
	v_pk_mul_f32 v[106:107], v[96:97], v[106:107] op_sel_hi:[0,1]
	v_pk_fma_f32 v[102:103], v[6:7], v[106:107], v[108:109]
	v_lshlrev_b32_e32 v106, 16, v75
	v_and_b32_e32 v107, 0xffff0000, v75
	v_lshlrev_b32_e32 v108, 16, v67
	v_and_b32_e32 v109, 0xffff0000, v67
	v_pk_mul_f32 v[106:107], v[96:97], v[106:107] op_sel_hi:[0,1]
	v_pk_fma_f32 v[104:105], v[8:9], v[106:107], v[108:109]
	v_pk_fma_f32 v[110:111], v[98:99], v[98:99], v[110:111]
	v_pk_fma_f32 v[110:111], v[100:101], v[100:101], v[110:111]
	v_pk_fma_f32 v[110:111], v[102:103], v[102:103], v[110:111]
	v_pk_fma_f32 v[110:111], v[104:105], v[104:105], v[110:111]
	v_cvt_pk_bf16_f32 v64, v98, v99
	v_cvt_pk_bf16_f32 v65, v100, v101
	v_cvt_pk_bf16_f32 v66, v102, v103
	v_cvt_pk_bf16_f32 v67, v104, v105
	global_store_dwordx4 v19, v[64:67], s[4:5] offset:1024 nt
	v_add_f32_e32 v112, v110, v111
	v_add_u32_e32 v22, 0x2000, v22
	s_nop 1
	v_add_f32_dpp v112, v112, v112 quad_perm:[1,0,3,2] row_mask:0xf bank_mask:0xf
	s_nop 1
	v_add_f32_dpp v112, v112, v112 quad_perm:[2,3,0,1] row_mask:0xf bank_mask:0xf
	s_nop 1
	v_add_f32_dpp v112, v112, v112 row_half_mirror row_mask:0xf bank_mask:0xf
	s_nop 1
	v_add_f32_dpp v112, v112, v112 row_mirror row_mask:0xf bank_mask:0xf
	s_nop 1
	v_add_f32_dpp v112, v112, v112 row_bcast:15 row_mask:0xa bank_mask:0xf
	s_nop 1
	v_add_f32_dpp v112, v112, v112 row_bcast:31 row_mask:0xc bank_mask:0xf
	v_fmamk_f32 v113, v112, 0x3a800000, v244
	v_rsq_f32_e32 v113, v113
	s_mov_b64 exec, s[8:9]
	global_store_dword v22, v113, s[4:5]
	s_mov_b64 exec, -1
	v_add_u32_e32 v18, 0x400000, v18
	v_add_u32_e32 v20, 0x400000, v20
	v_add_u32_e32 v21, 0x2000, v21
	global_load_dwordx4 v[60:63], v18, s[4:5]
	global_load_dwordx4 v[68:71], v20, s[6:7]
	global_load_dwordx4 v[64:67], v18, s[4:5] offset:1024
	global_load_dwordx4 v[72:75], v20, s[6:7] offset:1024
	global_load_dword v76, v21, s[4:5]
	s_waitcnt vmcnt(24)
	v_fmamk_f32 v96, v94, 0x3a800000, v244
	v_rsq_f32_e32 v96, v96
	v_add_u32_e32 v19, 0x400000, v19
	v_lshlrev_b32_e32 v106, 16, v86
	v_and_b32_e32 v107, 0xffff0000, v86
	v_lshlrev_b32_e32 v108, 16, v78
	v_and_b32_e32 v109, 0xffff0000, v78
	v_pk_mul_f32 v[106:107], v[96:97], v[106:107] op_sel_hi:[0,1]
	v_pk_fma_f32 v[98:99], v[10:11], v[106:107], v[108:109]
	v_lshlrev_b32_e32 v106, 16, v87
	v_and_b32_e32 v107, 0xffff0000, v87
	v_lshlrev_b32_e32 v108, 16, v79
	v_and_b32_e32 v109, 0xffff0000, v79
	v_pk_mul_f32 v[106:107], v[96:97], v[106:107] op_sel_hi:[0,1]
	v_pk_fma_f32 v[100:101], v[12:13], v[106:107], v[108:109]
	v_lshlrev_b32_e32 v106, 16, v88
	v_and_b32_e32 v107, 0xffff0000, v88
	v_lshlrev_b32_e32 v108, 16, v80
	v_and_b32_e32 v109, 0xffff0000, v80
	v_pk_mul_f32 v[106:107], v[96:97], v[106:107] op_sel_hi:[0,1]
	v_pk_fma_f32 v[102:103], v[14:15], v[106:107], v[108:109]
	v_lshlrev_b32_e32 v106, 16, v89
	v_and_b32_e32 v107, 0xffff0000, v89
	v_lshlrev_b32_e32 v108, 16, v81
	v_and_b32_e32 v109, 0xffff0000, v81
	v_pk_mul_f32 v[106:107], v[96:97], v[106:107] op_sel_hi:[0,1]
	v_pk_fma_f32 v[104:105], v[16:17], v[106:107], v[108:109]
	v_pk_mul_f32 v[110:111], v[98:99], v[98:99]
	v_pk_fma_f32 v[110:111], v[100:101], v[100:101], v[110:111]
	v_pk_fma_f32 v[110:111], v[102:103], v[102:103], v[110:111]
	v_pk_fma_f32 v[110:111], v[104:105], v[104:105], v[110:111]
	v_cvt_pk_bf16_f32 v78, v98, v99
	v_cvt_pk_bf16_f32 v79, v100, v101
	v_cvt_pk_bf16_f32 v80, v102, v103
	v_cvt_pk_bf16_f32 v81, v104, v105
	global_store_dwordx4 v19, v[78:81], s[4:5] nt
; __device__ __forceinline__ float bflo(unsigned w) { return __uint_as_float(w << 16); }
; __device__ __forceinline__ void resid_rows(bf16_t* R, const bf16_t* Y, const float* ssqY, const float* g, float* rstd_out, float* outf, bool wf32, int row_lo, int row_hi, int yoff, int gw, int NGW, int lane) {
;     ...
;     for (int row0 = row_lo + gw; row0 < row_hi; row0 += RP * NGW) {
;         u32x4 rr[RP][2], oo[RP][2]; float ssv[RP];
; #pragma unroll
;         for (int k = 0; k < RP; ++k) { const int row = row0 + k * NGW; const bool ok = row < row_hi; const int rw = ok ? row : row0;
;             ssv[k] = ssqY[rw];
; #pragma unroll
;             for (int j = 0; j < 2; ++j) { const int c = 8 * lane + 512 * j; rr[k][j] = *(const u32x4*)(R + (size_t)rw * DM + c); oo[k][j] = *(const u32x4*)(Y + (size_t)(rw - yoff) * DM + c); } }
; #pragma unroll
;         for (int k = 0; k < RP; ++k) { const int row = row0 + k * NGW; if (row < row_hi) {
;             const float rs = __builtin_amdgcn_rsqf(ssv[k] * (1.0f / DM) + RMS_EPS); float s = 0.f;
; #pragma unroll
;             for (int j = 0; j < 2; ++j) { const int c = 8 * lane + 512 * j; const u32x4 r = rr[k][j], o = oo[k][j]; const f32x4 ga = gv[j][0], gb = gv[j][1];
;                 f32x4 ya, yb; ya[0] = bflo(r.x) + bflo(o.x) * rs * ga[0]; ya[1] = bfhi(r.x) + bfhi(o.x) * rs * ga[1]; ya[2] = bflo(r.y) + bflo(o.y) * rs * ga[2]; ya[3] = bfhi(r.y) + bfhi(o.y) * rs * ga[3];
;                 yb[0] = bflo(r.z) + bflo(o.z) * rs * gb[0]; yb[1] = bfhi(r.z) + bfhi(o.z) * rs * gb[1]; yb[2] = bflo(r.w) + bflo(o.w) * rs * gb[2]; yb[3] = bfhi(r.w) + bfhi(o.w) * rs * gb[3];
;                 if (wf32) { *(f32x4*)(outf + (size_t)row * DM + c) = ya; *(f32x4*)(outf + (size_t)row * DM + c + 4) = yb; }
;                 s += (ya[0] * ya[0] + ya[1] * ya[1]) + (ya[2] * ya[2] + ya[3] * ya[3]) + (yb[0] * yb[0] + yb[1] * yb[1]) + (yb[2] * yb[2] + yb[3] * yb[3]);
;                 u32x4 w; w.x = pk2(ya[0], ya[1]); w.y = pk2(ya[2], ya[3]); w.z = pk2(yb[0], yb[1]); w.w = pk2(yb[2], yb[3]); *(u32x4*)(R + (size_t)row * DM + c) = w; }
;             s = wave_sum(s); if (lane == 0) rstd_out[row] = __builtin_amdgcn_rsqf(s * (1.0f / DM) + RMS_EPS); } }
; __global__ void __launch_bounds__(512, 2) fwd_megakernel(Params P) {
;     ...
;               resid_rows(XB, FH1, ssqF, PIN(I_LNFPOST) + l * DM, rstdA, out, lastl, HALF_TOK, MTOK, HALF_TOK, gw, NGW, lane); }
	v_lshlrev_b32_e32 v106, 16, v90
	v_and_b32_e32 v107, 0xffff0000, v90
	v_lshlrev_b32_e32 v108, 16, v82
	v_and_b32_e32 v109, 0xffff0000, v82
	v_pk_mul_f32 v[106:107], v[96:97], v[106:107] op_sel_hi:[0,1]
	v_pk_fma_f32 v[98:99], v[2:3], v[106:107], v[108:109]
	v_lshlrev_b32_e32 v106, 16, v91
	v_and_b32_e32 v107, 0xffff0000, v91
	v_lshlrev_b32_e32 v108, 16, v83
	v_and_b32_e32 v109, 0xffff0000, v83
	v_pk_mul_f32 v[106:107], v[96:97], v[106:107] op_sel_hi:[0,1]
	v_pk_fma_f32 v[100:101], v[4:5], v[106:107], v[108:109]
	v_lshlrev_b32_e32 v106, 16, v92
	v_and_b32_e32 v107, 0xffff0000, v92
	v_lshlrev_b32_e32 v108, 16, v84
	v_and_b32_e32 v109, 0xffff0000, v84
	v_pk_mul_f32 v[106:107], v[96:97], v[106:107] op_sel_hi:[0,1]
	v_pk_fma_f32 v[102:103], v[6:7], v[106:107], v[108:109]
	v_lshlrev_b32_e32 v106, 16, v93
	v_and_b32_e32 v107, 0xffff0000, v93
	v_lshlrev_b32_e32 v108, 16, v85
	v_and_b32_e32 v109, 0xffff0000, v85
	v_pk_mul_f32 v[106:107], v[96:97], v[106:107] op_sel_hi:[0,1]
	v_pk_fma_f32 v[104:105], v[8:9], v[106:107], v[108:109]
	v_pk_fma_f32 v[110:111], v[98:99], v[98:99], v[110:111]
	v_pk_fma_f32 v[110:111], v[100:101], v[100:101], v[110:111]
	v_pk_fma_f32 v[110:111], v[102:103], v[102:103], v[110:111]
	v_pk_fma_f32 v[110:111], v[104:105], v[104:105], v[110:111]
	v_cvt_pk_bf16_f32 v82, v98, v99
	v_cvt_pk_bf16_f32 v83, v100, v101
	v_cvt_pk_bf16_f32 v84, v102, v103
	v_cvt_pk_bf16_f32 v85, v104, v105
	global_store_dwordx4 v19, v[82:85], s[4:5] offset:1024 nt
	v_add_f32_e32 v112, v110, v111
	v_add_u32_e32 v22, 0x2000, v22
	s_nop 1
	v_add_f32_dpp v112, v112, v112 quad_perm:[1,0,3,2] row_mask:0xf bank_mask:0xf
	s_nop 1
	v_add_f32_dpp v112, v112, v112 quad_perm:[2,3,0,1] row_mask:0xf bank_mask:0xf
	s_nop 1
	v_add_f32_dpp v112, v112, v112 row_half_mirror row_mask:0xf bank_mask:0xf
	s_nop 1
	v_add_f32_dpp v112, v112, v112 row_mirror row_mask:0xf bank_mask:0xf
	s_nop 1
	v_add_f32_dpp v112, v112, v112 row_bcast:15 row_mask:0xa bank_mask:0xf
	s_nop 1
	v_add_f32_dpp v112, v112, v112 row_bcast:31 row_mask:0xc bank_mask:0xf
	v_fmamk_f32 v113, v112, 0x3a800000, v244
	v_rsq_f32_e32 v113, v113
	s_mov_b64 exec, s[8:9]
	global_store_dword v22, v113, s[4:5]
	s_mov_b64 exec, -1
	v_add_u32_e32 v18, 0x400000, v18
	v_add_u32_e32 v20, 0x400000, v20
	v_add_u32_e32 v21, 0x2000, v21
	global_load_dwordx4 v[78:81], v18, s[4:5]
	global_load_dwordx4 v[86:89], v20, s[6:7]
	global_load_dwordx4 v[82:85], v18, s[4:5] offset:1024
	global_load_dwordx4 v[90:93], v20, s[6:7] offset:1024
	global_load_dword v94, v21, s[4:5]
	s_waitcnt vmcnt(24)
	v_fmamk_f32 v96, v40, 0x3a800000, v244
	v_rsq_f32_e32 v96, v96
	v_add_u32_e32 v19, 0x400000, v19
	v_lshlrev_b32_e32 v106, 16, v32
	v_and_b32_e32 v107, 0xffff0000, v32
	v_lshlrev_b32_e32 v108, 16, v24
	v_and_b32_e32 v109, 0xffff0000, v24
	v_pk_mul_f32 v[106:107], v[96:97], v[106:107] op_sel_hi:[0,1]
	v_pk_fma_f32 v[98:99], v[10:11], v[106:107], v[108:109]
	v_lshlrev_b32_e32 v106, 16, v33
	v_and_b32_e32 v107, 0xffff0000, v33
	v_lshlrev_b32_e32 v108, 16, v25
	v_and_b32_e32 v109, 0xffff0000, v25
	v_pk_mul_f32 v[106:107], v[96:97], v[106:107] op_sel_hi:[0,1]
	v_pk_fma_f32 v[100:101], v[12:13], v[106:107], v[108:109]
	v_lshlrev_b32_e32 v106, 16, v34
	v_and_b32_e32 v107, 0xffff0000, v34
	v_lshlrev_b32_e32 v108, 16, v26
	v_and_b32_e32 v109, 0xffff0000, v26
	v_pk_mul_f32 v[106:107], v[96:97], v[106:107] op_sel_hi:[0,1]
	v_pk_fma_f32 v[102:103], v[14:15], v[106:107], v[108:109]
	v_lshlrev_b32_e32 v106, 16, v35
	v_and_b32_e32 v107, 0xffff0000, v35
	v_lshlrev_b32_e32 v108, 16, v27
	v_and_b32_e32 v109, 0xffff0000, v27
	v_pk_mul_f32 v[106:107], v[96:97], v[106:107] op_sel_hi:[0,1]
	v_pk_fma_f32 v[104:105], v[16:17], v[106:107], v[108:109]
	v_pk_mul_f32 v[110:111], v[98:99], v[98:99]
	v_pk_fma_f32 v[110:111], v[100:101], v[100:101], v[110:111]
	v_pk_fma_f32 v[110:111], v[102:103], v[102:103], v[110:111]
	v_pk_fma_f32 v[110:111], v[104:105], v[104:105], v[110:111]
	v_cvt_pk_bf16_f32 v24, v98, v99
	v_cvt_pk_bf16_f32 v25, v100, v101
	v_cvt_pk_bf16_f32 v26, v102, v103
	v_cvt_pk_bf16_f32 v27, v104, v105
	global_store_dwordx4 v19, v[24:27], s[4:5] nt
	v_lshlrev_b32_e32 v106, 16, v36
	v_and_b32_e32 v107, 0xffff0000, v36
	v_lshlrev_b32_e32 v108, 16, v28
	v_and_b32_e32 v109, 0xffff0000, v28
	v_pk_mul_f32 v[106:107], v[96:97], v[106:107] op_sel_hi:[0,1]
	v_pk_fma_f32 v[98:99], v[2:3], v[106:107], v[108:109]
	v_lshlrev_b32_e32 v106, 16, v37
	v_and_b32_e32 v107, 0xffff0000, v37
	v_lshlrev_b32_e32 v108, 16, v29
	v_and_b32_e32 v109, 0xffff0000, v29
	v_pk_mul_f32 v[106:107], v[96:97], v[106:107] op_sel_hi:[0,1]
	v_pk_fma_f32 v[100:101], v[4:5], v[106:107], v[108:109]
	v_lshlrev_b32_e32 v106, 16, v38
	v_and_b32_e32 v107, 0xffff0000, v38
	v_lshlrev_b32_e32 v108, 16, v30
	v_and_b32_e32 v109, 0xffff0000, v30
	v_pk_mul_f32 v[106:107], v[96:97], v[106:107] op_sel_hi:[0,1]
	v_pk_fma_f32 v[102:103], v[6:7], v[106:107], v[108:109]
	v_lshlrev_b32_e32 v106, 16, v39
	v_and_b32_e32 v107, 0xffff0000, v39
	v_lshlrev_b32_e32 v108, 16, v31
	v_and_b32_e32 v109, 0xffff0000, v31
	v_pk_mul_f32 v[106:107], v[96:97], v[106:107] op_sel_hi:[0,1]
	v_pk_fma_f32 v[104:105], v[8:9], v[106:107], v[108:109]
	v_pk_fma_f32 v[110:111], v[98:99], v[98:99], v[110:111]
	v_pk_fma_f32 v[110:111], v[100:101], v[100:101], v[110:111]
	v_pk_fma_f32 v[110:111], v[102:103], v[102:103], v[110:111]
	v_pk_fma_f32 v[110:111], v[104:105], v[104:105], v[110:111]
	v_cvt_pk_bf16_f32 v28, v98, v99
	v_cvt_pk_bf16_f32 v29, v100, v101
	v_cvt_pk_bf16_f32 v30, v102, v103
	v_cvt_pk_bf16_f32 v31, v104, v105
	global_store_dwordx4 v19, v[28:31], s[4:5] offset:1024 nt
	v_add_f32_e32 v112, v110, v111
	v_add_u32_e32 v22, 0x2000, v22
	s_nop 1
	v_add_f32_dpp v112, v112, v112 quad_perm:[1,0,3,2] row_mask:0xf bank_mask:0xf
	s_nop 1
	v_add_f32_dpp v112, v112, v112 quad_perm:[2,3,0,1] row_mask:0xf bank_mask:0xf
	s_nop 1
	v_add_f32_dpp v112, v112, v112 row_half_mirror row_mask:0xf bank_mask:0xf
	s_nop 1
	v_add_f32_dpp v112, v112, v112 row_mirror row_mask:0xf bank_mask:0xf
	s_nop 1
	v_add_f32_dpp v112, v112, v112 row_bcast:15 row_mask:0xa bank_mask:0xf
	s_nop 1
	v_add_f32_dpp v112, v112, v112 row_bcast:31 row_mask:0xc bank_mask:0xf
	v_fmamk_f32 v113, v112, 0x3a800000, v244
	v_rsq_f32_e32 v113, v113
	s_mov_b64 exec, s[8:9]
	global_store_dword v22, v113, s[4:5]
	s_mov_b64 exec, -1
	v_add_u32_e32 v18, 0xfc400000, v18
	v_add_u32_e32 v20, 0xb400000, v20
	v_add_u32_e32 v21, 0xfffe2000, v21
	global_load_dwordx4 v[24:27], v18, s[4:5]
	global_load_dwordx4 v[32:35], v20, s[4:5]
	global_load_dwordx4 v[28:31], v18, s[4:5] offset:1024
	global_load_dwordx4 v[36:39], v20, s[4:5] offset:1024
	global_load_dword v40, v21, s[4:5]
	s_waitcnt vmcnt(24)
; __device__ __forceinline__ float bflo(unsigned w) { return __uint_as_float(w << 16); }
; __device__ __forceinline__ float bfhi(unsigned w) { return __uint_as_float(w & 0xffff0000u); }
; __device__ __forceinline__ void resid_rows(bf16_t* R, const bf16_t* Y, const float* ssqY, const float* g, float* rstd_out, float* outf, bool wf32, int row_lo, int row_hi, int yoff, int gw, int NGW, int lane) {
;     ...
;     for (int row0 = row_lo + gw; row0 < row_hi; row0 += RP * NGW) {
;         u32x4 rr[RP][2], oo[RP][2]; float ssv[RP];
; #pragma unroll
;         for (int k = 0; k < RP; ++k) { const int row = row0 + k * NGW; const bool ok = row < row_hi; const int rw = ok ? row : row0;
;             ssv[k] = ssqY[rw];
; #pragma unroll
;             for (int j = 0; j < 2; ++j) { const int c = 8 * lane + 512 * j; rr[k][j] = *(const u32x4*)(R + (size_t)rw * DM + c); oo[k][j] = *(const u32x4*)(Y + (size_t)(rw - yoff) * DM + c); } }
; #pragma unroll
;         for (int k = 0; k < RP; ++k) { const int row = row0 + k * NGW; if (row < row_hi) {
;             const float rs = __builtin_amdgcn_rsqf(ssv[k] * (1.0f / DM) + RMS_EPS); float s = 0.f;
; #pragma unroll
;             for (int j = 0; j < 2; ++j) { const int c = 8 * lane + 512 * j; const u32x4 r = rr[k][j], o = oo[k][j]; const f32x4 ga = gv[j][0], gb = gv[j][1];
;                 f32x4 ya, yb; ya[0] = bflo(r.x) + bflo(o.x) * rs * ga[0]; ya[1] = bfhi(r.x) + bfhi(o.x) * rs * ga[1]; ya[2] = bflo(r.y) + bflo(o.y) * rs * ga[2]; ya[3] = bfhi(r.y) + bfhi(o.y) * rs * ga[3];
;                 yb[0] = bflo(r.z) + bflo(o.z) * rs * gb[0]; yb[1] = bfhi(r.z) + bfhi(o.z) * rs * gb[1]; yb[2] = bflo(r.w) + bflo(o.w) * rs * gb[2]; yb[3] = bfhi(r.w) + bfhi(o.w) * rs * gb[3];
;                 if (wf32) { *(f32x4*)(outf + (size_t)row * DM + c) = ya; *(f32x4*)(outf + (size_t)row * DM + c + 4) = yb; }
;                 s += (ya[0] * ya[0] + ya[1] * ya[1]) + (ya[2] * ya[2] + ya[3] * ya[3]) + (yb[0] * yb[0] + yb[1] * yb[1]) + (yb[2] * yb[2] + yb[3] * yb[3]);
;                 u32x4 w; w.x = pk2(ya[0], ya[1]); w.y = pk2(ya[2], ya[3]); w.z = pk2(yb[0], yb[1]); w.w = pk2(yb[2], yb[3]); *(u32x4*)(R + (size_t)row * DM + c) = w; }
;             s = wave_sum(s); if (lane == 0) rstd_out[row] = __builtin_amdgcn_rsqf(s * (1.0f / DM) + RMS_EPS); } }
	v_fmamk_f32 v96, v58, 0x3a800000, v244
	v_rsq_f32_e32 v96, v96
	v_add_u32_e32 v19, 0x400000, v19
	v_lshlrev_b32_e32 v106, 16, v50
	v_and_b32_e32 v107, 0xffff0000, v50
	v_lshlrev_b32_e32 v108, 16, v42
	v_and_b32_e32 v109, 0xffff0000, v42
	v_pk_mul_f32 v[106:107], v[96:97], v[106:107] op_sel_hi:[0,1]
	v_pk_fma_f32 v[98:99], v[10:11], v[106:107], v[108:109]
	v_lshlrev_b32_e32 v106, 16, v51
	v_and_b32_e32 v107, 0xffff0000, v51
	v_lshlrev_b32_e32 v108, 16, v43
	v_and_b32_e32 v109, 0xffff0000, v43
	v_pk_mul_f32 v[106:107], v[96:97], v[106:107] op_sel_hi:[0,1]
	v_pk_fma_f32 v[100:101], v[12:13], v[106:107], v[108:109]
	v_lshlrev_b32_e32 v106, 16, v52
	v_and_b32_e32 v107, 0xffff0000, v52
	v_lshlrev_b32_e32 v108, 16, v44
	v_and_b32_e32 v109, 0xffff0000, v44
	v_pk_mul_f32 v[106:107], v[96:97], v[106:107] op_sel_hi:[0,1]
	v_pk_fma_f32 v[102:103], v[14:15], v[106:107], v[108:109]
	v_lshlrev_b32_e32 v106, 16, v53
	v_and_b32_e32 v107, 0xffff0000, v53
	v_lshlrev_b32_e32 v108, 16, v45
	v_and_b32_e32 v109, 0xffff0000, v45
	v_pk_mul_f32 v[106:107], v[96:97], v[106:107] op_sel_hi:[0,1]
	v_pk_fma_f32 v[104:105], v[16:17], v[106:107], v[108:109]
	v_pk_mul_f32 v[110:111], v[98:99], v[98:99]
	v_pk_fma_f32 v[110:111], v[100:101], v[100:101], v[110:111]
	v_pk_fma_f32 v[110:111], v[102:103], v[102:103], v[110:111]
	v_pk_fma_f32 v[110:111], v[104:105], v[104:105], v[110:111]
	v_cvt_pk_bf16_f32 v42, v98, v99
	v_cvt_pk_bf16_f32 v43, v100, v101
	v_cvt_pk_bf16_f32 v44, v102, v103
	v_cvt_pk_bf16_f32 v45, v104, v105
	global_store_dwordx4 v19, v[42:45], s[4:5] nt
	v_lshlrev_b32_e32 v106, 16, v54
	v_and_b32_e32 v107, 0xffff0000, v54
	v_lshlrev_b32_e32 v108, 16, v46
	v_and_b32_e32 v109, 0xffff0000, v46
	v_pk_mul_f32 v[106:107], v[96:97], v[106:107] op_sel_hi:[0,1]
	v_pk_fma_f32 v[98:99], v[2:3], v[106:107], v[108:109]
	v_lshlrev_b32_e32 v106, 16, v55
	v_and_b32_e32 v107, 0xffff0000, v55
	v_lshlrev_b32_e32 v108, 16, v47
	v_and_b32_e32 v109, 0xffff0000, v47
	v_pk_mul_f32 v[106:107], v[96:97], v[106:107] op_sel_hi:[0,1]
	v_pk_fma_f32 v[100:101], v[4:5], v[106:107], v[108:109]
	v_lshlrev_b32_e32 v106, 16, v56
	v_and_b32_e32 v107, 0xffff0000, v56
	v_lshlrev_b32_e32 v108, 16, v48
	v_and_b32_e32 v109, 0xffff0000, v48
	v_pk_mul_f32 v[106:107], v[96:97], v[106:107] op_sel_hi:[0,1]
	v_pk_fma_f32 v[102:103], v[6:7], v[106:107], v[108:109]
	v_lshlrev_b32_e32 v106, 16, v57
	v_and_b32_e32 v107, 0xffff0000, v57
	v_lshlrev_b32_e32 v108, 16, v49
	v_and_b32_e32 v109, 0xffff0000, v49
	v_pk_mul_f32 v[106:107], v[96:97], v[106:107] op_sel_hi:[0,1]
	v_pk_fma_f32 v[104:105], v[8:9], v[106:107], v[108:109]
	v_pk_fma_f32 v[110:111], v[98:99], v[98:99], v[110:111]
	v_pk_fma_f32 v[110:111], v[100:101], v[100:101], v[110:111]
	v_pk_fma_f32 v[110:111], v[102:103], v[102:103], v[110:111]
	v_pk_fma_f32 v[110:111], v[104:105], v[104:105], v[110:111]
	v_cvt_pk_bf16_f32 v46, v98, v99
	v_cvt_pk_bf16_f32 v47, v100, v101
	v_cvt_pk_bf16_f32 v48, v102, v103
	v_cvt_pk_bf16_f32 v49, v104, v105
	global_store_dwordx4 v19, v[46:49], s[4:5] offset:1024 nt
	v_add_f32_e32 v112, v110, v111
	v_add_u32_e32 v22, 0x2000, v22
	s_nop 1
	v_add_f32_dpp v112, v112, v112 quad_perm:[1,0,3,2] row_mask:0xf bank_mask:0xf
	s_nop 1
	v_add_f32_dpp v112, v112, v112 quad_perm:[2,3,0,1] row_mask:0xf bank_mask:0xf
	s_nop 1
	v_add_f32_dpp v112, v112, v112 row_half_mirror row_mask:0xf bank_mask:0xf
	s_nop 1
	v_add_f32_dpp v112, v112, v112 row_mirror row_mask:0xf bank_mask:0xf
	s_nop 1
	v_add_f32_dpp v112, v112, v112 row_bcast:15 row_mask:0xa bank_mask:0xf
	s_nop 1
	v_add_f32_dpp v112, v112, v112 row_bcast:31 row_mask:0xc bank_mask:0xf
	v_fmamk_f32 v113, v112, 0x3a800000, v244
	v_rsq_f32_e32 v113, v113
	s_mov_b64 exec, s[8:9]
	global_store_dword v22, v113, s[4:5]
	s_mov_b64 exec, -1
	v_add_u32_e32 v18, 0x400000, v18
	v_add_u32_e32 v20, 0x400000, v20
	v_add_u32_e32 v21, 0x2000, v21
	global_load_dwordx4 v[42:45], v18, s[4:5]
	global_load_dwordx4 v[50:53], v20, s[4:5]
	global_load_dwordx4 v[46:49], v18, s[4:5] offset:1024
	global_load_dwordx4 v[54:57], v20, s[4:5] offset:1024
	global_load_dword v58, v21, s[4:5]
	s_waitcnt vmcnt(24)
	v_fmamk_f32 v96, v76, 0x3a800000, v244
	v_rsq_f32_e32 v96, v96
	v_add_u32_e32 v19, 0x400000, v19
	v_lshlrev_b32_e32 v106, 16, v68
	v_and_b32_e32 v107, 0xffff0000, v68
	v_lshlrev_b32_e32 v108, 16, v60
	v_and_b32_e32 v109, 0xffff0000, v60
	v_pk_mul_f32 v[106:107], v[96:97], v[106:107] op_sel_hi:[0,1]
	v_pk_fma_f32 v[98:99], v[10:11], v[106:107], v[108:109]
	v_lshlrev_b32_e32 v106, 16, v69
	v_and_b32_e32 v107, 0xffff0000, v69
	v_lshlrev_b32_e32 v108, 16, v61
	v_and_b32_e32 v109, 0xffff0000, v61
	v_pk_mul_f32 v[106:107], v[96:97], v[106:107] op_sel_hi:[0,1]
	v_pk_fma_f32 v[100:101], v[12:13], v[106:107], v[108:109]
	v_lshlrev_b32_e32 v106, 16, v70
	v_and_b32_e32 v107, 0xffff0000, v70
	v_lshlrev_b32_e32 v108, 16, v62
	v_and_b32_e32 v109, 0xffff0000, v62
	v_pk_mul_f32 v[106:107], v[96:97], v[106:107] op_sel_hi:[0,1]
	v_pk_fma_f32 v[102:103], v[14:15], v[106:107], v[108:109]
	v_lshlrev_b32_e32 v106, 16, v71
	v_and_b32_e32 v107, 0xffff0000, v71
	v_lshlrev_b32_e32 v108, 16, v63
	v_and_b32_e32 v109, 0xffff0000, v63
	v_pk_mul_f32 v[106:107], v[96:97], v[106:107] op_sel_hi:[0,1]
	v_pk_fma_f32 v[104:105], v[16:17], v[106:107], v[108:109]
	v_pk_mul_f32 v[110:111], v[98:99], v[98:99]
	v_pk_fma_f32 v[110:111], v[100:101], v[100:101], v[110:111]
	v_pk_fma_f32 v[110:111], v[102:103], v[102:103], v[110:111]
	v_pk_fma_f32 v[110:111], v[104:105], v[104:105], v[110:111]
	v_cvt_pk_bf16_f32 v60, v98, v99
	v_cvt_pk_bf16_f32 v61, v100, v101
	v_cvt_pk_bf16_f32 v62, v102, v103
	v_cvt_pk_bf16_f32 v63, v104, v105
	global_store_dwordx4 v19, v[60:63], s[4:5] nt
; __device__ __forceinline__ float bflo(unsigned w) { return __uint_as_float(w << 16); }
; __device__ __forceinline__ float bfhi(unsigned w) { return __uint_as_float(w & 0xffff0000u); }
; __device__ __forceinline__ void resid_rows(bf16_t* R, const bf16_t* Y, const float* ssqY, const float* g, float* rstd_out, float* outf, bool wf32, int row_lo, int row_hi, int yoff, int gw, int NGW, int lane) {
;     ...
;     for (int row0 = row_lo + gw; row0 < row_hi; row0 += RP * NGW) {
;         u32x4 rr[RP][2], oo[RP][2]; float ssv[RP];
; #pragma unroll
;         for (int k = 0; k < RP; ++k) { const int row = row0 + k * NGW; const bool ok = row < row_hi; const int rw = ok ? row : row0;
;             ssv[k] = ssqY[rw];
; #pragma unroll
;             for (int j = 0; j < 2; ++j) { const int c = 8 * lane + 512 * j; rr[k][j] = *(const u32x4*)(R + (size_t)rw * DM + c); oo[k][j] = *(const u32x4*)(Y + (size_t)(rw - yoff) * DM + c); } }
; #pragma unroll
;         for (int k = 0; k < RP; ++k) { const int row = row0 + k * NGW; if (row < row_hi) {
;             const float rs = __builtin_amdgcn_rsqf(ssv[k] * (1.0f / DM) + RMS_EPS); float s = 0.f;
; #pragma unroll
;             for (int j = 0; j < 2; ++j) { const int c = 8 * lane + 512 * j; const u32x4 r = rr[k][j], o = oo[k][j]; const f32x4 ga = gv[j][0], gb = gv[j][1];
;                 f32x4 ya, yb; ya[0] = bflo(r.x) + bflo(o.x) * rs * ga[0]; ya[1] = bfhi(r.x) + bfhi(o.x) * rs * ga[1]; ya[2] = bflo(r.y) + bflo(o.y) * rs * ga[2]; ya[3] = bfhi(r.y) + bfhi(o.y) * rs * ga[3];
;                 yb[0] = bflo(r.z) + bflo(o.z) * rs * gb[0]; yb[1] = bfhi(r.z) + bfhi(o.z) * rs * gb[1]; yb[2] = bflo(r.w) + bflo(o.w) * rs * gb[2]; yb[3] = bfhi(r.w) + bfhi(o.w) * rs * gb[3];
;                 if (wf32) { *(f32x4*)(outf + (size_t)row * DM + c) = ya; *(f32x4*)(outf + (size_t)row * DM + c + 4) = yb; }
;                 s += (ya[0] * ya[0] + ya[1] * ya[1]) + (ya[2] * ya[2] + ya[3] * ya[3]) + (yb[0] * yb[0] + yb[1] * yb[1]) + (yb[2] * yb[2] + yb[3] * yb[3]);
;                 u32x4 w; w.x = pk2(ya[0], ya[1]); w.y = pk2(ya[2], ya[3]); w.z = pk2(yb[0], yb[1]); w.w = pk2(yb[2], yb[3]); *(u32x4*)(R + (size_t)row * DM + c) = w; }
;             s = wave_sum(s); if (lane == 0) rstd_out[row] = __builtin_amdgcn_rsqf(s * (1.0f / DM) + RMS_EPS); } }
	v_lshlrev_b32_e32 v106, 16, v72
	v_and_b32_e32 v107, 0xffff0000, v72
	v_lshlrev_b32_e32 v108, 16, v64
	v_and_b32_e32 v109, 0xffff0000, v64
	v_pk_mul_f32 v[106:107], v[96:97], v[106:107] op_sel_hi:[0,1]
	v_pk_fma_f32 v[98:99], v[2:3], v[106:107], v[108:109]
	v_lshlrev_b32_e32 v106, 16, v73
	v_and_b32_e32 v107, 0xffff0000, v73
	v_lshlrev_b32_e32 v108, 16, v65
	v_and_b32_e32 v109, 0xffff0000, v65
	v_pk_mul_f32 v[106:107], v[96:97], v[106:107] op_sel_hi:[0,1]
	v_pk_fma_f32 v[100:101], v[4:5], v[106:107], v[108:109]
	v_lshlrev_b32_e32 v106, 16, v74
	v_and_b32_e32 v107, 0xffff0000, v74
	v_lshlrev_b32_e32 v108, 16, v66
	v_and_b32_e32 v109, 0xffff0000, v66
	v_pk_mul_f32 v[106:107], v[96:97], v[106:107] op_sel_hi:[0,1]
	v_pk_fma_f32 v[102:103], v[6:7], v[106:107], v[108:109]
	v_lshlrev_b32_e32 v106, 16, v75
	v_and_b32_e32 v107, 0xffff0000, v75
	v_lshlrev_b32_e32 v108, 16, v67
	v_and_b32_e32 v109, 0xffff0000, v67
	v_pk_mul_f32 v[106:107], v[96:97], v[106:107] op_sel_hi:[0,1]
	v_pk_fma_f32 v[104:105], v[8:9], v[106:107], v[108:109]
	v_pk_fma_f32 v[110:111], v[98:99], v[98:99], v[110:111]
	v_pk_fma_f32 v[110:111], v[100:101], v[100:101], v[110:111]
	v_pk_fma_f32 v[110:111], v[102:103], v[102:103], v[110:111]
	v_pk_fma_f32 v[110:111], v[104:105], v[104:105], v[110:111]
	v_cvt_pk_bf16_f32 v64, v98, v99
	v_cvt_pk_bf16_f32 v65, v100, v101
	v_cvt_pk_bf16_f32 v66, v102, v103
	v_cvt_pk_bf16_f32 v67, v104, v105
	global_store_dwordx4 v19, v[64:67], s[4:5] offset:1024 nt
	v_add_f32_e32 v112, v110, v111
	v_add_u32_e32 v22, 0x2000, v22
	s_nop 1
	v_add_f32_dpp v112, v112, v112 quad_perm:[1,0,3,2] row_mask:0xf bank_mask:0xf
	s_nop 1
	v_add_f32_dpp v112, v112, v112 quad_perm:[2,3,0,1] row_mask:0xf bank_mask:0xf
	s_nop 1
	v_add_f32_dpp v112, v112, v112 row_half_mirror row_mask:0xf bank_mask:0xf
	s_nop 1
	v_add_f32_dpp v112, v112, v112 row_mirror row_mask:0xf bank_mask:0xf
	s_nop 1
	v_add_f32_dpp v112, v112, v112 row_bcast:15 row_mask:0xa bank_mask:0xf
	s_nop 1
	v_add_f32_dpp v112, v112, v112 row_bcast:31 row_mask:0xc bank_mask:0xf
	v_fmamk_f32 v113, v112, 0x3a800000, v244
	v_rsq_f32_e32 v113, v113
	s_mov_b64 exec, s[8:9]
	global_store_dword v22, v113, s[4:5]
	s_mov_b64 exec, -1
	v_add_u32_e32 v18, 0x400000, v18
	v_add_u32_e32 v20, 0x400000, v20
	v_add_u32_e32 v21, 0x2000, v21
	global_load_dwordx4 v[60:63], v18, s[4:5]
	global_load_dwordx4 v[68:71], v20, s[4:5]
	global_load_dwordx4 v[64:67], v18, s[4:5] offset:1024
	global_load_dwordx4 v[72:75], v20, s[4:5] offset:1024
	global_load_dword v76, v21, s[4:5]
	s_waitcnt vmcnt(24)
	v_fmamk_f32 v96, v94, 0x3a800000, v244
	v_rsq_f32_e32 v96, v96
	v_add_u32_e32 v19, 0x400000, v19
	v_lshlrev_b32_e32 v106, 16, v86
	v_and_b32_e32 v107, 0xffff0000, v86
	v_lshlrev_b32_e32 v108, 16, v78
	v_and_b32_e32 v109, 0xffff0000, v78
	v_pk_mul_f32 v[106:107], v[96:97], v[106:107] op_sel_hi:[0,1]
	v_pk_fma_f32 v[98:99], v[10:11], v[106:107], v[108:109]
	v_lshlrev_b32_e32 v106, 16, v87
	v_and_b32_e32 v107, 0xffff0000, v87
	v_lshlrev_b32_e32 v108, 16, v79
	v_and_b32_e32 v109, 0xffff0000, v79
	v_pk_mul_f32 v[106:107], v[96:97], v[106:107] op_sel_hi:[0,1]
	v_pk_fma_f32 v[100:101], v[12:13], v[106:107], v[108:109]
	v_lshlrev_b32_e32 v106, 16, v88
	v_and_b32_e32 v107, 0xffff0000, v88
	v_lshlrev_b32_e32 v108, 16, v80
	v_and_b32_e32 v109, 0xffff0000, v80
	v_pk_mul_f32 v[106:107], v[96:97], v[106:107] op_sel_hi:[0,1]
	v_pk_fma_f32 v[102:103], v[14:15], v[106:107], v[108:109]
	v_lshlrev_b32_e32 v106, 16, v89
	v_and_b32_e32 v107, 0xffff0000, v89
	v_lshlrev_b32_e32 v108, 16, v81
	v_and_b32_e32 v109, 0xffff0000, v81
	v_pk_mul_f32 v[106:107], v[96:97], v[106:107] op_sel_hi:[0,1]
	v_pk_fma_f32 v[104:105], v[16:17], v[106:107], v[108:109]
	v_pk_mul_f32 v[110:111], v[98:99], v[98:99]
	v_pk_fma_f32 v[110:111], v[100:101], v[100:101], v[110:111]
	v_pk_fma_f32 v[110:111], v[102:103], v[102:103], v[110:111]
	v_pk_fma_f32 v[110:111], v[104:105], v[104:105], v[110:111]
	v_cvt_pk_bf16_f32 v78, v98, v99
	v_cvt_pk_bf16_f32 v79, v100, v101
	v_cvt_pk_bf16_f32 v80, v102, v103
	v_cvt_pk_bf16_f32 v81, v104, v105
	global_store_dwordx4 v19, v[78:81], s[4:5] nt
	v_lshlrev_b32_e32 v106, 16, v90
	v_and_b32_e32 v107, 0xffff0000, v90
	v_lshlrev_b32_e32 v108, 16, v82
	v_and_b32_e32 v109, 0xffff0000, v82
	v_pk_mul_f32 v[106:107], v[96:97], v[106:107] op_sel_hi:[0,1]
	v_pk_fma_f32 v[98:99], v[2:3], v[106:107], v[108:109]
	v_lshlrev_b32_e32 v106, 16, v91
	v_and_b32_e32 v107, 0xffff0000, v91
	v_lshlrev_b32_e32 v108, 16, v83
	v_and_b32_e32 v109, 0xffff0000, v83
	v_pk_mul_f32 v[106:107], v[96:97], v[106:107] op_sel_hi:[0,1]
	v_pk_fma_f32 v[100:101], v[4:5], v[106:107], v[108:109]
	v_lshlrev_b32_e32 v106, 16, v92
	v_and_b32_e32 v107, 0xffff0000, v92
	v_lshlrev_b32_e32 v108, 16, v84
	v_and_b32_e32 v109, 0xffff0000, v84
	v_pk_mul_f32 v[106:107], v[96:97], v[106:107] op_sel_hi:[0,1]
	v_pk_fma_f32 v[102:103], v[6:7], v[106:107], v[108:109]
	v_lshlrev_b32_e32 v106, 16, v93
	v_and_b32_e32 v107, 0xffff0000, v93
	v_lshlrev_b32_e32 v108, 16, v85
	v_and_b32_e32 v109, 0xffff0000, v85
	v_pk_mul_f32 v[106:107], v[96:97], v[106:107] op_sel_hi:[0,1]
	v_pk_fma_f32 v[104:105], v[8:9], v[106:107], v[108:109]
	v_pk_fma_f32 v[110:111], v[98:99], v[98:99], v[110:111]
	v_pk_fma_f32 v[110:111], v[100:101], v[100:101], v[110:111]
	v_pk_fma_f32 v[110:111], v[102:103], v[102:103], v[110:111]
	v_pk_fma_f32 v[110:111], v[104:105], v[104:105], v[110:111]
	v_cvt_pk_bf16_f32 v82, v98, v99
	v_cvt_pk_bf16_f32 v83, v100, v101
	v_cvt_pk_bf16_f32 v84, v102, v103
	v_cvt_pk_bf16_f32 v85, v104, v105
	global_store_dwordx4 v19, v[82:85], s[4:5] offset:1024 nt
	v_add_f32_e32 v112, v110, v111
	v_add_u32_e32 v22, 0x2000, v22
	s_nop 1
	v_add_f32_dpp v112, v112, v112 quad_perm:[1,0,3,2] row_mask:0xf bank_mask:0xf
	s_nop 1
	v_add_f32_dpp v112, v112, v112 quad_perm:[2,3,0,1] row_mask:0xf bank_mask:0xf
	s_nop 1
	v_add_f32_dpp v112, v112, v112 row_half_mirror row_mask:0xf bank_mask:0xf
	s_nop 1
	v_add_f32_dpp v112, v112, v112 row_mirror row_mask:0xf bank_mask:0xf
	s_nop 1
	v_add_f32_dpp v112, v112, v112 row_bcast:15 row_mask:0xa bank_mask:0xf
	s_nop 1
	v_add_f32_dpp v112, v112, v112 row_bcast:31 row_mask:0xc bank_mask:0xf
	v_fmamk_f32 v113, v112, 0x3a800000, v244
	v_rsq_f32_e32 v113, v113
	s_mov_b64 exec, s[8:9]
	global_store_dword v22, v113, s[4:5]
	s_mov_b64 exec, -1
	v_add_u32_e32 v18, 0x400000, v18
	v_add_u32_e32 v20, 0x400000, v20
	v_add_u32_e32 v21, 0x2000, v21
	global_load_dwordx4 v[78:81], v18, s[4:5]
	global_load_dwordx4 v[86:89], v20, s[4:5]
	global_load_dwordx4 v[82:85], v18, s[4:5] offset:1024
	global_load_dwordx4 v[90:93], v20, s[4:5] offset:1024
	global_load_dword v94, v21, s[4:5]
	s_waitcnt vmcnt(24)
; __device__ __forceinline__ float bflo(unsigned w) { return __uint_as_float(w << 16); }
; __device__ __forceinline__ float bfhi(unsigned w) { return __uint_as_float(w & 0xffff0000u); }
; __device__ __forceinline__ void resid_rows(bf16_t* R, const bf16_t* Y, const float* ssqY, const float* g, float* rstd_out, float* outf, bool wf32, int row_lo, int row_hi, int yoff, int gw, int NGW, int lane) {
;     ...
;     for (int row0 = row_lo + gw; row0 < row_hi; row0 += RP * NGW) {
;         u32x4 rr[RP][2], oo[RP][2]; float ssv[RP];
; #pragma unroll
;         for (int k = 0; k < RP; ++k) { const int row = row0 + k * NGW; const bool ok = row < row_hi; const int rw = ok ? row : row0;
;             ssv[k] = ssqY[rw];
; #pragma unroll
;             for (int j = 0; j < 2; ++j) { const int c = 8 * lane + 512 * j; rr[k][j] = *(const u32x4*)(R + (size_t)rw * DM + c); oo[k][j] = *(const u32x4*)(Y + (size_t)(rw - yoff) * DM + c); } }
; #pragma unroll
;         for (int k = 0; k < RP; ++k) { const int row = row0 + k * NGW; if (row < row_hi) {
;             const float rs = __builtin_amdgcn_rsqf(ssv[k] * (1.0f / DM) + RMS_EPS); float s = 0.f;
; #pragma unroll
;             for (int j = 0; j < 2; ++j) { const int c = 8 * lane + 512 * j; const u32x4 r = rr[k][j], o = oo[k][j]; const f32x4 ga = gv[j][0], gb = gv[j][1];
;                 f32x4 ya, yb; ya[0] = bflo(r.x) + bflo(o.x) * rs * ga[0]; ya[1] = bfhi(r.x) + bfhi(o.x) * rs * ga[1]; ya[2] = bflo(r.y) + bflo(o.y) * rs * ga[2]; ya[3] = bfhi(r.y) + bfhi(o.y) * rs * ga[3];
;                 yb[0] = bflo(r.z) + bflo(o.z) * rs * gb[0]; yb[1] = bfhi(r.z) + bfhi(o.z) * rs * gb[1]; yb[2] = bflo(r.w) + bflo(o.w) * rs * gb[2]; yb[3] = bfhi(r.w) + bfhi(o.w) * rs * gb[3];
;                 if (wf32) { *(f32x4*)(outf + (size_t)row * DM + c) = ya; *(f32x4*)(outf + (size_t)row * DM + c + 4) = yb; }
;                 s += (ya[0] * ya[0] + ya[1] * ya[1]) + (ya[2] * ya[2] + ya[3] * ya[3]) + (yb[0] * yb[0] + yb[1] * yb[1]) + (yb[2] * yb[2] + yb[3] * yb[3]);
;                 u32x4 w; w.x = pk2(ya[0], ya[1]); w.y = pk2(ya[2], ya[3]); w.z = pk2(yb[0], yb[1]); w.w = pk2(yb[2], yb[3]); *(u32x4*)(R + (size_t)row * DM + c) = w; }
;             s = wave_sum(s); if (lane == 0) rstd_out[row] = __builtin_amdgcn_rsqf(s * (1.0f / DM) + RMS_EPS); } }
	v_fmamk_f32 v96, v40, 0x3a800000, v244
	v_rsq_f32_e32 v96, v96
	v_add_u32_e32 v19, 0xfc400000, v19
	v_lshlrev_b32_e32 v106, 16, v32
	v_and_b32_e32 v107, 0xffff0000, v32
	v_lshlrev_b32_e32 v108, 16, v24
	v_and_b32_e32 v109, 0xffff0000, v24
	v_pk_mul_f32 v[106:107], v[96:97], v[106:107] op_sel_hi:[0,1]
	v_pk_fma_f32 v[98:99], v[10:11], v[106:107], v[108:109]
	v_lshlrev_b32_e32 v106, 16, v33
	v_and_b32_e32 v107, 0xffff0000, v33
	v_lshlrev_b32_e32 v108, 16, v25
	v_and_b32_e32 v109, 0xffff0000, v25
	v_pk_mul_f32 v[106:107], v[96:97], v[106:107] op_sel_hi:[0,1]
	v_pk_fma_f32 v[100:101], v[12:13], v[106:107], v[108:109]
	v_lshlrev_b32_e32 v106, 16, v34
	v_and_b32_e32 v107, 0xffff0000, v34
	v_lshlrev_b32_e32 v108, 16, v26
	v_and_b32_e32 v109, 0xffff0000, v26
	v_pk_mul_f32 v[106:107], v[96:97], v[106:107] op_sel_hi:[0,1]
	v_pk_fma_f32 v[102:103], v[14:15], v[106:107], v[108:109]
	v_lshlrev_b32_e32 v106, 16, v35
	v_and_b32_e32 v107, 0xffff0000, v35
	v_lshlrev_b32_e32 v108, 16, v27
	v_and_b32_e32 v109, 0xffff0000, v27
	v_pk_mul_f32 v[106:107], v[96:97], v[106:107] op_sel_hi:[0,1]
	v_pk_fma_f32 v[104:105], v[16:17], v[106:107], v[108:109]
	v_pk_mul_f32 v[110:111], v[98:99], v[98:99]
	v_pk_fma_f32 v[110:111], v[100:101], v[100:101], v[110:111]
	v_pk_fma_f32 v[110:111], v[102:103], v[102:103], v[110:111]
	v_pk_fma_f32 v[110:111], v[104:105], v[104:105], v[110:111]
	v_cvt_pk_bf16_f32 v24, v98, v99
	v_cvt_pk_bf16_f32 v25, v100, v101
	v_cvt_pk_bf16_f32 v26, v102, v103
	v_cvt_pk_bf16_f32 v27, v104, v105
	global_store_dwordx4 v19, v[24:27], s[4:5] nt
	v_lshlrev_b32_e32 v106, 16, v36
	v_and_b32_e32 v107, 0xffff0000, v36
	v_lshlrev_b32_e32 v108, 16, v28
	v_and_b32_e32 v109, 0xffff0000, v28
	v_pk_mul_f32 v[106:107], v[96:97], v[106:107] op_sel_hi:[0,1]
	v_pk_fma_f32 v[98:99], v[2:3], v[106:107], v[108:109]
	v_lshlrev_b32_e32 v106, 16, v37
	v_and_b32_e32 v107, 0xffff0000, v37
	v_lshlrev_b32_e32 v108, 16, v29
	v_and_b32_e32 v109, 0xffff0000, v29
	v_pk_mul_f32 v[106:107], v[96:97], v[106:107] op_sel_hi:[0,1]
	v_pk_fma_f32 v[100:101], v[4:5], v[106:107], v[108:109]
	v_lshlrev_b32_e32 v106, 16, v38
	v_and_b32_e32 v107, 0xffff0000, v38
	v_lshlrev_b32_e32 v108, 16, v30
	v_and_b32_e32 v109, 0xffff0000, v30
	v_pk_mul_f32 v[106:107], v[96:97], v[106:107] op_sel_hi:[0,1]
	v_pk_fma_f32 v[102:103], v[6:7], v[106:107], v[108:109]
	v_lshlrev_b32_e32 v106, 16, v39
	v_and_b32_e32 v107, 0xffff0000, v39
	v_lshlrev_b32_e32 v108, 16, v31
	v_and_b32_e32 v109, 0xffff0000, v31
	v_pk_mul_f32 v[106:107], v[96:97], v[106:107] op_sel_hi:[0,1]
	v_pk_fma_f32 v[104:105], v[8:9], v[106:107], v[108:109]
	v_pk_fma_f32 v[110:111], v[98:99], v[98:99], v[110:111]
	v_pk_fma_f32 v[110:111], v[100:101], v[100:101], v[110:111]
	v_pk_fma_f32 v[110:111], v[102:103], v[102:103], v[110:111]
	v_pk_fma_f32 v[110:111], v[104:105], v[104:105], v[110:111]
	v_cvt_pk_bf16_f32 v28, v98, v99
	v_cvt_pk_bf16_f32 v29, v100, v101
	v_cvt_pk_bf16_f32 v30, v102, v103
	v_cvt_pk_bf16_f32 v31, v104, v105
	global_store_dwordx4 v19, v[28:31], s[4:5] offset:1024 nt
	v_add_f32_e32 v112, v110, v111
	v_add_u32_e32 v22, 0xfffe2000, v22
	s_nop 1
	v_add_f32_dpp v112, v112, v112 quad_perm:[1,0,3,2] row_mask:0xf bank_mask:0xf
	s_nop 1
	v_add_f32_dpp v112, v112, v112 quad_perm:[2,3,0,1] row_mask:0xf bank_mask:0xf
	s_nop 1
	v_add_f32_dpp v112, v112, v112 row_half_mirror row_mask:0xf bank_mask:0xf
	s_nop 1
	v_add_f32_dpp v112, v112, v112 row_mirror row_mask:0xf bank_mask:0xf
	s_nop 1
	v_add_f32_dpp v112, v112, v112 row_bcast:15 row_mask:0xa bank_mask:0xf
	s_nop 1
	v_add_f32_dpp v112, v112, v112 row_bcast:31 row_mask:0xc bank_mask:0xf
	v_fmamk_f32 v113, v112, 0x3a800000, v244
	v_rsq_f32_e32 v113, v113
	s_mov_b64 exec, s[8:9]
	global_store_dword v22, v113, s[4:5]
	s_mov_b64 exec, -1
	v_add_u32_e32 v18, 0x400000, v18
	v_add_u32_e32 v20, 0x400000, v20
	v_add_u32_e32 v21, 0x2000, v21
	global_load_dwordx4 v[24:27], v18, s[4:5]
	global_load_dwordx4 v[32:35], v20, s[4:5]
	global_load_dwordx4 v[28:31], v18, s[4:5] offset:1024
	global_load_dwordx4 v[36:39], v20, s[4:5] offset:1024
	global_load_dword v40, v21, s[4:5]
	s_waitcnt vmcnt(24)
	v_fmamk_f32 v96, v58, 0x3a800000, v244
	v_rsq_f32_e32 v96, v96
	v_add_u32_e32 v19, 0x400000, v19
	v_lshlrev_b32_e32 v106, 16, v50
	v_and_b32_e32 v107, 0xffff0000, v50
	v_lshlrev_b32_e32 v108, 16, v42
	v_and_b32_e32 v109, 0xffff0000, v42
	v_pk_mul_f32 v[106:107], v[96:97], v[106:107] op_sel_hi:[0,1]
	v_pk_fma_f32 v[98:99], v[10:11], v[106:107], v[108:109]
	v_lshlrev_b32_e32 v106, 16, v51
	v_and_b32_e32 v107, 0xffff0000, v51
	v_lshlrev_b32_e32 v108, 16, v43
	v_and_b32_e32 v109, 0xffff0000, v43
	v_pk_mul_f32 v[106:107], v[96:97], v[106:107] op_sel_hi:[0,1]
	v_pk_fma_f32 v[100:101], v[12:13], v[106:107], v[108:109]
	v_lshlrev_b32_e32 v106, 16, v52
	v_and_b32_e32 v107, 0xffff0000, v52
	v_lshlrev_b32_e32 v108, 16, v44
	v_and_b32_e32 v109, 0xffff0000, v44
	v_pk_mul_f32 v[106:107], v[96:97], v[106:107] op_sel_hi:[0,1]
	v_pk_fma_f32 v[102:103], v[14:15], v[106:107], v[108:109]
	v_lshlrev_b32_e32 v106, 16, v53
	v_and_b32_e32 v107, 0xffff0000, v53
	v_lshlrev_b32_e32 v108, 16, v45
	v_and_b32_e32 v109, 0xffff0000, v45
	v_pk_mul_f32 v[106:107], v[96:97], v[106:107] op_sel_hi:[0,1]
	v_pk_fma_f32 v[104:105], v[16:17], v[106:107], v[108:109]
	v_pk_mul_f32 v[110:111], v[98:99], v[98:99]
	v_pk_fma_f32 v[110:111], v[100:101], v[100:101], v[110:111]
	v_pk_fma_f32 v[110:111], v[102:103], v[102:103], v[110:111]
	v_pk_fma_f32 v[110:111], v[104:105], v[104:105], v[110:111]
	v_cvt_pk_bf16_f32 v42, v98, v99
	v_cvt_pk_bf16_f32 v43, v100, v101
	v_cvt_pk_bf16_f32 v44, v102, v103
	v_cvt_pk_bf16_f32 v45, v104, v105
	global_store_dwordx4 v19, v[42:45], s[4:5] nt
; __device__ __forceinline__ float bflo(unsigned w) { return __uint_as_float(w << 16); }
; __device__ __forceinline__ float bfhi(unsigned w) { return __uint_as_float(w & 0xffff0000u); }
; __device__ __forceinline__ void resid_rows(bf16_t* R, const bf16_t* Y, const float* ssqY, const float* g, float* rstd_out, float* outf, bool wf32, int row_lo, int row_hi, int yoff, int gw, int NGW, int lane) {
;     ...
;     for (int row0 = row_lo + gw; row0 < row_hi; row0 += RP * NGW) {
;         u32x4 rr[RP][2], oo[RP][2]; float ssv[RP];
; #pragma unroll
;         for (int k = 0; k < RP; ++k) { const int row = row0 + k * NGW; const bool ok = row < row_hi; const int rw = ok ? row : row0;
;             ssv[k] = ssqY[rw];
; #pragma unroll
;             for (int j = 0; j < 2; ++j) { const int c = 8 * lane + 512 * j; rr[k][j] = *(const u32x4*)(R + (size_t)rw * DM + c); oo[k][j] = *(const u32x4*)(Y + (size_t)(rw - yoff) * DM + c); } }
; #pragma unroll
;         for (int k = 0; k < RP; ++k) { const int row = row0 + k * NGW; if (row < row_hi) {
;             const float rs = __builtin_amdgcn_rsqf(ssv[k] * (1.0f / DM) + RMS_EPS); float s = 0.f;
; #pragma unroll
;             for (int j = 0; j < 2; ++j) { const int c = 8 * lane + 512 * j; const u32x4 r = rr[k][j], o = oo[k][j]; const f32x4 ga = gv[j][0], gb = gv[j][1];
;                 f32x4 ya, yb; ya[0] = bflo(r.x) + bflo(o.x) * rs * ga[0]; ya[1] = bfhi(r.x) + bfhi(o.x) * rs * ga[1]; ya[2] = bflo(r.y) + bflo(o.y) * rs * ga[2]; ya[3] = bfhi(r.y) + bfhi(o.y) * rs * ga[3];
;                 yb[0] = bflo(r.z) + bflo(o.z) * rs * gb[0]; yb[1] = bfhi(r.z) + bfhi(o.z) * rs * gb[1]; yb[2] = bflo(r.w) + bflo(o.w) * rs * gb[2]; yb[3] = bfhi(r.w) + bfhi(o.w) * rs * gb[3];
;                 if (wf32) { *(f32x4*)(outf + (size_t)row * DM + c) = ya; *(f32x4*)(outf + (size_t)row * DM + c + 4) = yb; }
;                 s += (ya[0] * ya[0] + ya[1] * ya[1]) + (ya[2] * ya[2] + ya[3] * ya[3]) + (yb[0] * yb[0] + yb[1] * yb[1]) + (yb[2] * yb[2] + yb[3] * yb[3]);
;                 u32x4 w; w.x = pk2(ya[0], ya[1]); w.y = pk2(ya[2], ya[3]); w.z = pk2(yb[0], yb[1]); w.w = pk2(yb[2], yb[3]); *(u32x4*)(R + (size_t)row * DM + c) = w; }
;             s = wave_sum(s); if (lane == 0) rstd_out[row] = __builtin_amdgcn_rsqf(s * (1.0f / DM) + RMS_EPS); } }
	v_lshlrev_b32_e32 v106, 16, v54
	v_and_b32_e32 v107, 0xffff0000, v54
	v_lshlrev_b32_e32 v108, 16, v46
	v_and_b32_e32 v109, 0xffff0000, v46
	v_pk_mul_f32 v[106:107], v[96:97], v[106:107] op_sel_hi:[0,1]
	v_pk_fma_f32 v[98:99], v[2:3], v[106:107], v[108:109]
	v_lshlrev_b32_e32 v106, 16, v55
	v_and_b32_e32 v107, 0xffff0000, v55
	v_lshlrev_b32_e32 v108, 16, v47
	v_and_b32_e32 v109, 0xffff0000, v47
	v_pk_mul_f32 v[106:107], v[96:97], v[106:107] op_sel_hi:[0,1]
	v_pk_fma_f32 v[100:101], v[4:5], v[106:107], v[108:109]
	v_lshlrev_b32_e32 v106, 16, v56
	v_and_b32_e32 v107, 0xffff0000, v56
	v_lshlrev_b32_e32 v108, 16, v48
	v_and_b32_e32 v109, 0xffff0000, v48
	v_pk_mul_f32 v[106:107], v[96:97], v[106:107] op_sel_hi:[0,1]
	v_pk_fma_f32 v[102:103], v[6:7], v[106:107], v[108:109]
	v_lshlrev_b32_e32 v106, 16, v57
	v_and_b32_e32 v107, 0xffff0000, v57
	v_lshlrev_b32_e32 v108, 16, v49
	v_and_b32_e32 v109, 0xffff0000, v49
	v_pk_mul_f32 v[106:107], v[96:97], v[106:107] op_sel_hi:[0,1]
	v_pk_fma_f32 v[104:105], v[8:9], v[106:107], v[108:109]
	v_pk_fma_f32 v[110:111], v[98:99], v[98:99], v[110:111]
	v_pk_fma_f32 v[110:111], v[100:101], v[100:101], v[110:111]
	v_pk_fma_f32 v[110:111], v[102:103], v[102:103], v[110:111]
	v_pk_fma_f32 v[110:111], v[104:105], v[104:105], v[110:111]
	v_cvt_pk_bf16_f32 v46, v98, v99
	v_cvt_pk_bf16_f32 v47, v100, v101
	v_cvt_pk_bf16_f32 v48, v102, v103
	v_cvt_pk_bf16_f32 v49, v104, v105
	global_store_dwordx4 v19, v[46:49], s[4:5] offset:1024 nt
	v_add_f32_e32 v112, v110, v111
	v_add_u32_e32 v22, 0x2000, v22
	s_nop 1
	v_add_f32_dpp v112, v112, v112 quad_perm:[1,0,3,2] row_mask:0xf bank_mask:0xf
	s_nop 1
	v_add_f32_dpp v112, v112, v112 quad_perm:[2,3,0,1] row_mask:0xf bank_mask:0xf
	s_nop 1
	v_add_f32_dpp v112, v112, v112 row_half_mirror row_mask:0xf bank_mask:0xf
	s_nop 1
	v_add_f32_dpp v112, v112, v112 row_mirror row_mask:0xf bank_mask:0xf
	s_nop 1
	v_add_f32_dpp v112, v112, v112 row_bcast:15 row_mask:0xa bank_mask:0xf
	s_nop 1
	v_add_f32_dpp v112, v112, v112 row_bcast:31 row_mask:0xc bank_mask:0xf
	v_fmamk_f32 v113, v112, 0x3a800000, v244
	v_rsq_f32_e32 v113, v113
	s_mov_b64 exec, s[8:9]
	global_store_dword v22, v113, s[4:5]
	s_mov_b64 exec, -1
	v_add_u32_e32 v18, 0x400000, v18
	v_add_u32_e32 v20, 0x400000, v20
	v_add_u32_e32 v21, 0x2000, v21
	global_load_dwordx4 v[42:45], v18, s[4:5]
	global_load_dwordx4 v[50:53], v20, s[4:5]
	global_load_dwordx4 v[46:49], v18, s[4:5] offset:1024
	global_load_dwordx4 v[54:57], v20, s[4:5] offset:1024
	global_load_dword v58, v21, s[4:5]
	s_waitcnt vmcnt(24)
	v_fmamk_f32 v96, v76, 0x3a800000, v244
	v_rsq_f32_e32 v96, v96
	v_add_u32_e32 v19, 0x400000, v19
	v_lshlrev_b32_e32 v106, 16, v68
	v_and_b32_e32 v107, 0xffff0000, v68
	v_lshlrev_b32_e32 v108, 16, v60
	v_and_b32_e32 v109, 0xffff0000, v60
	v_pk_mul_f32 v[106:107], v[96:97], v[106:107] op_sel_hi:[0,1]
	v_pk_fma_f32 v[98:99], v[10:11], v[106:107], v[108:109]
	v_lshlrev_b32_e32 v106, 16, v69
	v_and_b32_e32 v107, 0xffff0000, v69
	v_lshlrev_b32_e32 v108, 16, v61
	v_and_b32_e32 v109, 0xffff0000, v61
	v_pk_mul_f32 v[106:107], v[96:97], v[106:107] op_sel_hi:[0,1]
	v_pk_fma_f32 v[100:101], v[12:13], v[106:107], v[108:109]
	v_lshlrev_b32_e32 v106, 16, v70
	v_and_b32_e32 v107, 0xffff0000, v70
	v_lshlrev_b32_e32 v108, 16, v62
	v_and_b32_e32 v109, 0xffff0000, v62
	v_pk_mul_f32 v[106:107], v[96:97], v[106:107] op_sel_hi:[0,1]
	v_pk_fma_f32 v[102:103], v[14:15], v[106:107], v[108:109]
	v_lshlrev_b32_e32 v106, 16, v71
	v_and_b32_e32 v107, 0xffff0000, v71
	v_lshlrev_b32_e32 v108, 16, v63
	v_and_b32_e32 v109, 0xffff0000, v63
	v_pk_mul_f32 v[106:107], v[96:97], v[106:107] op_sel_hi:[0,1]
	v_pk_fma_f32 v[104:105], v[16:17], v[106:107], v[108:109]
	v_pk_mul_f32 v[110:111], v[98:99], v[98:99]
	v_pk_fma_f32 v[110:111], v[100:101], v[100:101], v[110:111]
	v_pk_fma_f32 v[110:111], v[102:103], v[102:103], v[110:111]
	v_pk_fma_f32 v[110:111], v[104:105], v[104:105], v[110:111]
	v_cvt_pk_bf16_f32 v60, v98, v99
	v_cvt_pk_bf16_f32 v61, v100, v101
	v_cvt_pk_bf16_f32 v62, v102, v103
	v_cvt_pk_bf16_f32 v63, v104, v105
	global_store_dwordx4 v19, v[60:63], s[4:5] nt
	v_lshlrev_b32_e32 v106, 16, v72
	v_and_b32_e32 v107, 0xffff0000, v72
	v_lshlrev_b32_e32 v108, 16, v64
	v_and_b32_e32 v109, 0xffff0000, v64
	v_pk_mul_f32 v[106:107], v[96:97], v[106:107] op_sel_hi:[0,1]
	v_pk_fma_f32 v[98:99], v[2:3], v[106:107], v[108:109]
	v_lshlrev_b32_e32 v106, 16, v73
	v_and_b32_e32 v107, 0xffff0000, v73
	v_lshlrev_b32_e32 v108, 16, v65
	v_and_b32_e32 v109, 0xffff0000, v65
	v_pk_mul_f32 v[106:107], v[96:97], v[106:107] op_sel_hi:[0,1]
	v_pk_fma_f32 v[100:101], v[4:5], v[106:107], v[108:109]
	v_lshlrev_b32_e32 v106, 16, v74
	v_and_b32_e32 v107, 0xffff0000, v74
	v_lshlrev_b32_e32 v108, 16, v66
	v_and_b32_e32 v109, 0xffff0000, v66
	v_pk_mul_f32 v[106:107], v[96:97], v[106:107] op_sel_hi:[0,1]
	v_pk_fma_f32 v[102:103], v[6:7], v[106:107], v[108:109]
	v_lshlrev_b32_e32 v106, 16, v75
	v_and_b32_e32 v107, 0xffff0000, v75
	v_lshlrev_b32_e32 v108, 16, v67
	v_and_b32_e32 v109, 0xffff0000, v67
	v_pk_mul_f32 v[106:107], v[96:97], v[106:107] op_sel_hi:[0,1]
	v_pk_fma_f32 v[104:105], v[8:9], v[106:107], v[108:109]
	v_pk_fma_f32 v[110:111], v[98:99], v[98:99], v[110:111]
	v_pk_fma_f32 v[110:111], v[100:101], v[100:101], v[110:111]
	v_pk_fma_f32 v[110:111], v[102:103], v[102:103], v[110:111]
	v_pk_fma_f32 v[110:111], v[104:105], v[104:105], v[110:111]
	v_cvt_pk_bf16_f32 v64, v98, v99
	v_cvt_pk_bf16_f32 v65, v100, v101
	v_cvt_pk_bf16_f32 v66, v102, v103
	v_cvt_pk_bf16_f32 v67, v104, v105
	global_store_dwordx4 v19, v[64:67], s[4:5] offset:1024 nt
	v_add_f32_e32 v112, v110, v111
	v_add_u32_e32 v22, 0x2000, v22
	s_nop 1
	v_add_f32_dpp v112, v112, v112 quad_perm:[1,0,3,2] row_mask:0xf bank_mask:0xf
	s_nop 1
	v_add_f32_dpp v112, v112, v112 quad_perm:[2,3,0,1] row_mask:0xf bank_mask:0xf
	s_nop 1
	v_add_f32_dpp v112, v112, v112 row_half_mirror row_mask:0xf bank_mask:0xf
	s_nop 1
	v_add_f32_dpp v112, v112, v112 row_mirror row_mask:0xf bank_mask:0xf
	s_nop 1
	v_add_f32_dpp v112, v112, v112 row_bcast:15 row_mask:0xa bank_mask:0xf
	s_nop 1
	v_add_f32_dpp v112, v112, v112 row_bcast:31 row_mask:0xc bank_mask:0xf
	v_fmamk_f32 v113, v112, 0x3a800000, v244
	v_rsq_f32_e32 v113, v113
	s_mov_b64 exec, s[8:9]
	global_store_dword v22, v113, s[4:5]
	s_mov_b64 exec, -1
	v_add_u32_e32 v18, 0x400000, v18
	v_add_u32_e32 v20, 0x400000, v20
	v_add_u32_e32 v21, 0x2000, v21
	global_load_dwordx4 v[60:63], v18, s[4:5]
	global_load_dwordx4 v[68:71], v20, s[4:5]
	global_load_dwordx4 v[64:67], v18, s[4:5] offset:1024
	global_load_dwordx4 v[72:75], v20, s[4:5] offset:1024
	global_load_dword v76, v21, s[4:5]
	s_waitcnt vmcnt(24)
; __device__ __forceinline__ float bflo(unsigned w) { return __uint_as_float(w << 16); }
; __device__ __forceinline__ float bfhi(unsigned w) { return __uint_as_float(w & 0xffff0000u); }
; __device__ __forceinline__ void resid_rows(bf16_t* R, const bf16_t* Y, const float* ssqY, const float* g, float* rstd_out, float* outf, bool wf32, int row_lo, int row_hi, int yoff, int gw, int NGW, int lane) {
;     ...
;     for (int row0 = row_lo + gw; row0 < row_hi; row0 += RP * NGW) {
;         u32x4 rr[RP][2], oo[RP][2]; float ssv[RP];
; #pragma unroll
;         for (int k = 0; k < RP; ++k) { const int row = row0 + k * NGW; const bool ok = row < row_hi; const int rw = ok ? row : row0;
;             ssv[k] = ssqY[rw];
; #pragma unroll
;             for (int j = 0; j < 2; ++j) { const int c = 8 * lane + 512 * j; rr[k][j] = *(const u32x4*)(R + (size_t)rw * DM + c); oo[k][j] = *(const u32x4*)(Y + (size_t)(rw - yoff) * DM + c); } }
; #pragma unroll
;         for (int k = 0; k < RP; ++k) { const int row = row0 + k * NGW; if (row < row_hi) {
;             const float rs = __builtin_amdgcn_rsqf(ssv[k] * (1.0f / DM) + RMS_EPS); float s = 0.f;
; #pragma unroll
;             for (int j = 0; j < 2; ++j) { const int c = 8 * lane + 512 * j; const u32x4 r = rr[k][j], o = oo[k][j]; const f32x4 ga = gv[j][0], gb = gv[j][1];
;                 f32x4 ya, yb; ya[0] = bflo(r.x) + bflo(o.x) * rs * ga[0]; ya[1] = bfhi(r.x) + bfhi(o.x) * rs * ga[1]; ya[2] = bflo(r.y) + bflo(o.y) * rs * ga[2]; ya[3] = bfhi(r.y) + bfhi(o.y) * rs * ga[3];
;                 yb[0] = bflo(r.z) + bflo(o.z) * rs * gb[0]; yb[1] = bfhi(r.z) + bfhi(o.z) * rs * gb[1]; yb[2] = bflo(r.w) + bflo(o.w) * rs * gb[2]; yb[3] = bfhi(r.w) + bfhi(o.w) * rs * gb[3];
;                 if (wf32) { *(f32x4*)(outf + (size_t)row * DM + c) = ya; *(f32x4*)(outf + (size_t)row * DM + c + 4) = yb; }
;                 s += (ya[0] * ya[0] + ya[1] * ya[1]) + (ya[2] * ya[2] + ya[3] * ya[3]) + (yb[0] * yb[0] + yb[1] * yb[1]) + (yb[2] * yb[2] + yb[3] * yb[3]);
;                 u32x4 w; w.x = pk2(ya[0], ya[1]); w.y = pk2(ya[2], ya[3]); w.z = pk2(yb[0], yb[1]); w.w = pk2(yb[2], yb[3]); *(u32x4*)(R + (size_t)row * DM + c) = w; }
;             s = wave_sum(s); if (lane == 0) rstd_out[row] = __builtin_amdgcn_rsqf(s * (1.0f / DM) + RMS_EPS); } }
	v_fmamk_f32 v96, v94, 0x3a800000, v244
	v_rsq_f32_e32 v96, v96
	v_add_u32_e32 v19, 0x400000, v19
	v_lshlrev_b32_e32 v106, 16, v86
	v_and_b32_e32 v107, 0xffff0000, v86
	v_lshlrev_b32_e32 v108, 16, v78
	v_and_b32_e32 v109, 0xffff0000, v78
	v_pk_mul_f32 v[106:107], v[96:97], v[106:107] op_sel_hi:[0,1]
	v_pk_fma_f32 v[98:99], v[10:11], v[106:107], v[108:109]
	v_lshlrev_b32_e32 v106, 16, v87
	v_and_b32_e32 v107, 0xffff0000, v87
	v_lshlrev_b32_e32 v108, 16, v79
	v_and_b32_e32 v109, 0xffff0000, v79
	v_pk_mul_f32 v[106:107], v[96:97], v[106:107] op_sel_hi:[0,1]
	v_pk_fma_f32 v[100:101], v[12:13], v[106:107], v[108:109]
	v_lshlrev_b32_e32 v106, 16, v88
	v_and_b32_e32 v107, 0xffff0000, v88
	v_lshlrev_b32_e32 v108, 16, v80
	v_and_b32_e32 v109, 0xffff0000, v80
	v_pk_mul_f32 v[106:107], v[96:97], v[106:107] op_sel_hi:[0,1]
	v_pk_fma_f32 v[102:103], v[14:15], v[106:107], v[108:109]
	v_lshlrev_b32_e32 v106, 16, v89
	v_and_b32_e32 v107, 0xffff0000, v89
	v_lshlrev_b32_e32 v108, 16, v81
	v_and_b32_e32 v109, 0xffff0000, v81
	v_pk_mul_f32 v[106:107], v[96:97], v[106:107] op_sel_hi:[0,1]
	v_pk_fma_f32 v[104:105], v[16:17], v[106:107], v[108:109]
	v_pk_mul_f32 v[110:111], v[98:99], v[98:99]
	v_pk_fma_f32 v[110:111], v[100:101], v[100:101], v[110:111]
	v_pk_fma_f32 v[110:111], v[102:103], v[102:103], v[110:111]
	v_pk_fma_f32 v[110:111], v[104:105], v[104:105], v[110:111]
	v_cvt_pk_bf16_f32 v78, v98, v99
	v_cvt_pk_bf16_f32 v79, v100, v101
	v_cvt_pk_bf16_f32 v80, v102, v103
	v_cvt_pk_bf16_f32 v81, v104, v105
	global_store_dwordx4 v19, v[78:81], s[4:5] nt
	v_lshlrev_b32_e32 v106, 16, v90
	v_and_b32_e32 v107, 0xffff0000, v90
	v_lshlrev_b32_e32 v108, 16, v82
	v_and_b32_e32 v109, 0xffff0000, v82
	v_pk_mul_f32 v[106:107], v[96:97], v[106:107] op_sel_hi:[0,1]
	v_pk_fma_f32 v[98:99], v[2:3], v[106:107], v[108:109]
	v_lshlrev_b32_e32 v106, 16, v91
	v_and_b32_e32 v107, 0xffff0000, v91
	v_lshlrev_b32_e32 v108, 16, v83
	v_and_b32_e32 v109, 0xffff0000, v83
	v_pk_mul_f32 v[106:107], v[96:97], v[106:107] op_sel_hi:[0,1]
	v_pk_fma_f32 v[100:101], v[4:5], v[106:107], v[108:109]
	v_lshlrev_b32_e32 v106, 16, v92
	v_and_b32_e32 v107, 0xffff0000, v92
	v_lshlrev_b32_e32 v108, 16, v84
	v_and_b32_e32 v109, 0xffff0000, v84
	v_pk_mul_f32 v[106:107], v[96:97], v[106:107] op_sel_hi:[0,1]
	v_pk_fma_f32 v[102:103], v[6:7], v[106:107], v[108:109]
	v_lshlrev_b32_e32 v106, 16, v93
	v_and_b32_e32 v107, 0xffff0000, v93
	v_lshlrev_b32_e32 v108, 16, v85
	v_and_b32_e32 v109, 0xffff0000, v85
	v_pk_mul_f32 v[106:107], v[96:97], v[106:107] op_sel_hi:[0,1]
	v_pk_fma_f32 v[104:105], v[8:9], v[106:107], v[108:109]
	v_pk_fma_f32 v[110:111], v[98:99], v[98:99], v[110:111]
	v_pk_fma_f32 v[110:111], v[100:101], v[100:101], v[110:111]
	v_pk_fma_f32 v[110:111], v[102:103], v[102:103], v[110:111]
	v_pk_fma_f32 v[110:111], v[104:105], v[104:105], v[110:111]
	v_cvt_pk_bf16_f32 v82, v98, v99
	v_cvt_pk_bf16_f32 v83, v100, v101
	v_cvt_pk_bf16_f32 v84, v102, v103
	v_cvt_pk_bf16_f32 v85, v104, v105
	global_store_dwordx4 v19, v[82:85], s[4:5] offset:1024 nt
	v_add_f32_e32 v112, v110, v111
	v_add_u32_e32 v22, 0x2000, v22
	s_nop 1
	v_add_f32_dpp v112, v112, v112 quad_perm:[1,0,3,2] row_mask:0xf bank_mask:0xf
	s_nop 1
	v_add_f32_dpp v112, v112, v112 quad_perm:[2,3,0,1] row_mask:0xf bank_mask:0xf
	s_nop 1
	v_add_f32_dpp v112, v112, v112 row_half_mirror row_mask:0xf bank_mask:0xf
	s_nop 1
	v_add_f32_dpp v112, v112, v112 row_mirror row_mask:0xf bank_mask:0xf
	s_nop 1
	v_add_f32_dpp v112, v112, v112 row_bcast:15 row_mask:0xa bank_mask:0xf
	s_nop 1
	v_add_f32_dpp v112, v112, v112 row_bcast:31 row_mask:0xc bank_mask:0xf
	v_fmamk_f32 v113, v112, 0x3a800000, v244
	v_rsq_f32_e32 v113, v113
	s_mov_b64 exec, s[8:9]
	global_store_dword v22, v113, s[4:5]
	s_mov_b64 exec, -1
	v_add_u32_e32 v18, 0x400000, v18
	v_add_u32_e32 v20, 0x400000, v20
	v_add_u32_e32 v21, 0x2000, v21
	global_load_dwordx4 v[78:81], v18, s[4:5]
	global_load_dwordx4 v[86:89], v20, s[4:5]
	global_load_dwordx4 v[82:85], v18, s[4:5] offset:1024
	global_load_dwordx4 v[90:93], v20, s[4:5] offset:1024
	global_load_dword v94, v21, s[4:5]
	s_waitcnt vmcnt(24)
	v_fmamk_f32 v96, v40, 0x3a800000, v244
	v_rsq_f32_e32 v96, v96
	v_add_u32_e32 v19, 0x400000, v19
	v_lshlrev_b32_e32 v106, 16, v32
	v_and_b32_e32 v107, 0xffff0000, v32
	v_lshlrev_b32_e32 v108, 16, v24
	v_and_b32_e32 v109, 0xffff0000, v24
	v_pk_mul_f32 v[106:107], v[96:97], v[106:107] op_sel_hi:[0,1]
	v_pk_fma_f32 v[98:99], v[10:11], v[106:107], v[108:109]
	v_lshlrev_b32_e32 v106, 16, v33
	v_and_b32_e32 v107, 0xffff0000, v33
	v_lshlrev_b32_e32 v108, 16, v25
	v_and_b32_e32 v109, 0xffff0000, v25
	v_pk_mul_f32 v[106:107], v[96:97], v[106:107] op_sel_hi:[0,1]
	v_pk_fma_f32 v[100:101], v[12:13], v[106:107], v[108:109]
	v_lshlrev_b32_e32 v106, 16, v34
	v_and_b32_e32 v107, 0xffff0000, v34
	v_lshlrev_b32_e32 v108, 16, v26
	v_and_b32_e32 v109, 0xffff0000, v26
	v_pk_mul_f32 v[106:107], v[96:97], v[106:107] op_sel_hi:[0,1]
	v_pk_fma_f32 v[102:103], v[14:15], v[106:107], v[108:109]
	v_lshlrev_b32_e32 v106, 16, v35
	v_and_b32_e32 v107, 0xffff0000, v35
	v_lshlrev_b32_e32 v108, 16, v27
	v_and_b32_e32 v109, 0xffff0000, v27
	v_pk_mul_f32 v[106:107], v[96:97], v[106:107] op_sel_hi:[0,1]
	v_pk_fma_f32 v[104:105], v[16:17], v[106:107], v[108:109]
	v_pk_mul_f32 v[110:111], v[98:99], v[98:99]
	v_pk_fma_f32 v[110:111], v[100:101], v[100:101], v[110:111]
	v_pk_fma_f32 v[110:111], v[102:103], v[102:103], v[110:111]
	v_pk_fma_f32 v[110:111], v[104:105], v[104:105], v[110:111]
	v_cvt_pk_bf16_f32 v24, v98, v99
	v_cvt_pk_bf16_f32 v25, v100, v101
	v_cvt_pk_bf16_f32 v26, v102, v103
	v_cvt_pk_bf16_f32 v27, v104, v105
	global_store_dwordx4 v19, v[24:27], s[4:5] nt
; __device__ __forceinline__ float bflo(unsigned w) { return __uint_as_float(w << 16); }
; __device__ __forceinline__ float bfhi(unsigned w) { return __uint_as_float(w & 0xffff0000u); }
; __device__ __forceinline__ void resid_rows(bf16_t* R, const bf16_t* Y, const float* ssqY, const float* g, float* rstd_out, float* outf, bool wf32, int row_lo, int row_hi, int yoff, int gw, int NGW, int lane) {
;     ...
;     for (int row0 = row_lo + gw; row0 < row_hi; row0 += RP * NGW) {
;         u32x4 rr[RP][2], oo[RP][2]; float ssv[RP];
; #pragma unroll
;         for (int k = 0; k < RP; ++k) { const int row = row0 + k * NGW; const bool ok = row < row_hi; const int rw = ok ? row : row0;
;             ssv[k] = ssqY[rw];
; #pragma unroll
;             for (int j = 0; j < 2; ++j) { const int c = 8 * lane + 512 * j; rr[k][j] = *(const u32x4*)(R + (size_t)rw * DM + c); oo[k][j] = *(const u32x4*)(Y + (size_t)(rw - yoff) * DM + c); } }
; #pragma unroll
;         for (int k = 0; k < RP; ++k) { const int row = row0 + k * NGW; if (row < row_hi) {
;             const float rs = __builtin_amdgcn_rsqf(ssv[k] * (1.0f / DM) + RMS_EPS); float s = 0.f;
; #pragma unroll
;             for (int j = 0; j < 2; ++j) { const int c = 8 * lane + 512 * j; const u32x4 r = rr[k][j], o = oo[k][j]; const f32x4 ga = gv[j][0], gb = gv[j][1];
;                 f32x4 ya, yb; ya[0] = bflo(r.x) + bflo(o.x) * rs * ga[0]; ya[1] = bfhi(r.x) + bfhi(o.x) * rs * ga[1]; ya[2] = bflo(r.y) + bflo(o.y) * rs * ga[2]; ya[3] = bfhi(r.y) + bfhi(o.y) * rs * ga[3];
;                 yb[0] = bflo(r.z) + bflo(o.z) * rs * gb[0]; yb[1] = bfhi(r.z) + bfhi(o.z) * rs * gb[1]; yb[2] = bflo(r.w) + bflo(o.w) * rs * gb[2]; yb[3] = bfhi(r.w) + bfhi(o.w) * rs * gb[3];
;                 if (wf32) { *(f32x4*)(outf + (size_t)row * DM + c) = ya; *(f32x4*)(outf + (size_t)row * DM + c + 4) = yb; }
;                 s += (ya[0] * ya[0] + ya[1] * ya[1]) + (ya[2] * ya[2] + ya[3] * ya[3]) + (yb[0] * yb[0] + yb[1] * yb[1]) + (yb[2] * yb[2] + yb[3] * yb[3]);
;                 u32x4 w; w.x = pk2(ya[0], ya[1]); w.y = pk2(ya[2], ya[3]); w.z = pk2(yb[0], yb[1]); w.w = pk2(yb[2], yb[3]); *(u32x4*)(R + (size_t)row * DM + c) = w; }
;             s = wave_sum(s); if (lane == 0) rstd_out[row] = __builtin_amdgcn_rsqf(s * (1.0f / DM) + RMS_EPS); } }
	v_lshlrev_b32_e32 v106, 16, v36
	v_and_b32_e32 v107, 0xffff0000, v36
	v_lshlrev_b32_e32 v108, 16, v28
	v_and_b32_e32 v109, 0xffff0000, v28
	v_pk_mul_f32 v[106:107], v[96:97], v[106:107] op_sel_hi:[0,1]
	v_pk_fma_f32 v[98:99], v[2:3], v[106:107], v[108:109]
	v_lshlrev_b32_e32 v106, 16, v37
	v_and_b32_e32 v107, 0xffff0000, v37
	v_lshlrev_b32_e32 v108, 16, v29
	v_and_b32_e32 v109, 0xffff0000, v29
	v_pk_mul_f32 v[106:107], v[96:97], v[106:107] op_sel_hi:[0,1]
	v_pk_fma_f32 v[100:101], v[4:5], v[106:107], v[108:109]
	v_lshlrev_b32_e32 v106, 16, v38
	v_and_b32_e32 v107, 0xffff0000, v38
	v_lshlrev_b32_e32 v108, 16, v30
	v_and_b32_e32 v109, 0xffff0000, v30
	v_pk_mul_f32 v[106:107], v[96:97], v[106:107] op_sel_hi:[0,1]
	v_pk_fma_f32 v[102:103], v[6:7], v[106:107], v[108:109]
	v_lshlrev_b32_e32 v106, 16, v39
	v_and_b32_e32 v107, 0xffff0000, v39
	v_lshlrev_b32_e32 v108, 16, v31
	v_and_b32_e32 v109, 0xffff0000, v31
	v_pk_mul_f32 v[106:107], v[96:97], v[106:107] op_sel_hi:[0,1]
	v_pk_fma_f32 v[104:105], v[8:9], v[106:107], v[108:109]
	v_pk_fma_f32 v[110:111], v[98:99], v[98:99], v[110:111]
	v_pk_fma_f32 v[110:111], v[100:101], v[100:101], v[110:111]
	v_pk_fma_f32 v[110:111], v[102:103], v[102:103], v[110:111]
	v_pk_fma_f32 v[110:111], v[104:105], v[104:105], v[110:111]
	v_cvt_pk_bf16_f32 v28, v98, v99
	v_cvt_pk_bf16_f32 v29, v100, v101
	v_cvt_pk_bf16_f32 v30, v102, v103
	v_cvt_pk_bf16_f32 v31, v104, v105
	global_store_dwordx4 v19, v[28:31], s[4:5] offset:1024 nt
	v_add_f32_e32 v112, v110, v111
	v_add_u32_e32 v22, 0x2000, v22
	s_nop 1
	v_add_f32_dpp v112, v112, v112 quad_perm:[1,0,3,2] row_mask:0xf bank_mask:0xf
	s_nop 1
	v_add_f32_dpp v112, v112, v112 quad_perm:[2,3,0,1] row_mask:0xf bank_mask:0xf
	s_nop 1
	v_add_f32_dpp v112, v112, v112 row_half_mirror row_mask:0xf bank_mask:0xf
	s_nop 1
	v_add_f32_dpp v112, v112, v112 row_mirror row_mask:0xf bank_mask:0xf
	s_nop 1
	v_add_f32_dpp v112, v112, v112 row_bcast:15 row_mask:0xa bank_mask:0xf
	s_nop 1
	v_add_f32_dpp v112, v112, v112 row_bcast:31 row_mask:0xc bank_mask:0xf
	v_fmamk_f32 v113, v112, 0x3a800000, v244
	v_rsq_f32_e32 v113, v113
	s_mov_b64 exec, s[8:9]
	global_store_dword v22, v113, s[4:5]
	s_mov_b64 exec, -1
	s_waitcnt vmcnt(19)
	v_fmamk_f32 v96, v58, 0x3a800000, v244
	v_rsq_f32_e32 v96, v96
	v_add_u32_e32 v19, 0x400000, v19
	v_lshlrev_b32_e32 v106, 16, v50
	v_and_b32_e32 v107, 0xffff0000, v50
	v_lshlrev_b32_e32 v108, 16, v42
	v_and_b32_e32 v109, 0xffff0000, v42
	v_pk_mul_f32 v[106:107], v[96:97], v[106:107] op_sel_hi:[0,1]
	v_pk_fma_f32 v[98:99], v[10:11], v[106:107], v[108:109]
	v_lshlrev_b32_e32 v106, 16, v51
	v_and_b32_e32 v107, 0xffff0000, v51
	v_lshlrev_b32_e32 v108, 16, v43
	v_and_b32_e32 v109, 0xffff0000, v43
	v_pk_mul_f32 v[106:107], v[96:97], v[106:107] op_sel_hi:[0,1]
	v_pk_fma_f32 v[100:101], v[12:13], v[106:107], v[108:109]
	v_lshlrev_b32_e32 v106, 16, v52
	v_and_b32_e32 v107, 0xffff0000, v52
	v_lshlrev_b32_e32 v108, 16, v44
	v_and_b32_e32 v109, 0xffff0000, v44
	v_pk_mul_f32 v[106:107], v[96:97], v[106:107] op_sel_hi:[0,1]
	v_pk_fma_f32 v[102:103], v[14:15], v[106:107], v[108:109]
	v_lshlrev_b32_e32 v106, 16, v53
	v_and_b32_e32 v107, 0xffff0000, v53
	v_lshlrev_b32_e32 v108, 16, v45
	v_and_b32_e32 v109, 0xffff0000, v45
	v_pk_mul_f32 v[106:107], v[96:97], v[106:107] op_sel_hi:[0,1]
	v_pk_fma_f32 v[104:105], v[16:17], v[106:107], v[108:109]
	v_pk_mul_f32 v[110:111], v[98:99], v[98:99]
	v_pk_fma_f32 v[110:111], v[100:101], v[100:101], v[110:111]
	v_pk_fma_f32 v[110:111], v[102:103], v[102:103], v[110:111]
	v_pk_fma_f32 v[110:111], v[104:105], v[104:105], v[110:111]
	v_cvt_pk_bf16_f32 v42, v98, v99
	v_cvt_pk_bf16_f32 v43, v100, v101
	v_cvt_pk_bf16_f32 v44, v102, v103
	v_cvt_pk_bf16_f32 v45, v104, v105
	global_store_dwordx4 v19, v[42:45], s[4:5] nt
	v_lshlrev_b32_e32 v106, 16, v54
	v_and_b32_e32 v107, 0xffff0000, v54
	v_lshlrev_b32_e32 v108, 16, v46
	v_and_b32_e32 v109, 0xffff0000, v46
	v_pk_mul_f32 v[106:107], v[96:97], v[106:107] op_sel_hi:[0,1]
	v_pk_fma_f32 v[98:99], v[2:3], v[106:107], v[108:109]
	v_lshlrev_b32_e32 v106, 16, v55
	v_and_b32_e32 v107, 0xffff0000, v55
	v_lshlrev_b32_e32 v108, 16, v47
	v_and_b32_e32 v109, 0xffff0000, v47
	v_pk_mul_f32 v[106:107], v[96:97], v[106:107] op_sel_hi:[0,1]
	v_pk_fma_f32 v[100:101], v[4:5], v[106:107], v[108:109]
	v_lshlrev_b32_e32 v106, 16, v56
	v_and_b32_e32 v107, 0xffff0000, v56
	v_lshlrev_b32_e32 v108, 16, v48
	v_and_b32_e32 v109, 0xffff0000, v48
	v_pk_mul_f32 v[106:107], v[96:97], v[106:107] op_sel_hi:[0,1]
	v_pk_fma_f32 v[102:103], v[6:7], v[106:107], v[108:109]
	v_lshlrev_b32_e32 v106, 16, v57
	v_and_b32_e32 v107, 0xffff0000, v57
	v_lshlrev_b32_e32 v108, 16, v49
	v_and_b32_e32 v109, 0xffff0000, v49
	v_pk_mul_f32 v[106:107], v[96:97], v[106:107] op_sel_hi:[0,1]
	v_pk_fma_f32 v[104:105], v[8:9], v[106:107], v[108:109]
	v_pk_fma_f32 v[110:111], v[98:99], v[98:99], v[110:111]
	v_pk_fma_f32 v[110:111], v[100:101], v[100:101], v[110:111]
	v_pk_fma_f32 v[110:111], v[102:103], v[102:103], v[110:111]
	v_pk_fma_f32 v[110:111], v[104:105], v[104:105], v[110:111]
	v_cvt_pk_bf16_f32 v46, v98, v99
	v_cvt_pk_bf16_f32 v47, v100, v101
	v_cvt_pk_bf16_f32 v48, v102, v103
	v_cvt_pk_bf16_f32 v49, v104, v105
	global_store_dwordx4 v19, v[46:49], s[4:5] offset:1024 nt
	v_add_f32_e32 v112, v110, v111
	v_add_u32_e32 v22, 0x2000, v22
	s_nop 1
	v_add_f32_dpp v112, v112, v112 quad_perm:[1,0,3,2] row_mask:0xf bank_mask:0xf
	s_nop 1
	v_add_f32_dpp v112, v112, v112 quad_perm:[2,3,0,1] row_mask:0xf bank_mask:0xf
	s_nop 1
	v_add_f32_dpp v112, v112, v112 row_half_mirror row_mask:0xf bank_mask:0xf
	s_nop 1
	v_add_f32_dpp v112, v112, v112 row_mirror row_mask:0xf bank_mask:0xf
	s_nop 1
	v_add_f32_dpp v112, v112, v112 row_bcast:15 row_mask:0xa bank_mask:0xf
	s_nop 1
	v_add_f32_dpp v112, v112, v112 row_bcast:31 row_mask:0xc bank_mask:0xf
	v_fmamk_f32 v113, v112, 0x3a800000, v244
	v_rsq_f32_e32 v113, v113
	s_mov_b64 exec, s[8:9]
	global_store_dword v22, v113, s[4:5]
	s_mov_b64 exec, -1
	s_waitcnt vmcnt(14)
; __device__ __forceinline__ float bflo(unsigned w) { return __uint_as_float(w << 16); }
; __device__ __forceinline__ float bfhi(unsigned w) { return __uint_as_float(w & 0xffff0000u); }
; __device__ __forceinline__ void resid_rows(bf16_t* R, const bf16_t* Y, const float* ssqY, const float* g, float* rstd_out, float* outf, bool wf32, int row_lo, int row_hi, int yoff, int gw, int NGW, int lane) {
;     ...
;     for (int row0 = row_lo + gw; row0 < row_hi; row0 += RP * NGW) {
;         u32x4 rr[RP][2], oo[RP][2]; float ssv[RP];
; #pragma unroll
;         for (int k = 0; k < RP; ++k) { const int row = row0 + k * NGW; const bool ok = row < row_hi; const int rw = ok ? row : row0;
;             ssv[k] = ssqY[rw];
; #pragma unroll
;             for (int j = 0; j < 2; ++j) { const int c = 8 * lane + 512 * j; rr[k][j] = *(const u32x4*)(R + (size_t)rw * DM + c); oo[k][j] = *(const u32x4*)(Y + (size_t)(rw - yoff) * DM + c); } }
; #pragma unroll
;         for (int k = 0; k < RP; ++k) { const int row = row0 + k * NGW; if (row < row_hi) {
;             const float rs = __builtin_amdgcn_rsqf(ssv[k] * (1.0f / DM) + RMS_EPS); float s = 0.f;
; #pragma unroll
;             for (int j = 0; j < 2; ++j) { const int c = 8 * lane + 512 * j; const u32x4 r = rr[k][j], o = oo[k][j]; const f32x4 ga = gv[j][0], gb = gv[j][1];
;                 f32x4 ya, yb; ya[0] = bflo(r.x) + bflo(o.x) * rs * ga[0]; ya[1] = bfhi(r.x) + bfhi(o.x) * rs * ga[1]; ya[2] = bflo(r.y) + bflo(o.y) * rs * ga[2]; ya[3] = bfhi(r.y) + bfhi(o.y) * rs * ga[3];
;                 yb[0] = bflo(r.z) + bflo(o.z) * rs * gb[0]; yb[1] = bfhi(r.z) + bfhi(o.z) * rs * gb[1]; yb[2] = bflo(r.w) + bflo(o.w) * rs * gb[2]; yb[3] = bfhi(r.w) + bfhi(o.w) * rs * gb[3];
;                 if (wf32) { *(f32x4*)(outf + (size_t)row * DM + c) = ya; *(f32x4*)(outf + (size_t)row * DM + c + 4) = yb; }
;                 s += (ya[0] * ya[0] + ya[1] * ya[1]) + (ya[2] * ya[2] + ya[3] * ya[3]) + (yb[0] * yb[0] + yb[1] * yb[1]) + (yb[2] * yb[2] + yb[3] * yb[3]);
;                 u32x4 w; w.x = pk2(ya[0], ya[1]); w.y = pk2(ya[2], ya[3]); w.z = pk2(yb[0], yb[1]); w.w = pk2(yb[2], yb[3]); *(u32x4*)(R + (size_t)row * DM + c) = w; }
;             s = wave_sum(s); if (lane == 0) rstd_out[row] = __builtin_amdgcn_rsqf(s * (1.0f / DM) + RMS_EPS); } }
	v_fmamk_f32 v96, v76, 0x3a800000, v244
	v_rsq_f32_e32 v96, v96
	v_add_u32_e32 v19, 0x400000, v19
	v_lshlrev_b32_e32 v106, 16, v68
	v_and_b32_e32 v107, 0xffff0000, v68
	v_lshlrev_b32_e32 v108, 16, v60
	v_and_b32_e32 v109, 0xffff0000, v60
	v_pk_mul_f32 v[106:107], v[96:97], v[106:107] op_sel_hi:[0,1]
	v_pk_fma_f32 v[98:99], v[10:11], v[106:107], v[108:109]
	v_lshlrev_b32_e32 v106, 16, v69
	v_and_b32_e32 v107, 0xffff0000, v69
	v_lshlrev_b32_e32 v108, 16, v61
	v_and_b32_e32 v109, 0xffff0000, v61
	v_pk_mul_f32 v[106:107], v[96:97], v[106:107] op_sel_hi:[0,1]
	v_pk_fma_f32 v[100:101], v[12:13], v[106:107], v[108:109]
	v_lshlrev_b32_e32 v106, 16, v70
	v_and_b32_e32 v107, 0xffff0000, v70
	v_lshlrev_b32_e32 v108, 16, v62
	v_and_b32_e32 v109, 0xffff0000, v62
	v_pk_mul_f32 v[106:107], v[96:97], v[106:107] op_sel_hi:[0,1]
	v_pk_fma_f32 v[102:103], v[14:15], v[106:107], v[108:109]
	v_lshlrev_b32_e32 v106, 16, v71
	v_and_b32_e32 v107, 0xffff0000, v71
	v_lshlrev_b32_e32 v108, 16, v63
	v_and_b32_e32 v109, 0xffff0000, v63
	v_pk_mul_f32 v[106:107], v[96:97], v[106:107] op_sel_hi:[0,1]
	v_pk_fma_f32 v[104:105], v[16:17], v[106:107], v[108:109]
	v_pk_mul_f32 v[110:111], v[98:99], v[98:99]
	v_pk_fma_f32 v[110:111], v[100:101], v[100:101], v[110:111]
	v_pk_fma_f32 v[110:111], v[102:103], v[102:103], v[110:111]
	v_pk_fma_f32 v[110:111], v[104:105], v[104:105], v[110:111]
	v_cvt_pk_bf16_f32 v60, v98, v99
	v_cvt_pk_bf16_f32 v61, v100, v101
	v_cvt_pk_bf16_f32 v62, v102, v103
	v_cvt_pk_bf16_f32 v63, v104, v105
	global_store_dwordx4 v19, v[60:63], s[4:5] nt
	v_lshlrev_b32_e32 v106, 16, v72
	v_and_b32_e32 v107, 0xffff0000, v72
	v_lshlrev_b32_e32 v108, 16, v64
	v_and_b32_e32 v109, 0xffff0000, v64
	v_pk_mul_f32 v[106:107], v[96:97], v[106:107] op_sel_hi:[0,1]
	v_pk_fma_f32 v[98:99], v[2:3], v[106:107], v[108:109]
	v_lshlrev_b32_e32 v106, 16, v73
	v_and_b32_e32 v107, 0xffff0000, v73
	v_lshlrev_b32_e32 v108, 16, v65
	v_and_b32_e32 v109, 0xffff0000, v65
	v_pk_mul_f32 v[106:107], v[96:97], v[106:107] op_sel_hi:[0,1]
	v_pk_fma_f32 v[100:101], v[4:5], v[106:107], v[108:109]
	v_lshlrev_b32_e32 v106, 16, v74
	v_and_b32_e32 v107, 0xffff0000, v74
	v_lshlrev_b32_e32 v108, 16, v66
	v_and_b32_e32 v109, 0xffff0000, v66
	v_pk_mul_f32 v[106:107], v[96:97], v[106:107] op_sel_hi:[0,1]
	v_pk_fma_f32 v[102:103], v[6:7], v[106:107], v[108:109]
	v_lshlrev_b32_e32 v106, 16, v75
	v_and_b32_e32 v107, 0xffff0000, v75
	v_lshlrev_b32_e32 v108, 16, v67
	v_and_b32_e32 v109, 0xffff0000, v67
	v_pk_mul_f32 v[106:107], v[96:97], v[106:107] op_sel_hi:[0,1]
	v_pk_fma_f32 v[104:105], v[8:9], v[106:107], v[108:109]
	v_pk_fma_f32 v[110:111], v[98:99], v[98:99], v[110:111]
	v_pk_fma_f32 v[110:111], v[100:101], v[100:101], v[110:111]
	v_pk_fma_f32 v[110:111], v[102:103], v[102:103], v[110:111]
	v_pk_fma_f32 v[110:111], v[104:105], v[104:105], v[110:111]
	v_cvt_pk_bf16_f32 v64, v98, v99
	v_cvt_pk_bf16_f32 v65, v100, v101
	v_cvt_pk_bf16_f32 v66, v102, v103
	v_cvt_pk_bf16_f32 v67, v104, v105
	global_store_dwordx4 v19, v[64:67], s[4:5] offset:1024 nt
	v_add_f32_e32 v112, v110, v111
	v_add_u32_e32 v22, 0x2000, v22
	s_nop 1
	v_add_f32_dpp v112, v112, v112 quad_perm:[1,0,3,2] row_mask:0xf bank_mask:0xf
	s_nop 1
	v_add_f32_dpp v112, v112, v112 quad_perm:[2,3,0,1] row_mask:0xf bank_mask:0xf
	s_nop 1
	v_add_f32_dpp v112, v112, v112 row_half_mirror row_mask:0xf bank_mask:0xf
	s_nop 1
	v_add_f32_dpp v112, v112, v112 row_mirror row_mask:0xf bank_mask:0xf
	s_nop 1
	v_add_f32_dpp v112, v112, v112 row_bcast:15 row_mask:0xa bank_mask:0xf
	s_nop 1
	v_add_f32_dpp v112, v112, v112 row_bcast:31 row_mask:0xc bank_mask:0xf
	v_fmamk_f32 v113, v112, 0x3a800000, v244
	v_rsq_f32_e32 v113, v113
	s_mov_b64 exec, s[8:9]
	global_store_dword v22, v113, s[4:5]
	s_mov_b64 exec, -1
	s_waitcnt vmcnt(9)
	v_fmamk_f32 v96, v94, 0x3a800000, v244
	v_rsq_f32_e32 v96, v96
	v_add_u32_e32 v19, 0x400000, v19
	v_lshlrev_b32_e32 v106, 16, v86
	v_and_b32_e32 v107, 0xffff0000, v86
	v_lshlrev_b32_e32 v108, 16, v78
	v_and_b32_e32 v109, 0xffff0000, v78
	v_pk_mul_f32 v[106:107], v[96:97], v[106:107] op_sel_hi:[0,1]
	v_pk_fma_f32 v[98:99], v[10:11], v[106:107], v[108:109]
	v_lshlrev_b32_e32 v106, 16, v87
	v_and_b32_e32 v107, 0xffff0000, v87
	v_lshlrev_b32_e32 v108, 16, v79
	v_and_b32_e32 v109, 0xffff0000, v79
	v_pk_mul_f32 v[106:107], v[96:97], v[106:107] op_sel_hi:[0,1]
	v_pk_fma_f32 v[100:101], v[12:13], v[106:107], v[108:109]
	v_lshlrev_b32_e32 v106, 16, v88
	v_and_b32_e32 v107, 0xffff0000, v88
	v_lshlrev_b32_e32 v108, 16, v80
	v_and_b32_e32 v109, 0xffff0000, v80
	v_pk_mul_f32 v[106:107], v[96:97], v[106:107] op_sel_hi:[0,1]
	v_pk_fma_f32 v[102:103], v[14:15], v[106:107], v[108:109]
	v_lshlrev_b32_e32 v106, 16, v89
	v_and_b32_e32 v107, 0xffff0000, v89
	v_lshlrev_b32_e32 v108, 16, v81
	v_and_b32_e32 v109, 0xffff0000, v81
	v_pk_mul_f32 v[106:107], v[96:97], v[106:107] op_sel_hi:[0,1]
	v_pk_fma_f32 v[104:105], v[16:17], v[106:107], v[108:109]
	v_pk_mul_f32 v[110:111], v[98:99], v[98:99]
	v_pk_fma_f32 v[110:111], v[100:101], v[100:101], v[110:111]
	v_pk_fma_f32 v[110:111], v[102:103], v[102:103], v[110:111]
	v_pk_fma_f32 v[110:111], v[104:105], v[104:105], v[110:111]
	v_cvt_pk_bf16_f32 v78, v98, v99
	v_cvt_pk_bf16_f32 v79, v100, v101
	v_cvt_pk_bf16_f32 v80, v102, v103
	v_cvt_pk_bf16_f32 v81, v104, v105
	global_store_dwordx4 v19, v[78:81], s[4:5] nt
	v_lshlrev_b32_e32 v106, 16, v90
	v_and_b32_e32 v107, 0xffff0000, v90
	v_lshlrev_b32_e32 v108, 16, v82
	v_and_b32_e32 v109, 0xffff0000, v82
	v_pk_mul_f32 v[106:107], v[96:97], v[106:107] op_sel_hi:[0,1]
	v_pk_fma_f32 v[98:99], v[2:3], v[106:107], v[108:109]
	v_lshlrev_b32_e32 v106, 16, v91
	v_and_b32_e32 v107, 0xffff0000, v91
; #define LAS __attribute__((address_space(3)))
; __device__ __forceinline__ int otid() { int t = threadIdx.x; asm volatile("" : "+v"(t)); return t; }
; __device__ __forceinline__ unsigned xb_xcc_id() { return (unsigned)__builtin_amdgcn_s_getreg((3 << 11) | 20) & 0xFu; }
; #define PIN(i) karg_ptr(8 * (i))
; __device__ __forceinline__ void resid_rows(bf16_t* R, const bf16_t* Y, const float* ssqY, const float* g, float* rstd_out, float* outf, bool wf32, int row_lo, int row_hi, int yoff, int gw, int NGW, int lane) {
;     ...
;                 u32x4 w; w.x = pk2(ya[0], ya[1]); w.y = pk2(ya[2], ya[3]); w.z = pk2(yb[0], yb[1]); w.w = pk2(yb[2], yb[3]); *(u32x4*)(R + (size_t)row * DM + c) = w; }
;             s = wave_sum(s); if (lane == 0) rstd_out[row] = __builtin_amdgcn_rsqf(s * (1.0f / DM) + RMS_EPS); } }
; __global__ void __launch_bounds__(512, 2) fwd_megakernel(Params P) {
;     ...
;             const bool lastl = (l == NLAYER - 1);
;             { const int lane = otid() & 63, gw = bx * 8 + (otid() >> 6);
;               resid_rows(XB, FH1, ssqF, PIN(I_LNFPOST) + l * DM, rstdA, out, lastl, HALF_TOK, MTOK, HALF_TOK, gw, NGW, lane); }
;             if (lastl && (P.ph_hi - P.ph_lo > 1)) { XcdBarrier xb_; xb_.bar = (unsigned*)(ws + OFF_BAR); xb_.x = xb_xcc_id(); xb_.st = (volatile LAS unsigned*)(lds + LDS_BYTES - 16); xcd_barrier(xb_); }
;             { const int lane = otid() & 63, gw = bx * 8 + (otid() >> 6);
;               resid_rows(XB, FH0, ssqF, PIN(I_LNFPOST) + l * DM, rstdA, out, lastl, 0, HALF_TOK, 0, gw, NGW, lane); }
	v_lshlrev_b32_e32 v108, 16, v83
	v_and_b32_e32 v109, 0xffff0000, v83
	v_pk_mul_f32 v[106:107], v[96:97], v[106:107] op_sel_hi:[0,1]
	v_pk_fma_f32 v[100:101], v[4:5], v[106:107], v[108:109]
	v_lshlrev_b32_e32 v106, 16, v92
	v_and_b32_e32 v107, 0xffff0000, v92
	v_lshlrev_b32_e32 v108, 16, v84
	v_and_b32_e32 v109, 0xffff0000, v84
	v_pk_mul_f32 v[106:107], v[96:97], v[106:107] op_sel_hi:[0,1]
	v_pk_fma_f32 v[102:103], v[6:7], v[106:107], v[108:109]
	v_lshlrev_b32_e32 v106, 16, v93
	v_and_b32_e32 v107, 0xffff0000, v93
	v_lshlrev_b32_e32 v108, 16, v85
	v_and_b32_e32 v109, 0xffff0000, v85
	v_pk_mul_f32 v[106:107], v[96:97], v[106:107] op_sel_hi:[0,1]
	v_pk_fma_f32 v[104:105], v[8:9], v[106:107], v[108:109]
	v_pk_fma_f32 v[110:111], v[98:99], v[98:99], v[110:111]
	v_pk_fma_f32 v[110:111], v[100:101], v[100:101], v[110:111]
	v_pk_fma_f32 v[110:111], v[102:103], v[102:103], v[110:111]
	v_pk_fma_f32 v[110:111], v[104:105], v[104:105], v[110:111]
	v_cvt_pk_bf16_f32 v82, v98, v99
	v_cvt_pk_bf16_f32 v83, v100, v101
	v_cvt_pk_bf16_f32 v84, v102, v103
	v_cvt_pk_bf16_f32 v85, v104, v105
	global_store_dwordx4 v19, v[82:85], s[4:5] offset:1024 nt
	v_add_f32_e32 v112, v110, v111
	v_add_u32_e32 v22, 0x2000, v22
	s_nop 1
	v_add_f32_dpp v112, v112, v112 quad_perm:[1,0,3,2] row_mask:0xf bank_mask:0xf
	s_nop 1
	v_add_f32_dpp v112, v112, v112 quad_perm:[2,3,0,1] row_mask:0xf bank_mask:0xf
	s_nop 1
	v_add_f32_dpp v112, v112, v112 row_half_mirror row_mask:0xf bank_mask:0xf
	s_nop 1
	v_add_f32_dpp v112, v112, v112 row_mirror row_mask:0xf bank_mask:0xf
	s_nop 1
	v_add_f32_dpp v112, v112, v112 row_bcast:15 row_mask:0xa bank_mask:0xf
	s_nop 1
	v_add_f32_dpp v112, v112, v112 row_bcast:31 row_mask:0xc bank_mask:0xf
	v_fmamk_f32 v113, v112, 0x3a800000, v244
	v_rsq_f32_e32 v113, v113
	s_mov_b64 exec, s[8:9]
	global_store_dword v22, v113, s[4:5]
	s_mov_b64 exec, -1
	s_branch .LBB0_823
.Lrs2_last1:
	v_lshrrev_b32_e32 v114, 6, v0
	v_readlane_b32 s12, v255, 49
	v_readlane_b32 s13, v255, 4
	v_readfirstlane_b32 s18, v114
	s_load_dwordx2 s[4:5], s[0:1], 0x98
	s_load_dwordx2 s[10:11], s[0:1], 0x68
	s_load_dwordx2 s[6:7], s[0:1], 0x90
	s_add_i32 s13, s13, s18
	v_and_b32_e32 v115, 63, v0
	v_lshlrev_b32_e32 v114, 4, v115
	v_lshlrev_b32_e32 v115, 5, v115
	s_lshl_b32 s18, s12, 12
	s_lshl_b32 s19, s12, 18
	s_bfm_b64 s[8:9], 1, 63
	s_waitcnt lgkmcnt(0)
	s_add_u32 s10, s10, s18
	s_addc_u32 s11, s11, 0
	global_load_dwordx4 v[2:5], v115, s[10:11] offset:2048
	global_load_dwordx4 v[6:9], v115, s[10:11] offset:2064
	global_load_dwordx4 v[10:13], v115, s[10:11]
	global_load_dwordx4 v[14:17], v115, s[10:11] offset:16
	s_lshl_b32 s18, s13, 11
	v_add_u32_e32 v18, s18, v114
	v_mov_b32_e32 v19, v18
	v_mov_b32_e32 v20, v18
	s_lshl_b32 s18, s13, 2
	v_mov_b32_e32 v22, s18
	s_add_i32 s18, s18, s19
	v_mov_b32_e32 v21, s18
	s_lshl_b32 s18, s13, 12
	v_add_u32_e32 v23, s18, v115
	v_add_u32_e32 v18, 0x5001000, v18
	v_add_u32_e32 v21, 0x2d70000, v21
	global_load_dwordx4 v[24:27], v18, s[4:5]
	global_load_dwordx4 v[32:35], v20, s[6:7]
	global_load_dwordx4 v[28:31], v18, s[4:5] offset:1024
	global_load_dwordx4 v[36:39], v20, s[6:7] offset:1024
	global_load_dword v40, v21, s[4:5]
	v_add_u32_e32 v18, 0x400000, v18
	v_add_u32_e32 v20, 0x400000, v20
	v_add_u32_e32 v21, 0x2000, v21
	global_load_dwordx4 v[42:45], v18, s[4:5]
	global_load_dwordx4 v[50:53], v20, s[6:7]
	global_load_dwordx4 v[46:49], v18, s[4:5] offset:1024
	global_load_dwordx4 v[54:57], v20, s[6:7] offset:1024
	global_load_dword v58, v21, s[4:5]
	v_add_u32_e32 v18, 0x400000, v18
	v_add_u32_e32 v20, 0x400000, v20
	v_add_u32_e32 v21, 0x2000, v21
	global_load_dwordx4 v[60:63], v18, s[4:5]
	global_load_dwordx4 v[68:71], v20, s[6:7]
	global_load_dwordx4 v[64:67], v18, s[4:5] offset:1024
	global_load_dwordx4 v[72:75], v20, s[6:7] offset:1024
	global_load_dword v76, v21, s[4:5]
	v_add_u32_e32 v18, 0x400000, v18
	v_add_u32_e32 v20, 0x400000, v20
	v_add_u32_e32 v21, 0x2000, v21
	global_load_dwordx4 v[78:81], v18, s[4:5]
	global_load_dwordx4 v[86:89], v20, s[6:7]
	global_load_dwordx4 v[82:85], v18, s[4:5] offset:1024
	global_load_dwordx4 v[90:93], v20, s[6:7] offset:1024
	global_load_dword v94, v21, s[4:5]
	s_waitcnt vmcnt(15)
	v_fmamk_f32 v96, v40, 0x3a800000, v244
	v_rsq_f32_e32 v96, v96
	v_add_u32_e32 v19, 0x5001000, v19
	v_add_u32_e32 v23, 0x4000000, v23
	v_lshlrev_b32_e32 v106, 16, v32
	v_and_b32_e32 v107, 0xffff0000, v32
	v_lshlrev_b32_e32 v108, 16, v24
	v_and_b32_e32 v109, 0xffff0000, v24
	v_pk_mul_f32 v[106:107], v[96:97], v[106:107] op_sel_hi:[0,1]
	v_pk_fma_f32 v[98:99], v[10:11], v[106:107], v[108:109]
	v_lshlrev_b32_e32 v106, 16, v33
	v_and_b32_e32 v107, 0xffff0000, v33
	v_lshlrev_b32_e32 v108, 16, v25
	v_and_b32_e32 v109, 0xffff0000, v25
	v_pk_mul_f32 v[106:107], v[96:97], v[106:107] op_sel_hi:[0,1]
	v_pk_fma_f32 v[100:101], v[12:13], v[106:107], v[108:109]
	v_lshlrev_b32_e32 v106, 16, v34
	v_and_b32_e32 v107, 0xffff0000, v34
	v_lshlrev_b32_e32 v108, 16, v26
	v_and_b32_e32 v109, 0xffff0000, v26
	v_pk_mul_f32 v[106:107], v[96:97], v[106:107] op_sel_hi:[0,1]
	v_pk_fma_f32 v[102:103], v[14:15], v[106:107], v[108:109]
	v_lshlrev_b32_e32 v106, 16, v35
	v_and_b32_e32 v107, 0xffff0000, v35
	v_lshlrev_b32_e32 v108, 16, v27
	v_and_b32_e32 v109, 0xffff0000, v27
	v_pk_mul_f32 v[106:107], v[96:97], v[106:107] op_sel_hi:[0,1]
	v_pk_fma_f32 v[104:105], v[16:17], v[106:107], v[108:109]
	global_store_dwordx4 v23, v[98:101], s[6:7] nt
	global_store_dwordx4 v23, v[102:105], s[6:7] offset:16 nt
	v_lshlrev_b32_e32 v106, 16, v36
	v_and_b32_e32 v107, 0xffff0000, v36
	v_lshlrev_b32_e32 v108, 16, v28
	v_and_b32_e32 v109, 0xffff0000, v28
	v_pk_mul_f32 v[106:107], v[96:97], v[106:107] op_sel_hi:[0,1]
	v_pk_fma_f32 v[98:99], v[2:3], v[106:107], v[108:109]
	v_lshlrev_b32_e32 v106, 16, v37
	v_and_b32_e32 v107, 0xffff0000, v37
	v_lshlrev_b32_e32 v108, 16, v29
	v_and_b32_e32 v109, 0xffff0000, v29
	v_pk_mul_f32 v[106:107], v[96:97], v[106:107] op_sel_hi:[0,1]
	v_pk_fma_f32 v[100:101], v[4:5], v[106:107], v[108:109]
	v_lshlrev_b32_e32 v106, 16, v38
	v_and_b32_e32 v107, 0xffff0000, v38
	v_lshlrev_b32_e32 v108, 16, v30
	v_and_b32_e32 v109, 0xffff0000, v30
	v_pk_mul_f32 v[106:107], v[96:97], v[106:107] op_sel_hi:[0,1]
	v_pk_fma_f32 v[102:103], v[6:7], v[106:107], v[108:109]
	v_lshlrev_b32_e32 v106, 16, v39
	v_and_b32_e32 v107, 0xffff0000, v39
	v_lshlrev_b32_e32 v108, 16, v31
	v_and_b32_e32 v109, 0xffff0000, v31
	v_pk_mul_f32 v[106:107], v[96:97], v[106:107] op_sel_hi:[0,1]
	v_pk_fma_f32 v[104:105], v[8:9], v[106:107], v[108:109]
	global_store_dwordx4 v23, v[98:101], s[6:7] offset:2048 nt
	global_store_dwordx4 v23, v[102:105], s[6:7] offset:2064 nt
	v_add_u32_e32 v18, 0x400000, v18
	v_add_u32_e32 v20, 0x400000, v20
	v_add_u32_e32 v21, 0x2000, v21
	global_load_dwordx4 v[24:27], v18, s[4:5]
	global_load_dwordx4 v[32:35], v20, s[6:7]
	global_load_dwordx4 v[28:31], v18, s[4:5] offset:1024
	global_load_dwordx4 v[36:39], v20, s[6:7] offset:1024
	global_load_dword v40, v21, s[4:5]
	s_waitcnt vmcnt(19)
; __device__ __forceinline__ float bflo(unsigned w) { return __uint_as_float(w << 16); }
; __device__ __forceinline__ float bfhi(unsigned w) { return __uint_as_float(w & 0xffff0000u); }
; __device__ __forceinline__ void resid_rows(bf16_t* R, const bf16_t* Y, const float* ssqY, const float* g, float* rstd_out, float* outf, bool wf32, int row_lo, int row_hi, int yoff, int gw, int NGW, int lane) {
;     ...
;             const float rs = __builtin_amdgcn_rsqf(ssv[k] * (1.0f / DM) + RMS_EPS); float s = 0.f;
; #pragma unroll
;             for (int j = 0; j < 2; ++j) { const int c = 8 * lane + 512 * j; const u32x4 r = rr[k][j], o = oo[k][j]; const f32x4 ga = gv[j][0], gb = gv[j][1];
;                 f32x4 ya, yb; ya[0] = bflo(r.x) + bflo(o.x) * rs * ga[0]; ya[1] = bfhi(r.x) + bfhi(o.x) * rs * ga[1]; ya[2] = bflo(r.y) + bflo(o.y) * rs * ga[2]; ya[3] = bfhi(r.y) + bfhi(o.y) * rs * ga[3];
;                 yb[0] = bflo(r.z) + bflo(o.z) * rs * gb[0]; yb[1] = bfhi(r.z) + bfhi(o.z) * rs * gb[1]; yb[2] = bflo(r.w) + bflo(o.w) * rs * gb[2]; yb[3] = bfhi(r.w) + bfhi(o.w) * rs * gb[3];
;                 if (wf32) { *(f32x4*)(outf + (size_t)row * DM + c) = ya; *(f32x4*)(outf + (size_t)row * DM + c + 4) = yb; }
	v_fmamk_f32 v96, v58, 0x3a800000, v244
	v_rsq_f32_e32 v96, v96
	v_add_u32_e32 v19, 0x400000, v19
	v_add_u32_e32 v23, 0x800000, v23
	v_lshlrev_b32_e32 v106, 16, v50
	v_and_b32_e32 v107, 0xffff0000, v50
	v_lshlrev_b32_e32 v108, 16, v42
	v_and_b32_e32 v109, 0xffff0000, v42
	v_pk_mul_f32 v[106:107], v[96:97], v[106:107] op_sel_hi:[0,1]
	v_pk_fma_f32 v[98:99], v[10:11], v[106:107], v[108:109]
	v_lshlrev_b32_e32 v106, 16, v51
	v_and_b32_e32 v107, 0xffff0000, v51
	v_lshlrev_b32_e32 v108, 16, v43
	v_and_b32_e32 v109, 0xffff0000, v43
	v_pk_mul_f32 v[106:107], v[96:97], v[106:107] op_sel_hi:[0,1]
	v_pk_fma_f32 v[100:101], v[12:13], v[106:107], v[108:109]
	v_lshlrev_b32_e32 v106, 16, v52
	v_and_b32_e32 v107, 0xffff0000, v52
	v_lshlrev_b32_e32 v108, 16, v44
	v_and_b32_e32 v109, 0xffff0000, v44
	v_pk_mul_f32 v[106:107], v[96:97], v[106:107] op_sel_hi:[0,1]
	v_pk_fma_f32 v[102:103], v[14:15], v[106:107], v[108:109]
	v_lshlrev_b32_e32 v106, 16, v53
	v_and_b32_e32 v107, 0xffff0000, v53
	v_lshlrev_b32_e32 v108, 16, v45
	v_and_b32_e32 v109, 0xffff0000, v45
	v_pk_mul_f32 v[106:107], v[96:97], v[106:107] op_sel_hi:[0,1]
	v_pk_fma_f32 v[104:105], v[16:17], v[106:107], v[108:109]
	global_store_dwordx4 v23, v[98:101], s[6:7] nt
	global_store_dwordx4 v23, v[102:105], s[6:7] offset:16 nt
	v_lshlrev_b32_e32 v106, 16, v54
	v_and_b32_e32 v107, 0xffff0000, v54
	v_lshlrev_b32_e32 v108, 16, v46
	v_and_b32_e32 v109, 0xffff0000, v46
	v_pk_mul_f32 v[106:107], v[96:97], v[106:107] op_sel_hi:[0,1]
	v_pk_fma_f32 v[98:99], v[2:3], v[106:107], v[108:109]
	v_lshlrev_b32_e32 v106, 16, v55
	v_and_b32_e32 v107, 0xffff0000, v55
	v_lshlrev_b32_e32 v108, 16, v47
	v_and_b32_e32 v109, 0xffff0000, v47
	v_pk_mul_f32 v[106:107], v[96:97], v[106:107] op_sel_hi:[0,1]
	v_pk_fma_f32 v[100:101], v[4:5], v[106:107], v[108:109]
	v_lshlrev_b32_e32 v106, 16, v56
	v_and_b32_e32 v107, 0xffff0000, v56
	v_lshlrev_b32_e32 v108, 16, v48
	v_and_b32_e32 v109, 0xffff0000, v48
	v_pk_mul_f32 v[106:107], v[96:97], v[106:107] op_sel_hi:[0,1]
	v_pk_fma_f32 v[102:103], v[6:7], v[106:107], v[108:109]
	v_lshlrev_b32_e32 v106, 16, v57
	v_and_b32_e32 v107, 0xffff0000, v57
	v_lshlrev_b32_e32 v108, 16, v49
	v_and_b32_e32 v109, 0xffff0000, v49
	v_pk_mul_f32 v[106:107], v[96:97], v[106:107] op_sel_hi:[0,1]
	v_pk_fma_f32 v[104:105], v[8:9], v[106:107], v[108:109]
	global_store_dwordx4 v23, v[98:101], s[6:7] offset:2048 nt
	global_store_dwordx4 v23, v[102:105], s[6:7] offset:2064 nt
	v_add_u32_e32 v18, 0x400000, v18
	v_add_u32_e32 v20, 0x400000, v20
	v_add_u32_e32 v21, 0x2000, v21
	global_load_dwordx4 v[42:45], v18, s[4:5]
	global_load_dwordx4 v[50:53], v20, s[6:7]
	global_load_dwordx4 v[46:49], v18, s[4:5] offset:1024
	global_load_dwordx4 v[54:57], v20, s[6:7] offset:1024
	global_load_dword v58, v21, s[4:5]
	s_waitcnt vmcnt(23)
	v_fmamk_f32 v96, v76, 0x3a800000, v244
	v_rsq_f32_e32 v96, v96
	v_add_u32_e32 v19, 0x400000, v19
	v_add_u32_e32 v23, 0x800000, v23
	v_lshlrev_b32_e32 v106, 16, v68
	v_and_b32_e32 v107, 0xffff0000, v68
	v_lshlrev_b32_e32 v108, 16, v60
	v_and_b32_e32 v109, 0xffff0000, v60
	v_pk_mul_f32 v[106:107], v[96:97], v[106:107] op_sel_hi:[0,1]
	v_pk_fma_f32 v[98:99], v[10:11], v[106:107], v[108:109]
	v_lshlrev_b32_e32 v106, 16, v69
	v_and_b32_e32 v107, 0xffff0000, v69
	v_lshlrev_b32_e32 v108, 16, v61
	v_and_b32_e32 v109, 0xffff0000, v61
	v_pk_mul_f32 v[106:107], v[96:97], v[106:107] op_sel_hi:[0,1]
	v_pk_fma_f32 v[100:101], v[12:13], v[106:107], v[108:109]
	v_lshlrev_b32_e32 v106, 16, v70
	v_and_b32_e32 v107, 0xffff0000, v70
	v_lshlrev_b32_e32 v108, 16, v62
	v_and_b32_e32 v109, 0xffff0000, v62
	v_pk_mul_f32 v[106:107], v[96:97], v[106:107] op_sel_hi:[0,1]
	v_pk_fma_f32 v[102:103], v[14:15], v[106:107], v[108:109]
	v_lshlrev_b32_e32 v106, 16, v71
	v_and_b32_e32 v107, 0xffff0000, v71
	v_lshlrev_b32_e32 v108, 16, v63
	v_and_b32_e32 v109, 0xffff0000, v63
	v_pk_mul_f32 v[106:107], v[96:97], v[106:107] op_sel_hi:[0,1]
	v_pk_fma_f32 v[104:105], v[16:17], v[106:107], v[108:109]
	global_store_dwordx4 v23, v[98:101], s[6:7] nt
	global_store_dwordx4 v23, v[102:105], s[6:7] offset:16 nt
	v_lshlrev_b32_e32 v106, 16, v72
	v_and_b32_e32 v107, 0xffff0000, v72
	v_lshlrev_b32_e32 v108, 16, v64
	v_and_b32_e32 v109, 0xffff0000, v64
	v_pk_mul_f32 v[106:107], v[96:97], v[106:107] op_sel_hi:[0,1]
	v_pk_fma_f32 v[98:99], v[2:3], v[106:107], v[108:109]
	v_lshlrev_b32_e32 v106, 16, v73
	v_and_b32_e32 v107, 0xffff0000, v73
	v_lshlrev_b32_e32 v108, 16, v65
	v_and_b32_e32 v109, 0xffff0000, v65
	v_pk_mul_f32 v[106:107], v[96:97], v[106:107] op_sel_hi:[0,1]
	v_pk_fma_f32 v[100:101], v[4:5], v[106:107], v[108:109]
	v_lshlrev_b32_e32 v106, 16, v74
	v_and_b32_e32 v107, 0xffff0000, v74
	v_lshlrev_b32_e32 v108, 16, v66
	v_and_b32_e32 v109, 0xffff0000, v66
	v_pk_mul_f32 v[106:107], v[96:97], v[106:107] op_sel_hi:[0,1]
	v_pk_fma_f32 v[102:103], v[6:7], v[106:107], v[108:109]
	v_lshlrev_b32_e32 v106, 16, v75
	v_and_b32_e32 v107, 0xffff0000, v75
	v_lshlrev_b32_e32 v108, 16, v67
	v_and_b32_e32 v109, 0xffff0000, v67
	v_pk_mul_f32 v[106:107], v[96:97], v[106:107] op_sel_hi:[0,1]
	v_pk_fma_f32 v[104:105], v[8:9], v[106:107], v[108:109]
	global_store_dwordx4 v23, v[98:101], s[6:7] offset:2048 nt
	global_store_dwordx4 v23, v[102:105], s[6:7] offset:2064 nt
	v_add_u32_e32 v18, 0x400000, v18
	v_add_u32_e32 v20, 0x400000, v20
	v_add_u32_e32 v21, 0x2000, v21
	global_load_dwordx4 v[60:63], v18, s[4:5]
	global_load_dwordx4 v[68:71], v20, s[6:7]
	global_load_dwordx4 v[64:67], v18, s[4:5] offset:1024
	global_load_dwordx4 v[72:75], v20, s[6:7] offset:1024
	global_load_dword v76, v21, s[4:5]
	s_waitcnt vmcnt(27)
; __device__ __forceinline__ float bflo(unsigned w) { return __uint_as_float(w << 16); }
; __device__ __forceinline__ float bfhi(unsigned w) { return __uint_as_float(w & 0xffff0000u); }
; __device__ __forceinline__ void resid_rows(bf16_t* R, const bf16_t* Y, const float* ssqY, const float* g, float* rstd_out, float* outf, bool wf32, int row_lo, int row_hi, int yoff, int gw, int NGW, int lane) {
;     ...
;             const float rs = __builtin_amdgcn_rsqf(ssv[k] * (1.0f / DM) + RMS_EPS); float s = 0.f;
; #pragma unroll
;             for (int j = 0; j < 2; ++j) { const int c = 8 * lane + 512 * j; const u32x4 r = rr[k][j], o = oo[k][j]; const f32x4 ga = gv[j][0], gb = gv[j][1];
;                 f32x4 ya, yb; ya[0] = bflo(r.x) + bflo(o.x) * rs * ga[0]; ya[1] = bfhi(r.x) + bfhi(o.x) * rs * ga[1]; ya[2] = bflo(r.y) + bflo(o.y) * rs * ga[2]; ya[3] = bfhi(r.y) + bfhi(o.y) * rs * ga[3];
;                 yb[0] = bflo(r.z) + bflo(o.z) * rs * gb[0]; yb[1] = bfhi(r.z) + bfhi(o.z) * rs * gb[1]; yb[2] = bflo(r.w) + bflo(o.w) * rs * gb[2]; yb[3] = bfhi(r.w) + bfhi(o.w) * rs * gb[3];
;                 if (wf32) { *(f32x4*)(outf + (size_t)row * DM + c) = ya; *(f32x4*)(outf + (size_t)row * DM + c + 4) = yb; }
	v_fmamk_f32 v96, v94, 0x3a800000, v244
	v_rsq_f32_e32 v96, v96
	v_add_u32_e32 v19, 0x400000, v19
	v_add_u32_e32 v23, 0x800000, v23
	v_lshlrev_b32_e32 v106, 16, v86
	v_and_b32_e32 v107, 0xffff0000, v86
	v_lshlrev_b32_e32 v108, 16, v78
	v_and_b32_e32 v109, 0xffff0000, v78
	v_pk_mul_f32 v[106:107], v[96:97], v[106:107] op_sel_hi:[0,1]
	v_pk_fma_f32 v[98:99], v[10:11], v[106:107], v[108:109]
	v_lshlrev_b32_e32 v106, 16, v87
	v_and_b32_e32 v107, 0xffff0000, v87
	v_lshlrev_b32_e32 v108, 16, v79
	v_and_b32_e32 v109, 0xffff0000, v79
	v_pk_mul_f32 v[106:107], v[96:97], v[106:107] op_sel_hi:[0,1]
	v_pk_fma_f32 v[100:101], v[12:13], v[106:107], v[108:109]
	v_lshlrev_b32_e32 v106, 16, v88
	v_and_b32_e32 v107, 0xffff0000, v88
	v_lshlrev_b32_e32 v108, 16, v80
	v_and_b32_e32 v109, 0xffff0000, v80
	v_pk_mul_f32 v[106:107], v[96:97], v[106:107] op_sel_hi:[0,1]
	v_pk_fma_f32 v[102:103], v[14:15], v[106:107], v[108:109]
	v_lshlrev_b32_e32 v106, 16, v89
	v_and_b32_e32 v107, 0xffff0000, v89
	v_lshlrev_b32_e32 v108, 16, v81
	v_and_b32_e32 v109, 0xffff0000, v81
	v_pk_mul_f32 v[106:107], v[96:97], v[106:107] op_sel_hi:[0,1]
	v_pk_fma_f32 v[104:105], v[16:17], v[106:107], v[108:109]
	global_store_dwordx4 v23, v[98:101], s[6:7] nt
	global_store_dwordx4 v23, v[102:105], s[6:7] offset:16 nt
	v_lshlrev_b32_e32 v106, 16, v90
	v_and_b32_e32 v107, 0xffff0000, v90
	v_lshlrev_b32_e32 v108, 16, v82
	v_and_b32_e32 v109, 0xffff0000, v82
	v_pk_mul_f32 v[106:107], v[96:97], v[106:107] op_sel_hi:[0,1]
	v_pk_fma_f32 v[98:99], v[2:3], v[106:107], v[108:109]
	v_lshlrev_b32_e32 v106, 16, v91
	v_and_b32_e32 v107, 0xffff0000, v91
	v_lshlrev_b32_e32 v108, 16, v83
	v_and_b32_e32 v109, 0xffff0000, v83
	v_pk_mul_f32 v[106:107], v[96:97], v[106:107] op_sel_hi:[0,1]
	v_pk_fma_f32 v[100:101], v[4:5], v[106:107], v[108:109]
	v_lshlrev_b32_e32 v106, 16, v92
	v_and_b32_e32 v107, 0xffff0000, v92
	v_lshlrev_b32_e32 v108, 16, v84
	v_and_b32_e32 v109, 0xffff0000, v84
	v_pk_mul_f32 v[106:107], v[96:97], v[106:107] op_sel_hi:[0,1]
	v_pk_fma_f32 v[102:103], v[6:7], v[106:107], v[108:109]
	v_lshlrev_b32_e32 v106, 16, v93
	v_and_b32_e32 v107, 0xffff0000, v93
	v_lshlrev_b32_e32 v108, 16, v85
	v_and_b32_e32 v109, 0xffff0000, v85
	v_pk_mul_f32 v[106:107], v[96:97], v[106:107] op_sel_hi:[0,1]
	v_pk_fma_f32 v[104:105], v[8:9], v[106:107], v[108:109]
	global_store_dwordx4 v23, v[98:101], s[6:7] offset:2048 nt
	global_store_dwordx4 v23, v[102:105], s[6:7] offset:2064 nt
	v_add_u32_e32 v18, 0x400000, v18
	v_add_u32_e32 v20, 0x400000, v20
	v_add_u32_e32 v21, 0x2000, v21
	global_load_dwordx4 v[78:81], v18, s[4:5]
	global_load_dwordx4 v[86:89], v20, s[6:7]
	global_load_dwordx4 v[82:85], v18, s[4:5] offset:1024
	global_load_dwordx4 v[90:93], v20, s[6:7] offset:1024
	global_load_dword v94, v21, s[4:5]
	s_waitcnt vmcnt(27)
	v_fmamk_f32 v96, v40, 0x3a800000, v244
	v_rsq_f32_e32 v96, v96
	v_add_u32_e32 v19, 0x400000, v19
	v_add_u32_e32 v23, 0x800000, v23
	v_lshlrev_b32_e32 v106, 16, v32
	v_and_b32_e32 v107, 0xffff0000, v32
	v_lshlrev_b32_e32 v108, 16, v24
	v_and_b32_e32 v109, 0xffff0000, v24
	v_pk_mul_f32 v[106:107], v[96:97], v[106:107] op_sel_hi:[0,1]
	v_pk_fma_f32 v[98:99], v[10:11], v[106:107], v[108:109]
	v_lshlrev_b32_e32 v106, 16, v33
	v_and_b32_e32 v107, 0xffff0000, v33
	v_lshlrev_b32_e32 v108, 16, v25
	v_and_b32_e32 v109, 0xffff0000, v25
	v_pk_mul_f32 v[106:107], v[96:97], v[106:107] op_sel_hi:[0,1]
	v_pk_fma_f32 v[100:101], v[12:13], v[106:107], v[108:109]
	v_lshlrev_b32_e32 v106, 16, v34
	v_and_b32_e32 v107, 0xffff0000, v34
	v_lshlrev_b32_e32 v108, 16, v26
	v_and_b32_e32 v109, 0xffff0000, v26
	v_pk_mul_f32 v[106:107], v[96:97], v[106:107] op_sel_hi:[0,1]
	v_pk_fma_f32 v[102:103], v[14:15], v[106:107], v[108:109]
	v_lshlrev_b32_e32 v106, 16, v35
	v_and_b32_e32 v107, 0xffff0000, v35
	v_lshlrev_b32_e32 v108, 16, v27
	v_and_b32_e32 v109, 0xffff0000, v27
	v_pk_mul_f32 v[106:107], v[96:97], v[106:107] op_sel_hi:[0,1]
	v_pk_fma_f32 v[104:105], v[16:17], v[106:107], v[108:109]
	global_store_dwordx4 v23, v[98:101], s[6:7] nt
	global_store_dwordx4 v23, v[102:105], s[6:7] offset:16 nt
	v_lshlrev_b32_e32 v106, 16, v36
	v_and_b32_e32 v107, 0xffff0000, v36
	v_lshlrev_b32_e32 v108, 16, v28
	v_and_b32_e32 v109, 0xffff0000, v28
	v_pk_mul_f32 v[106:107], v[96:97], v[106:107] op_sel_hi:[0,1]
	v_pk_fma_f32 v[98:99], v[2:3], v[106:107], v[108:109]
	v_lshlrev_b32_e32 v106, 16, v37
	v_and_b32_e32 v107, 0xffff0000, v37
	v_lshlrev_b32_e32 v108, 16, v29
	v_and_b32_e32 v109, 0xffff0000, v29
	v_pk_mul_f32 v[106:107], v[96:97], v[106:107] op_sel_hi:[0,1]
	v_pk_fma_f32 v[100:101], v[4:5], v[106:107], v[108:109]
	v_lshlrev_b32_e32 v106, 16, v38
	v_and_b32_e32 v107, 0xffff0000, v38
	v_lshlrev_b32_e32 v108, 16, v30
	v_and_b32_e32 v109, 0xffff0000, v30
	v_pk_mul_f32 v[106:107], v[96:97], v[106:107] op_sel_hi:[0,1]
	v_pk_fma_f32 v[102:103], v[6:7], v[106:107], v[108:109]
	v_lshlrev_b32_e32 v106, 16, v39
	v_and_b32_e32 v107, 0xffff0000, v39
	v_lshlrev_b32_e32 v108, 16, v31
	v_and_b32_e32 v109, 0xffff0000, v31
	v_pk_mul_f32 v[106:107], v[96:97], v[106:107] op_sel_hi:[0,1]
	v_pk_fma_f32 v[104:105], v[8:9], v[106:107], v[108:109]
	global_store_dwordx4 v23, v[98:101], s[6:7] offset:2048 nt
	global_store_dwordx4 v23, v[102:105], s[6:7] offset:2064 nt
	s_waitcnt vmcnt(22)
; __device__ __forceinline__ float bflo(unsigned w) { return __uint_as_float(w << 16); }
; __device__ __forceinline__ float bfhi(unsigned w) { return __uint_as_float(w & 0xffff0000u); }
; __device__ __forceinline__ void resid_rows(bf16_t* R, const bf16_t* Y, const float* ssqY, const float* g, float* rstd_out, float* outf, bool wf32, int row_lo, int row_hi, int yoff, int gw, int NGW, int lane) {
;     ...
;         for (int k = 0; k < RP; ++k) { const int row = row0 + k * NGW; if (row < row_hi) {
;             const float rs = __builtin_amdgcn_rsqf(ssv[k] * (1.0f / DM) + RMS_EPS); float s = 0.f;
; #pragma unroll
;             for (int j = 0; j < 2; ++j) { const int c = 8 * lane + 512 * j; const u32x4 r = rr[k][j], o = oo[k][j]; const f32x4 ga = gv[j][0], gb = gv[j][1];
;                 f32x4 ya, yb; ya[0] = bflo(r.x) + bflo(o.x) * rs * ga[0]; ya[1] = bfhi(r.x) + bfhi(o.x) * rs * ga[1]; ya[2] = bflo(r.y) + bflo(o.y) * rs * ga[2]; ya[3] = bfhi(r.y) + bfhi(o.y) * rs * ga[3];
;                 yb[0] = bflo(r.z) + bflo(o.z) * rs * gb[0]; yb[1] = bfhi(r.z) + bfhi(o.z) * rs * gb[1]; yb[2] = bflo(r.w) + bflo(o.w) * rs * gb[2]; yb[3] = bfhi(r.w) + bfhi(o.w) * rs * gb[3];
;                 if (wf32) { *(f32x4*)(outf + (size_t)row * DM + c) = ya; *(f32x4*)(outf + (size_t)row * DM + c + 4) = yb; }
;                 s += (ya[0] * ya[0] + ya[1] * ya[1]) + (ya[2] * ya[2] + ya[3] * ya[3]) + (yb[0] * yb[0] + yb[1] * yb[1]) + (yb[2] * yb[2] + yb[3] * yb[3]);
;                 u32x4 w; w.x = pk2(ya[0], ya[1]); w.y = pk2(ya[2], ya[3]); w.z = pk2(yb[0], yb[1]); w.w = pk2(yb[2], yb[3]); *(u32x4*)(R + (size_t)row * DM + c) = w; }
	v_fmamk_f32 v96, v58, 0x3a800000, v244
	v_rsq_f32_e32 v96, v96
	v_add_u32_e32 v19, 0x400000, v19
	v_add_u32_e32 v23, 0x800000, v23
	v_lshlrev_b32_e32 v106, 16, v50
	v_and_b32_e32 v107, 0xffff0000, v50
	v_lshlrev_b32_e32 v108, 16, v42
	v_and_b32_e32 v109, 0xffff0000, v42
	v_pk_mul_f32 v[106:107], v[96:97], v[106:107] op_sel_hi:[0,1]
	v_pk_fma_f32 v[98:99], v[10:11], v[106:107], v[108:109]
	v_lshlrev_b32_e32 v106, 16, v51
	v_and_b32_e32 v107, 0xffff0000, v51
	v_lshlrev_b32_e32 v108, 16, v43
	v_and_b32_e32 v109, 0xffff0000, v43
	v_pk_mul_f32 v[106:107], v[96:97], v[106:107] op_sel_hi:[0,1]
	v_pk_fma_f32 v[100:101], v[12:13], v[106:107], v[108:109]
	v_lshlrev_b32_e32 v106, 16, v52
	v_and_b32_e32 v107, 0xffff0000, v52
	v_lshlrev_b32_e32 v108, 16, v44
	v_and_b32_e32 v109, 0xffff0000, v44
	v_pk_mul_f32 v[106:107], v[96:97], v[106:107] op_sel_hi:[0,1]
	v_pk_fma_f32 v[102:103], v[14:15], v[106:107], v[108:109]
	v_lshlrev_b32_e32 v106, 16, v53
	v_and_b32_e32 v107, 0xffff0000, v53
	v_lshlrev_b32_e32 v108, 16, v45
	v_and_b32_e32 v109, 0xffff0000, v45
	v_pk_mul_f32 v[106:107], v[96:97], v[106:107] op_sel_hi:[0,1]
	v_pk_fma_f32 v[104:105], v[16:17], v[106:107], v[108:109]
	global_store_dwordx4 v23, v[98:101], s[6:7] nt
	global_store_dwordx4 v23, v[102:105], s[6:7] offset:16 nt
	v_lshlrev_b32_e32 v106, 16, v54
	v_and_b32_e32 v107, 0xffff0000, v54
	v_lshlrev_b32_e32 v108, 16, v46
	v_and_b32_e32 v109, 0xffff0000, v46
	v_pk_mul_f32 v[106:107], v[96:97], v[106:107] op_sel_hi:[0,1]
	v_pk_fma_f32 v[98:99], v[2:3], v[106:107], v[108:109]
	v_lshlrev_b32_e32 v106, 16, v55
	v_and_b32_e32 v107, 0xffff0000, v55
	v_lshlrev_b32_e32 v108, 16, v47
	v_and_b32_e32 v109, 0xffff0000, v47
	v_pk_mul_f32 v[106:107], v[96:97], v[106:107] op_sel_hi:[0,1]
	v_pk_fma_f32 v[100:101], v[4:5], v[106:107], v[108:109]
	v_lshlrev_b32_e32 v106, 16, v56
	v_and_b32_e32 v107, 0xffff0000, v56
	v_lshlrev_b32_e32 v108, 16, v48
	v_and_b32_e32 v109, 0xffff0000, v48
	v_pk_mul_f32 v[106:107], v[96:97], v[106:107] op_sel_hi:[0,1]
	v_pk_fma_f32 v[102:103], v[6:7], v[106:107], v[108:109]
	v_lshlrev_b32_e32 v106, 16, v57
	v_and_b32_e32 v107, 0xffff0000, v57
	v_lshlrev_b32_e32 v108, 16, v49
	v_and_b32_e32 v109, 0xffff0000, v49
	v_pk_mul_f32 v[106:107], v[96:97], v[106:107] op_sel_hi:[0,1]
	v_pk_fma_f32 v[104:105], v[8:9], v[106:107], v[108:109]
	global_store_dwordx4 v23, v[98:101], s[6:7] offset:2048 nt
	global_store_dwordx4 v23, v[102:105], s[6:7] offset:2064 nt
	s_waitcnt vmcnt(17)
; __device__ __forceinline__ float bflo(unsigned w) { return __uint_as_float(w << 16); }
; __device__ __forceinline__ float bfhi(unsigned w) { return __uint_as_float(w & 0xffff0000u); }
; __device__ __forceinline__ void resid_rows(bf16_t* R, const bf16_t* Y, const float* ssqY, const float* g, float* rstd_out, float* outf, bool wf32, int row_lo, int row_hi, int yoff, int gw, int NGW, int lane) {
;     ...
;         for (int k = 0; k < RP; ++k) { const int row = row0 + k * NGW; if (row < row_hi) {
;             const float rs = __builtin_amdgcn_rsqf(ssv[k] * (1.0f / DM) + RMS_EPS); float s = 0.f;
; #pragma unroll
;             for (int j = 0; j < 2; ++j) { const int c = 8 * lane + 512 * j; const u32x4 r = rr[k][j], o = oo[k][j]; const f32x4 ga = gv[j][0], gb = gv[j][1];
;                 f32x4 ya, yb; ya[0] = bflo(r.x) + bflo(o.x) * rs * ga[0]; ya[1] = bfhi(r.x) + bfhi(o.x) * rs * ga[1]; ya[2] = bflo(r.y) + bflo(o.y) * rs * ga[2]; ya[3] = bfhi(r.y) + bfhi(o.y) * rs * ga[3];
;                 yb[0] = bflo(r.z) + bflo(o.z) * rs * gb[0]; yb[1] = bfhi(r.z) + bfhi(o.z) * rs * gb[1]; yb[2] = bflo(r.w) + bflo(o.w) * rs * gb[2]; yb[3] = bfhi(r.w) + bfhi(o.w) * rs * gb[3];
;                 if (wf32) { *(f32x4*)(outf + (size_t)row * DM + c) = ya; *(f32x4*)(outf + (size_t)row * DM + c + 4) = yb; }
;                 s += (ya[0] * ya[0] + ya[1] * ya[1]) + (ya[2] * ya[2] + ya[3] * ya[3]) + (yb[0] * yb[0] + yb[1] * yb[1]) + (yb[2] * yb[2] + yb[3] * yb[3]);
;                 u32x4 w; w.x = pk2(ya[0], ya[1]); w.y = pk2(ya[2], ya[3]); w.z = pk2(yb[0], yb[1]); w.w = pk2(yb[2], yb[3]); *(u32x4*)(R + (size_t)row * DM + c) = w; }
	v_fmamk_f32 v96, v76, 0x3a800000, v244
	v_rsq_f32_e32 v96, v96
	v_add_u32_e32 v19, 0x400000, v19
	v_add_u32_e32 v23, 0x800000, v23
	v_lshlrev_b32_e32 v106, 16, v68
	v_and_b32_e32 v107, 0xffff0000, v68
	v_lshlrev_b32_e32 v108, 16, v60
	v_and_b32_e32 v109, 0xffff0000, v60
	v_pk_mul_f32 v[106:107], v[96:97], v[106:107] op_sel_hi:[0,1]
	v_pk_fma_f32 v[98:99], v[10:11], v[106:107], v[108:109]
	v_lshlrev_b32_e32 v106, 16, v69
	v_and_b32_e32 v107, 0xffff0000, v69
	v_lshlrev_b32_e32 v108, 16, v61
	v_and_b32_e32 v109, 0xffff0000, v61
	v_pk_mul_f32 v[106:107], v[96:97], v[106:107] op_sel_hi:[0,1]
	v_pk_fma_f32 v[100:101], v[12:13], v[106:107], v[108:109]
	v_lshlrev_b32_e32 v106, 16, v70
	v_and_b32_e32 v107, 0xffff0000, v70
	v_lshlrev_b32_e32 v108, 16, v62
	v_and_b32_e32 v109, 0xffff0000, v62
	v_pk_mul_f32 v[106:107], v[96:97], v[106:107] op_sel_hi:[0,1]
	v_pk_fma_f32 v[102:103], v[14:15], v[106:107], v[108:109]
	v_lshlrev_b32_e32 v106, 16, v71
	v_and_b32_e32 v107, 0xffff0000, v71
	v_lshlrev_b32_e32 v108, 16, v63
	v_and_b32_e32 v109, 0xffff0000, v63
	v_pk_mul_f32 v[106:107], v[96:97], v[106:107] op_sel_hi:[0,1]
	v_pk_fma_f32 v[104:105], v[16:17], v[106:107], v[108:109]
	global_store_dwordx4 v23, v[98:101], s[6:7] nt
	global_store_dwordx4 v23, v[102:105], s[6:7] offset:16 nt
	v_lshlrev_b32_e32 v106, 16, v72
	v_and_b32_e32 v107, 0xffff0000, v72
	v_lshlrev_b32_e32 v108, 16, v64
	v_and_b32_e32 v109, 0xffff0000, v64
	v_pk_mul_f32 v[106:107], v[96:97], v[106:107] op_sel_hi:[0,1]
	v_pk_fma_f32 v[98:99], v[2:3], v[106:107], v[108:109]
	v_lshlrev_b32_e32 v106, 16, v73
	v_and_b32_e32 v107, 0xffff0000, v73
	v_lshlrev_b32_e32 v108, 16, v65
	v_and_b32_e32 v109, 0xffff0000, v65
	v_pk_mul_f32 v[106:107], v[96:97], v[106:107] op_sel_hi:[0,1]
	v_pk_fma_f32 v[100:101], v[4:5], v[106:107], v[108:109]
	v_lshlrev_b32_e32 v106, 16, v74
	v_and_b32_e32 v107, 0xffff0000, v74
	v_lshlrev_b32_e32 v108, 16, v66
	v_and_b32_e32 v109, 0xffff0000, v66
	v_pk_mul_f32 v[106:107], v[96:97], v[106:107] op_sel_hi:[0,1]
	v_pk_fma_f32 v[102:103], v[6:7], v[106:107], v[108:109]
	v_lshlrev_b32_e32 v106, 16, v75
	v_and_b32_e32 v107, 0xffff0000, v75
	v_lshlrev_b32_e32 v108, 16, v67
	v_and_b32_e32 v109, 0xffff0000, v67
	v_pk_mul_f32 v[106:107], v[96:97], v[106:107] op_sel_hi:[0,1]
	v_pk_fma_f32 v[104:105], v[8:9], v[106:107], v[108:109]
	global_store_dwordx4 v23, v[98:101], s[6:7] offset:2048 nt
	global_store_dwordx4 v23, v[102:105], s[6:7] offset:2064 nt
	s_waitcnt vmcnt(12)
	v_fmamk_f32 v96, v94, 0x3a800000, v244
	v_rsq_f32_e32 v96, v96
	v_add_u32_e32 v19, 0x400000, v19
	v_add_u32_e32 v23, 0x800000, v23
	v_lshlrev_b32_e32 v106, 16, v86
	v_and_b32_e32 v107, 0xffff0000, v86
	v_lshlrev_b32_e32 v108, 16, v78
	v_and_b32_e32 v109, 0xffff0000, v78
	v_pk_mul_f32 v[106:107], v[96:97], v[106:107] op_sel_hi:[0,1]
	v_pk_fma_f32 v[98:99], v[10:11], v[106:107], v[108:109]
	v_lshlrev_b32_e32 v106, 16, v87
	v_and_b32_e32 v107, 0xffff0000, v87
	v_lshlrev_b32_e32 v108, 16, v79
	v_and_b32_e32 v109, 0xffff0000, v79
	v_pk_mul_f32 v[106:107], v[96:97], v[106:107] op_sel_hi:[0,1]
	v_pk_fma_f32 v[100:101], v[12:13], v[106:107], v[108:109]
	v_lshlrev_b32_e32 v106, 16, v88
	v_and_b32_e32 v107, 0xffff0000, v88
	v_lshlrev_b32_e32 v108, 16, v80
	v_and_b32_e32 v109, 0xffff0000, v80
	v_pk_mul_f32 v[106:107], v[96:97], v[106:107] op_sel_hi:[0,1]
	v_pk_fma_f32 v[102:103], v[14:15], v[106:107], v[108:109]
	v_lshlrev_b32_e32 v106, 16, v89
	v_and_b32_e32 v107, 0xffff0000, v89
	v_lshlrev_b32_e32 v108, 16, v81
	v_and_b32_e32 v109, 0xffff0000, v81
	v_pk_mul_f32 v[106:107], v[96:97], v[106:107] op_sel_hi:[0,1]
	v_pk_fma_f32 v[104:105], v[16:17], v[106:107], v[108:109]
	global_store_dwordx4 v23, v[98:101], s[6:7] nt
	global_store_dwordx4 v23, v[102:105], s[6:7] offset:16 nt
	v_lshlrev_b32_e32 v106, 16, v90
	v_and_b32_e32 v107, 0xffff0000, v90
	v_lshlrev_b32_e32 v108, 16, v82
	v_and_b32_e32 v109, 0xffff0000, v82
	v_pk_mul_f32 v[106:107], v[96:97], v[106:107] op_sel_hi:[0,1]
	v_pk_fma_f32 v[98:99], v[2:3], v[106:107], v[108:109]
	v_lshlrev_b32_e32 v106, 16, v91
	v_and_b32_e32 v107, 0xffff0000, v91
	v_lshlrev_b32_e32 v108, 16, v83
	v_and_b32_e32 v109, 0xffff0000, v83
	v_pk_mul_f32 v[106:107], v[96:97], v[106:107] op_sel_hi:[0,1]
	v_pk_fma_f32 v[100:101], v[4:5], v[106:107], v[108:109]
	v_lshlrev_b32_e32 v106, 16, v92
	v_and_b32_e32 v107, 0xffff0000, v92
	v_lshlrev_b32_e32 v108, 16, v84
	v_and_b32_e32 v109, 0xffff0000, v84
	v_pk_mul_f32 v[106:107], v[96:97], v[106:107] op_sel_hi:[0,1]
	v_pk_fma_f32 v[102:103], v[6:7], v[106:107], v[108:109]
	v_lshlrev_b32_e32 v106, 16, v93
	v_and_b32_e32 v107, 0xffff0000, v93
	v_lshlrev_b32_e32 v108, 16, v85
	v_and_b32_e32 v109, 0xffff0000, v85
	v_pk_mul_f32 v[106:107], v[96:97], v[106:107] op_sel_hi:[0,1]
	v_pk_fma_f32 v[104:105], v[8:9], v[106:107], v[108:109]
	global_store_dwordx4 v23, v[98:101], s[6:7] offset:2048 nt
	global_store_dwordx4 v23, v[102:105], s[6:7] offset:2064 nt

; __device__ __forceinline__ float bflo(unsigned w) { return __uint_as_float(w << 16); }
; #define PIN(i) karg_ptr(8 * (i))
; __device__ __forceinline__ void resid_rows(bf16_t* R, const bf16_t* Y, const float* ssqY, const float* g, float* rstd_out, float* outf, bool wf32, int row_lo, int row_hi, int yoff, int gw, int NGW, int lane) {
;     ...
;     for (int row0 = row_lo + gw; row0 < row_hi; row0 += RP * NGW) {
;         u32x4 rr[RP][2], oo[RP][2]; float ssv[RP];
; #pragma unroll
;         for (int k = 0; k < RP; ++k) { const int row = row0 + k * NGW; const bool ok = row < row_hi; const int rw = ok ? row : row0;
;             ssv[k] = ssqY[rw];
; #pragma unroll
;             for (int j = 0; j < 2; ++j) { const int c = 8 * lane + 512 * j; rr[k][j] = *(const u32x4*)(R + (size_t)rw * DM + c); oo[k][j] = *(const u32x4*)(Y + (size_t)(rw - yoff) * DM + c); } }
; #pragma unroll
;         for (int k = 0; k < RP; ++k) { const int row = row0 + k * NGW; if (row < row_hi) {
;             const float rs = __builtin_amdgcn_rsqf(ssv[k] * (1.0f / DM) + RMS_EPS); float s = 0.f;
; #pragma unroll
;             for (int j = 0; j < 2; ++j) { const int c = 8 * lane + 512 * j; const u32x4 r = rr[k][j], o = oo[k][j]; const f32x4 ga = gv[j][0], gb = gv[j][1];
;                 f32x4 ya, yb; ya[0] = bflo(r.x) + bflo(o.x) * rs * ga[0]; ya[1] = bfhi(r.x) + bfhi(o.x) * rs * ga[1]; ya[2] = bflo(r.y) + bflo(o.y) * rs * ga[2]; ya[3] = bfhi(r.y) + bfhi(o.y) * rs * ga[3];
;                 yb[0] = bflo(r.z) + bflo(o.z) * rs * gb[0]; yb[1] = bfhi(r.z) + bfhi(o.z) * rs * gb[1]; yb[2] = bflo(r.w) + bflo(o.w) * rs * gb[2]; yb[3] = bfhi(r.w) + bfhi(o.w) * rs * gb[3];
;                 if (wf32) { *(f32x4*)(outf + (size_t)row * DM + c) = ya; *(f32x4*)(outf + (size_t)row * DM + c + 4) = yb; }
;                 s += (ya[0] * ya[0] + ya[1] * ya[1]) + (ya[2] * ya[2] + ya[3] * ya[3]) + (yb[0] * yb[0] + yb[1] * yb[1]) + (yb[2] * yb[2] + yb[3] * yb[3]);
;                 u32x4 w; w.x = pk2(ya[0], ya[1]); w.y = pk2(ya[2], ya[3]); w.z = pk2(yb[0], yb[1]); w.w = pk2(yb[2], yb[3]); *(u32x4*)(R + (size_t)row * DM + c) = w; }
; __global__ void __launch_bounds__(512, 2) fwd_megakernel(Params P) {
;     ...
;             { const int lane = otid() & 63, gw = bx * 8 + (otid() >> 6);
;               resid_rows(XB, FH0, ssqF, PIN(I_LNFPOST) + l * DM, rstdA, out, lastl, 0, HALF_TOK, 0, gw, NGW, lane); }
.LBB0_877:
	v_mov_b32_e32 v2, v0
	v_mov_b32_e32 v3, v0
	v_readlane_b32 s4, v255, 4
	v_ashrrev_i32_e32 v18, 6, v3
	s_mov_b64 s[6:7], s[0:1]
	v_add_u32_e32 v86, s4, v18
	s_mov_b64 s[4:5], s[0:1]
	s_mov_b64 s[10:11], s[0:1]
	s_mov_b64 s[12:13], s[0:1]
	s_mov_b64 s[8:9], s[0:1]
	v_cmp_gt_i32_e32 vcc, s47, v86
	s_and_saveexec_b64 s[16:17], vcc
	s_cbranch_execz .LBB0_907
	v_readlane_b32 s12, v255, 49
	s_cmp_eq_u32 s12, 1
	s_cbranch_scc0 .LBB0_907
	v_lshrrev_b32_e32 v114, 6, v0
	v_readlane_b32 s12, v255, 49
	v_readlane_b32 s13, v255, 4
	v_readfirstlane_b32 s18, v114
	s_load_dwordx2 s[4:5], s[0:1], 0x98
	s_load_dwordx2 s[10:11], s[0:1], 0x68
	s_load_dwordx2 s[6:7], s[0:1], 0x90
	s_add_i32 s13, s13, s18
	v_and_b32_e32 v115, 63, v0
	v_lshlrev_b32_e32 v114, 4, v115
	v_lshlrev_b32_e32 v115, 5, v115
	s_lshl_b32 s18, s12, 12
	s_lshl_b32 s19, s12, 18
	s_bfm_b64 s[8:9], 1, 63
	s_waitcnt lgkmcnt(0)
	s_add_u32 s10, s10, s18
	s_addc_u32 s11, s11, 0
	global_load_dwordx4 v[2:5], v115, s[10:11] offset:2048
	global_load_dwordx4 v[6:9], v115, s[10:11] offset:2064
	global_load_dwordx4 v[10:13], v115, s[10:11]
	global_load_dwordx4 v[14:17], v115, s[10:11] offset:16
	s_lshl_b32 s18, s13, 11
	v_add_u32_e32 v18, s18, v114
	v_mov_b32_e32 v19, v18
	v_mov_b32_e32 v20, v18
	s_lshl_b32 s18, s13, 2
	v_mov_b32_e32 v22, s18
	s_add_i32 s18, s18, s19
	v_mov_b32_e32 v21, s18
	s_lshl_b32 s18, s13, 12
	v_add_u32_e32 v23, s18, v115
	v_add_u32_e32 v18, 0x3001000, v18
	v_add_u32_e32 v20, 0xd000000, v20
	v_add_u32_e32 v21, 0x2d60000, v21
	global_load_dwordx4 v[24:27], v18, s[4:5]
	global_load_dwordx4 v[32:35], v20, s[4:5]
	global_load_dwordx4 v[28:31], v18, s[4:5] offset:1024
	global_load_dwordx4 v[36:39], v20, s[4:5] offset:1024
	global_load_dword v40, v21, s[4:5]
	v_add_u32_e32 v18, 0x400000, v18
	v_add_u32_e32 v20, 0x400000, v20
	v_add_u32_e32 v21, 0x2000, v21
	global_load_dwordx4 v[42:45], v18, s[4:5]
	global_load_dwordx4 v[50:53], v20, s[4:5]
	global_load_dwordx4 v[46:49], v18, s[4:5] offset:1024
	global_load_dwordx4 v[54:57], v20, s[4:5] offset:1024
	global_load_dword v58, v21, s[4:5]
	v_add_u32_e32 v18, 0x400000, v18
	v_add_u32_e32 v20, 0x400000, v20
	v_add_u32_e32 v21, 0x2000, v21
	global_load_dwordx4 v[60:63], v18, s[4:5]
	global_load_dwordx4 v[68:71], v20, s[4:5]
	global_load_dwordx4 v[64:67], v18, s[4:5] offset:1024
	global_load_dwordx4 v[72:75], v20, s[4:5] offset:1024
	global_load_dword v76, v21, s[4:5]
	v_add_u32_e32 v18, 0x400000, v18
	v_add_u32_e32 v20, 0x400000, v20
	v_add_u32_e32 v21, 0x2000, v21
	global_load_dwordx4 v[78:81], v18, s[4:5]
	global_load_dwordx4 v[86:89], v20, s[4:5]
	global_load_dwordx4 v[82:85], v18, s[4:5] offset:1024
	global_load_dwordx4 v[90:93], v20, s[4:5] offset:1024
	global_load_dword v94, v21, s[4:5]
	s_waitcnt vmcnt(15)
	v_fmamk_f32 v96, v40, 0x3a800000, v244
	v_rsq_f32_e32 v96, v96
	v_add_u32_e32 v19, 0x3001000, v19
	v_lshlrev_b32_e32 v106, 16, v32
	v_and_b32_e32 v107, 0xffff0000, v32
	v_lshlrev_b32_e32 v108, 16, v24
	v_and_b32_e32 v109, 0xffff0000, v24
	v_pk_mul_f32 v[106:107], v[96:97], v[106:107] op_sel_hi:[0,1]
	v_pk_fma_f32 v[98:99], v[10:11], v[106:107], v[108:109]
	v_lshlrev_b32_e32 v106, 16, v33
	v_and_b32_e32 v107, 0xffff0000, v33
	v_lshlrev_b32_e32 v108, 16, v25
	v_and_b32_e32 v109, 0xffff0000, v25
	v_pk_mul_f32 v[106:107], v[96:97], v[106:107] op_sel_hi:[0,1]
	v_pk_fma_f32 v[100:101], v[12:13], v[106:107], v[108:109]
	v_lshlrev_b32_e32 v106, 16, v34
	v_and_b32_e32 v107, 0xffff0000, v34
	v_lshlrev_b32_e32 v108, 16, v26
	v_and_b32_e32 v109, 0xffff0000, v26
	v_pk_mul_f32 v[106:107], v[96:97], v[106:107] op_sel_hi:[0,1]
	v_pk_fma_f32 v[102:103], v[14:15], v[106:107], v[108:109]
	v_lshlrev_b32_e32 v106, 16, v35
	v_and_b32_e32 v107, 0xffff0000, v35
	v_lshlrev_b32_e32 v108, 16, v27
	v_and_b32_e32 v109, 0xffff0000, v27
	v_pk_mul_f32 v[106:107], v[96:97], v[106:107] op_sel_hi:[0,1]
	v_pk_fma_f32 v[104:105], v[16:17], v[106:107], v[108:109]
	global_store_dwordx4 v23, v[98:101], s[6:7] nt
	global_store_dwordx4 v23, v[102:105], s[6:7] offset:16 nt
	v_lshlrev_b32_e32 v106, 16, v36
	v_and_b32_e32 v107, 0xffff0000, v36
	v_lshlrev_b32_e32 v108, 16, v28
	v_and_b32_e32 v109, 0xffff0000, v28
	v_pk_mul_f32 v[106:107], v[96:97], v[106:107] op_sel_hi:[0,1]
	v_pk_fma_f32 v[98:99], v[2:3], v[106:107], v[108:109]
	v_lshlrev_b32_e32 v106, 16, v37
	v_and_b32_e32 v107, 0xffff0000, v37
	v_lshlrev_b32_e32 v108, 16, v29
	v_and_b32_e32 v109, 0xffff0000, v29
	v_pk_mul_f32 v[106:107], v[96:97], v[106:107] op_sel_hi:[0,1]
	v_pk_fma_f32 v[100:101], v[4:5], v[106:107], v[108:109]
	v_lshlrev_b32_e32 v106, 16, v38
	v_and_b32_e32 v107, 0xffff0000, v38
	v_lshlrev_b32_e32 v108, 16, v30
	v_and_b32_e32 v109, 0xffff0000, v30
	v_pk_mul_f32 v[106:107], v[96:97], v[106:107] op_sel_hi:[0,1]
	v_pk_fma_f32 v[102:103], v[6:7], v[106:107], v[108:109]
	v_lshlrev_b32_e32 v106, 16, v39
	v_and_b32_e32 v107, 0xffff0000, v39
	v_lshlrev_b32_e32 v108, 16, v31
	v_and_b32_e32 v109, 0xffff0000, v31
	v_pk_mul_f32 v[106:107], v[96:97], v[106:107] op_sel_hi:[0,1]
	v_pk_fma_f32 v[104:105], v[8:9], v[106:107], v[108:109]
	global_store_dwordx4 v23, v[98:101], s[6:7] offset:2048 nt
	global_store_dwordx4 v23, v[102:105], s[6:7] offset:2064 nt
	v_add_u32_e32 v18, 0x400000, v18
	v_add_u32_e32 v20, 0x400000, v20
	v_add_u32_e32 v21, 0x2000, v21
	global_load_dwordx4 v[24:27], v18, s[4:5]
	global_load_dwordx4 v[32:35], v20, s[4:5]
	global_load_dwordx4 v[28:31], v18, s[4:5] offset:1024
	global_load_dwordx4 v[36:39], v20, s[4:5] offset:1024
	global_load_dword v40, v21, s[4:5]
	s_waitcnt vmcnt(19)
; __device__ __forceinline__ float bflo(unsigned w) { return __uint_as_float(w << 16); }
; __device__ __forceinline__ float bfhi(unsigned w) { return __uint_as_float(w & 0xffff0000u); }
; __device__ __forceinline__ void resid_rows(bf16_t* R, const bf16_t* Y, const float* ssqY, const float* g, float* rstd_out, float* outf, bool wf32, int row_lo, int row_hi, int yoff, int gw, int NGW, int lane) {
;     ...
;         for (int k = 0; k < RP; ++k) { const int row = row0 + k * NGW; const bool ok = row < row_hi; const int rw = ok ? row : row0;
;             ssv[k] = ssqY[rw];
; #pragma unroll
;             for (int j = 0; j < 2; ++j) { const int c = 8 * lane + 512 * j; rr[k][j] = *(const u32x4*)(R + (size_t)rw * DM + c); oo[k][j] = *(const u32x4*)(Y + (size_t)(rw - yoff) * DM + c); } }
;     ...
;         for (int k = 0; k < RP; ++k) { const int row = row0 + k * NGW; if (row < row_hi) {
;             const float rs = __builtin_amdgcn_rsqf(ssv[k] * (1.0f / DM) + RMS_EPS); float s = 0.f;
; #pragma unroll
;             for (int j = 0; j < 2; ++j) { const int c = 8 * lane + 512 * j; const u32x4 r = rr[k][j], o = oo[k][j]; const f32x4 ga = gv[j][0], gb = gv[j][1];
;                 f32x4 ya, yb; ya[0] = bflo(r.x) + bflo(o.x) * rs * ga[0]; ya[1] = bfhi(r.x) + bfhi(o.x) * rs * ga[1]; ya[2] = bflo(r.y) + bflo(o.y) * rs * ga[2]; ya[3] = bfhi(r.y) + bfhi(o.y) * rs * ga[3];
;                 yb[0] = bflo(r.z) + bflo(o.z) * rs * gb[0]; yb[1] = bfhi(r.z) + bfhi(o.z) * rs * gb[1]; yb[2] = bflo(r.w) + bflo(o.w) * rs * gb[2]; yb[3] = bfhi(r.w) + bfhi(o.w) * rs * gb[3];
;                 if (wf32) { *(f32x4*)(outf + (size_t)row * DM + c) = ya; *(f32x4*)(outf + (size_t)row * DM + c + 4) = yb; }
;                 s += (ya[0] * ya[0] + ya[1] * ya[1]) + (ya[2] * ya[2] + ya[3] * ya[3]) + (yb[0] * yb[0] + yb[1] * yb[1]) + (yb[2] * yb[2] + yb[3] * yb[3]);
;                 u32x4 w; w.x = pk2(ya[0], ya[1]); w.y = pk2(ya[2], ya[3]); w.z = pk2(yb[0], yb[1]); w.w = pk2(yb[2], yb[3]); *(u32x4*)(R + (size_t)row * DM + c) = w; }
	v_fmamk_f32 v96, v58, 0x3a800000, v244
	v_rsq_f32_e32 v96, v96
	v_add_u32_e32 v19, 0x400000, v19
	v_add_u32_e32 v23, 0x800000, v23
	v_lshlrev_b32_e32 v106, 16, v50
	v_and_b32_e32 v107, 0xffff0000, v50
	v_lshlrev_b32_e32 v108, 16, v42
	v_and_b32_e32 v109, 0xffff0000, v42
	v_pk_mul_f32 v[106:107], v[96:97], v[106:107] op_sel_hi:[0,1]
	v_pk_fma_f32 v[98:99], v[10:11], v[106:107], v[108:109]
	v_lshlrev_b32_e32 v106, 16, v51
	v_and_b32_e32 v107, 0xffff0000, v51
	v_lshlrev_b32_e32 v108, 16, v43
	v_and_b32_e32 v109, 0xffff0000, v43
	v_pk_mul_f32 v[106:107], v[96:97], v[106:107] op_sel_hi:[0,1]
	v_pk_fma_f32 v[100:101], v[12:13], v[106:107], v[108:109]
	v_lshlrev_b32_e32 v106, 16, v52
	v_and_b32_e32 v107, 0xffff0000, v52
	v_lshlrev_b32_e32 v108, 16, v44
	v_and_b32_e32 v109, 0xffff0000, v44
	v_pk_mul_f32 v[106:107], v[96:97], v[106:107] op_sel_hi:[0,1]
	v_pk_fma_f32 v[102:103], v[14:15], v[106:107], v[108:109]
	v_lshlrev_b32_e32 v106, 16, v53
	v_and_b32_e32 v107, 0xffff0000, v53
	v_lshlrev_b32_e32 v108, 16, v45
	v_and_b32_e32 v109, 0xffff0000, v45
	v_pk_mul_f32 v[106:107], v[96:97], v[106:107] op_sel_hi:[0,1]
	v_pk_fma_f32 v[104:105], v[16:17], v[106:107], v[108:109]
	global_store_dwordx4 v23, v[98:101], s[6:7] nt
	global_store_dwordx4 v23, v[102:105], s[6:7] offset:16 nt
	v_lshlrev_b32_e32 v106, 16, v54
	v_and_b32_e32 v107, 0xffff0000, v54
	v_lshlrev_b32_e32 v108, 16, v46
	v_and_b32_e32 v109, 0xffff0000, v46
	v_pk_mul_f32 v[106:107], v[96:97], v[106:107] op_sel_hi:[0,1]
	v_pk_fma_f32 v[98:99], v[2:3], v[106:107], v[108:109]
	v_lshlrev_b32_e32 v106, 16, v55
	v_and_b32_e32 v107, 0xffff0000, v55
	v_lshlrev_b32_e32 v108, 16, v47
	v_and_b32_e32 v109, 0xffff0000, v47
	v_pk_mul_f32 v[106:107], v[96:97], v[106:107] op_sel_hi:[0,1]
	v_pk_fma_f32 v[100:101], v[4:5], v[106:107], v[108:109]
	v_lshlrev_b32_e32 v106, 16, v56
	v_and_b32_e32 v107, 0xffff0000, v56
	v_lshlrev_b32_e32 v108, 16, v48
	v_and_b32_e32 v109, 0xffff0000, v48
	v_pk_mul_f32 v[106:107], v[96:97], v[106:107] op_sel_hi:[0,1]
	v_pk_fma_f32 v[102:103], v[6:7], v[106:107], v[108:109]
	v_lshlrev_b32_e32 v106, 16, v57
	v_and_b32_e32 v107, 0xffff0000, v57
	v_lshlrev_b32_e32 v108, 16, v49
	v_and_b32_e32 v109, 0xffff0000, v49
	v_pk_mul_f32 v[106:107], v[96:97], v[106:107] op_sel_hi:[0,1]
	v_pk_fma_f32 v[104:105], v[8:9], v[106:107], v[108:109]
	global_store_dwordx4 v23, v[98:101], s[6:7] offset:2048 nt
	global_store_dwordx4 v23, v[102:105], s[6:7] offset:2064 nt
	v_add_u32_e32 v18, 0x400000, v18
	v_add_u32_e32 v20, 0x400000, v20
	v_add_u32_e32 v21, 0x2000, v21
	global_load_dwordx4 v[42:45], v18, s[4:5]
	global_load_dwordx4 v[50:53], v20, s[4:5]
	global_load_dwordx4 v[46:49], v18, s[4:5] offset:1024
	global_load_dwordx4 v[54:57], v20, s[4:5] offset:1024
	global_load_dword v58, v21, s[4:5]
	s_waitcnt vmcnt(23)
	v_fmamk_f32 v96, v76, 0x3a800000, v244
	v_rsq_f32_e32 v96, v96
	v_add_u32_e32 v19, 0x400000, v19
	v_add_u32_e32 v23, 0x800000, v23
	v_lshlrev_b32_e32 v106, 16, v68
	v_and_b32_e32 v107, 0xffff0000, v68
	v_lshlrev_b32_e32 v108, 16, v60
	v_and_b32_e32 v109, 0xffff0000, v60
	v_pk_mul_f32 v[106:107], v[96:97], v[106:107] op_sel_hi:[0,1]
	v_pk_fma_f32 v[98:99], v[10:11], v[106:107], v[108:109]
	v_lshlrev_b32_e32 v106, 16, v69
	v_and_b32_e32 v107, 0xffff0000, v69
	v_lshlrev_b32_e32 v108, 16, v61
	v_and_b32_e32 v109, 0xffff0000, v61
	v_pk_mul_f32 v[106:107], v[96:97], v[106:107] op_sel_hi:[0,1]
	v_pk_fma_f32 v[100:101], v[12:13], v[106:107], v[108:109]
	v_lshlrev_b32_e32 v106, 16, v70
	v_and_b32_e32 v107, 0xffff0000, v70
	v_lshlrev_b32_e32 v108, 16, v62
	v_and_b32_e32 v109, 0xffff0000, v62
	v_pk_mul_f32 v[106:107], v[96:97], v[106:107] op_sel_hi:[0,1]
	v_pk_fma_f32 v[102:103], v[14:15], v[106:107], v[108:109]
	v_lshlrev_b32_e32 v106, 16, v71
	v_and_b32_e32 v107, 0xffff0000, v71
	v_lshlrev_b32_e32 v108, 16, v63
	v_and_b32_e32 v109, 0xffff0000, v63
	v_pk_mul_f32 v[106:107], v[96:97], v[106:107] op_sel_hi:[0,1]
	v_pk_fma_f32 v[104:105], v[16:17], v[106:107], v[108:109]
	global_store_dwordx4 v23, v[98:101], s[6:7] nt
	global_store_dwordx4 v23, v[102:105], s[6:7] offset:16 nt
	v_lshlrev_b32_e32 v106, 16, v72
	v_and_b32_e32 v107, 0xffff0000, v72
	v_lshlrev_b32_e32 v108, 16, v64
	v_and_b32_e32 v109, 0xffff0000, v64
	v_pk_mul_f32 v[106:107], v[96:97], v[106:107] op_sel_hi:[0,1]
	v_pk_fma_f32 v[98:99], v[2:3], v[106:107], v[108:109]
	v_lshlrev_b32_e32 v106, 16, v73
	v_and_b32_e32 v107, 0xffff0000, v73
	v_lshlrev_b32_e32 v108, 16, v65
	v_and_b32_e32 v109, 0xffff0000, v65
	v_pk_mul_f32 v[106:107], v[96:97], v[106:107] op_sel_hi:[0,1]
	v_pk_fma_f32 v[100:101], v[4:5], v[106:107], v[108:109]
	v_lshlrev_b32_e32 v106, 16, v74
	v_and_b32_e32 v107, 0xffff0000, v74
	v_lshlrev_b32_e32 v108, 16, v66
	v_and_b32_e32 v109, 0xffff0000, v66
	v_pk_mul_f32 v[106:107], v[96:97], v[106:107] op_sel_hi:[0,1]
	v_pk_fma_f32 v[102:103], v[6:7], v[106:107], v[108:109]
	v_lshlrev_b32_e32 v106, 16, v75
	v_and_b32_e32 v107, 0xffff0000, v75
	v_lshlrev_b32_e32 v108, 16, v67
	v_and_b32_e32 v109, 0xffff0000, v67
	v_pk_mul_f32 v[106:107], v[96:97], v[106:107] op_sel_hi:[0,1]
	v_pk_fma_f32 v[104:105], v[8:9], v[106:107], v[108:109]
	global_store_dwordx4 v23, v[98:101], s[6:7] offset:2048 nt
	global_store_dwordx4 v23, v[102:105], s[6:7] offset:2064 nt
	v_add_u32_e32 v18, 0x400000, v18
	v_add_u32_e32 v20, 0x400000, v20
	v_add_u32_e32 v21, 0x2000, v21
	global_load_dwordx4 v[60:63], v18, s[4:5]
	global_load_dwordx4 v[68:71], v20, s[4:5]
	global_load_dwordx4 v[64:67], v18, s[4:5] offset:1024
	global_load_dwordx4 v[72:75], v20, s[4:5] offset:1024
	global_load_dword v76, v21, s[4:5]
	s_waitcnt vmcnt(27)
; __device__ __forceinline__ float bflo(unsigned w) { return __uint_as_float(w << 16); }
; __device__ __forceinline__ float bfhi(unsigned w) { return __uint_as_float(w & 0xffff0000u); }
; __device__ __forceinline__ void resid_rows(bf16_t* R, const bf16_t* Y, const float* ssqY, const float* g, float* rstd_out, float* outf, bool wf32, int row_lo, int row_hi, int yoff, int gw, int NGW, int lane) {
;     ...
;         for (int k = 0; k < RP; ++k) { const int row = row0 + k * NGW; const bool ok = row < row_hi; const int rw = ok ? row : row0;
;             ssv[k] = ssqY[rw];
; #pragma unroll
;             for (int j = 0; j < 2; ++j) { const int c = 8 * lane + 512 * j; rr[k][j] = *(const u32x4*)(R + (size_t)rw * DM + c); oo[k][j] = *(const u32x4*)(Y + (size_t)(rw - yoff) * DM + c); } }
;     ...
;         for (int k = 0; k < RP; ++k) { const int row = row0 + k * NGW; if (row < row_hi) {
;             const float rs = __builtin_amdgcn_rsqf(ssv[k] * (1.0f / DM) + RMS_EPS); float s = 0.f;
; #pragma unroll
;             for (int j = 0; j < 2; ++j) { const int c = 8 * lane + 512 * j; const u32x4 r = rr[k][j], o = oo[k][j]; const f32x4 ga = gv[j][0], gb = gv[j][1];
;                 f32x4 ya, yb; ya[0] = bflo(r.x) + bflo(o.x) * rs * ga[0]; ya[1] = bfhi(r.x) + bfhi(o.x) * rs * ga[1]; ya[2] = bflo(r.y) + bflo(o.y) * rs * ga[2]; ya[3] = bfhi(r.y) + bfhi(o.y) * rs * ga[3];
;                 yb[0] = bflo(r.z) + bflo(o.z) * rs * gb[0]; yb[1] = bfhi(r.z) + bfhi(o.z) * rs * gb[1]; yb[2] = bflo(r.w) + bflo(o.w) * rs * gb[2]; yb[3] = bfhi(r.w) + bfhi(o.w) * rs * gb[3];
;                 if (wf32) { *(f32x4*)(outf + (size_t)row * DM + c) = ya; *(f32x4*)(outf + (size_t)row * DM + c + 4) = yb; }
;                 s += (ya[0] * ya[0] + ya[1] * ya[1]) + (ya[2] * ya[2] + ya[3] * ya[3]) + (yb[0] * yb[0] + yb[1] * yb[1]) + (yb[2] * yb[2] + yb[3] * yb[3]);
;                 u32x4 w; w.x = pk2(ya[0], ya[1]); w.y = pk2(ya[2], ya[3]); w.z = pk2(yb[0], yb[1]); w.w = pk2(yb[2], yb[3]); *(u32x4*)(R + (size_t)row * DM + c) = w; }
	v_fmamk_f32 v96, v94, 0x3a800000, v244
	v_rsq_f32_e32 v96, v96
	v_add_u32_e32 v19, 0x400000, v19
	v_add_u32_e32 v23, 0x800000, v23
	v_lshlrev_b32_e32 v106, 16, v86
	v_and_b32_e32 v107, 0xffff0000, v86
	v_lshlrev_b32_e32 v108, 16, v78
	v_and_b32_e32 v109, 0xffff0000, v78
	v_pk_mul_f32 v[106:107], v[96:97], v[106:107] op_sel_hi:[0,1]
	v_pk_fma_f32 v[98:99], v[10:11], v[106:107], v[108:109]
	v_lshlrev_b32_e32 v106, 16, v87
	v_and_b32_e32 v107, 0xffff0000, v87
	v_lshlrev_b32_e32 v108, 16, v79
	v_and_b32_e32 v109, 0xffff0000, v79
	v_pk_mul_f32 v[106:107], v[96:97], v[106:107] op_sel_hi:[0,1]
	v_pk_fma_f32 v[100:101], v[12:13], v[106:107], v[108:109]
	v_lshlrev_b32_e32 v106, 16, v88
	v_and_b32_e32 v107, 0xffff0000, v88
	v_lshlrev_b32_e32 v108, 16, v80
	v_and_b32_e32 v109, 0xffff0000, v80
	v_pk_mul_f32 v[106:107], v[96:97], v[106:107] op_sel_hi:[0,1]
	v_pk_fma_f32 v[102:103], v[14:15], v[106:107], v[108:109]
	v_lshlrev_b32_e32 v106, 16, v89
	v_and_b32_e32 v107, 0xffff0000, v89
	v_lshlrev_b32_e32 v108, 16, v81
	v_and_b32_e32 v109, 0xffff0000, v81
	v_pk_mul_f32 v[106:107], v[96:97], v[106:107] op_sel_hi:[0,1]
	v_pk_fma_f32 v[104:105], v[16:17], v[106:107], v[108:109]
	global_store_dwordx4 v23, v[98:101], s[6:7] nt
	global_store_dwordx4 v23, v[102:105], s[6:7] offset:16 nt
	v_lshlrev_b32_e32 v106, 16, v90
	v_and_b32_e32 v107, 0xffff0000, v90
	v_lshlrev_b32_e32 v108, 16, v82
	v_and_b32_e32 v109, 0xffff0000, v82
	v_pk_mul_f32 v[106:107], v[96:97], v[106:107] op_sel_hi:[0,1]
	v_pk_fma_f32 v[98:99], v[2:3], v[106:107], v[108:109]
	v_lshlrev_b32_e32 v106, 16, v91
	v_and_b32_e32 v107, 0xffff0000, v91
	v_lshlrev_b32_e32 v108, 16, v83
	v_and_b32_e32 v109, 0xffff0000, v83
	v_pk_mul_f32 v[106:107], v[96:97], v[106:107] op_sel_hi:[0,1]
	v_pk_fma_f32 v[100:101], v[4:5], v[106:107], v[108:109]
	v_lshlrev_b32_e32 v106, 16, v92
	v_and_b32_e32 v107, 0xffff0000, v92
	v_lshlrev_b32_e32 v108, 16, v84
	v_and_b32_e32 v109, 0xffff0000, v84
	v_pk_mul_f32 v[106:107], v[96:97], v[106:107] op_sel_hi:[0,1]
	v_pk_fma_f32 v[102:103], v[6:7], v[106:107], v[108:109]
	v_lshlrev_b32_e32 v106, 16, v93
	v_and_b32_e32 v107, 0xffff0000, v93
	v_lshlrev_b32_e32 v108, 16, v85
	v_and_b32_e32 v109, 0xffff0000, v85
	v_pk_mul_f32 v[106:107], v[96:97], v[106:107] op_sel_hi:[0,1]
	v_pk_fma_f32 v[104:105], v[8:9], v[106:107], v[108:109]
	global_store_dwordx4 v23, v[98:101], s[6:7] offset:2048 nt
	global_store_dwordx4 v23, v[102:105], s[6:7] offset:2064 nt
	v_add_u32_e32 v18, 0x400000, v18
	v_add_u32_e32 v20, 0x400000, v20
	v_add_u32_e32 v21, 0x2000, v21
	global_load_dwordx4 v[78:81], v18, s[4:5]
	global_load_dwordx4 v[86:89], v20, s[4:5]
	global_load_dwordx4 v[82:85], v18, s[4:5] offset:1024
	global_load_dwordx4 v[90:93], v20, s[4:5] offset:1024
	global_load_dword v94, v21, s[4:5]
	s_waitcnt vmcnt(27)
	v_fmamk_f32 v96, v40, 0x3a800000, v244
	v_rsq_f32_e32 v96, v96
	v_add_u32_e32 v19, 0x400000, v19
	v_add_u32_e32 v23, 0x800000, v23
	v_lshlrev_b32_e32 v106, 16, v32
	v_and_b32_e32 v107, 0xffff0000, v32
	v_lshlrev_b32_e32 v108, 16, v24
	v_and_b32_e32 v109, 0xffff0000, v24
	v_pk_mul_f32 v[106:107], v[96:97], v[106:107] op_sel_hi:[0,1]
	v_pk_fma_f32 v[98:99], v[10:11], v[106:107], v[108:109]
	v_lshlrev_b32_e32 v106, 16, v33
	v_and_b32_e32 v107, 0xffff0000, v33
	v_lshlrev_b32_e32 v108, 16, v25
	v_and_b32_e32 v109, 0xffff0000, v25
	v_pk_mul_f32 v[106:107], v[96:97], v[106:107] op_sel_hi:[0,1]
	v_pk_fma_f32 v[100:101], v[12:13], v[106:107], v[108:109]
	v_lshlrev_b32_e32 v106, 16, v34
	v_and_b32_e32 v107, 0xffff0000, v34
	v_lshlrev_b32_e32 v108, 16, v26
	v_and_b32_e32 v109, 0xffff0000, v26
	v_pk_mul_f32 v[106:107], v[96:97], v[106:107] op_sel_hi:[0,1]
	v_pk_fma_f32 v[102:103], v[14:15], v[106:107], v[108:109]
	v_lshlrev_b32_e32 v106, 16, v35
	v_and_b32_e32 v107, 0xffff0000, v35
	v_lshlrev_b32_e32 v108, 16, v27
	v_and_b32_e32 v109, 0xffff0000, v27
	v_pk_mul_f32 v[106:107], v[96:97], v[106:107] op_sel_hi:[0,1]
	v_pk_fma_f32 v[104:105], v[16:17], v[106:107], v[108:109]
	global_store_dwordx4 v23, v[98:101], s[6:7] nt
	global_store_dwordx4 v23, v[102:105], s[6:7] offset:16 nt
	v_lshlrev_b32_e32 v106, 16, v36
	v_and_b32_e32 v107, 0xffff0000, v36
	v_lshlrev_b32_e32 v108, 16, v28
	v_and_b32_e32 v109, 0xffff0000, v28
	v_pk_mul_f32 v[106:107], v[96:97], v[106:107] op_sel_hi:[0,1]
	v_pk_fma_f32 v[98:99], v[2:3], v[106:107], v[108:109]
	v_lshlrev_b32_e32 v106, 16, v37
	v_and_b32_e32 v107, 0xffff0000, v37
	v_lshlrev_b32_e32 v108, 16, v29
	v_and_b32_e32 v109, 0xffff0000, v29
	v_pk_mul_f32 v[106:107], v[96:97], v[106:107] op_sel_hi:[0,1]
	v_pk_fma_f32 v[100:101], v[4:5], v[106:107], v[108:109]
	v_lshlrev_b32_e32 v106, 16, v38
	v_and_b32_e32 v107, 0xffff0000, v38
	v_lshlrev_b32_e32 v108, 16, v30
	v_and_b32_e32 v109, 0xffff0000, v30
	v_pk_mul_f32 v[106:107], v[96:97], v[106:107] op_sel_hi:[0,1]
	v_pk_fma_f32 v[102:103], v[6:7], v[106:107], v[108:109]
	v_lshlrev_b32_e32 v106, 16, v39
	v_and_b32_e32 v107, 0xffff0000, v39
	v_lshlrev_b32_e32 v108, 16, v31
	v_and_b32_e32 v109, 0xffff0000, v31
	v_pk_mul_f32 v[106:107], v[96:97], v[106:107] op_sel_hi:[0,1]
	v_pk_fma_f32 v[104:105], v[8:9], v[106:107], v[108:109]
	global_store_dwordx4 v23, v[98:101], s[6:7] offset:2048 nt
	global_store_dwordx4 v23, v[102:105], s[6:7] offset:2064 nt
	s_waitcnt vmcnt(22)
; __device__ __forceinline__ float bflo(unsigned w) { return __uint_as_float(w << 16); }
; __device__ __forceinline__ float bfhi(unsigned w) { return __uint_as_float(w & 0xffff0000u); }
; __device__ __forceinline__ void resid_rows(bf16_t* R, const bf16_t* Y, const float* ssqY, const float* g, float* rstd_out, float* outf, bool wf32, int row_lo, int row_hi, int yoff, int gw, int NGW, int lane) {
;     ...
;         for (int k = 0; k < RP; ++k) { const int row = row0 + k * NGW; if (row < row_hi) {
;             const float rs = __builtin_amdgcn_rsqf(ssv[k] * (1.0f / DM) + RMS_EPS); float s = 0.f;
; #pragma unroll
;             for (int j = 0; j < 2; ++j) { const int c = 8 * lane + 512 * j; const u32x4 r = rr[k][j], o = oo[k][j]; const f32x4 ga = gv[j][0], gb = gv[j][1];
;                 f32x4 ya, yb; ya[0] = bflo(r.x) + bflo(o.x) * rs * ga[0]; ya[1] = bfhi(r.x) + bfhi(o.x) * rs * ga[1]; ya[2] = bflo(r.y) + bflo(o.y) * rs * ga[2]; ya[3] = bfhi(r.y) + bfhi(o.y) * rs * ga[3];
;                 yb[0] = bflo(r.z) + bflo(o.z) * rs * gb[0]; yb[1] = bfhi(r.z) + bfhi(o.z) * rs * gb[1]; yb[2] = bflo(r.w) + bflo(o.w) * rs * gb[2]; yb[3] = bfhi(r.w) + bfhi(o.w) * rs * gb[3];
;                 if (wf32) { *(f32x4*)(outf + (size_t)row * DM + c) = ya; *(f32x4*)(outf + (size_t)row * DM + c + 4) = yb; }
;                 s += (ya[0] * ya[0] + ya[1] * ya[1]) + (ya[2] * ya[2] + ya[3] * ya[3]) + (yb[0] * yb[0] + yb[1] * yb[1]) + (yb[2] * yb[2] + yb[3] * yb[3]);
;                 u32x4 w; w.x = pk2(ya[0], ya[1]); w.y = pk2(ya[2], ya[3]); w.z = pk2(yb[0], yb[1]); w.w = pk2(yb[2], yb[3]); *(u32x4*)(R + (size_t)row * DM + c) = w; }
	v_fmamk_f32 v96, v58, 0x3a800000, v244
	v_rsq_f32_e32 v96, v96
	v_add_u32_e32 v19, 0x400000, v19
	v_add_u32_e32 v23, 0x800000, v23
	v_lshlrev_b32_e32 v106, 16, v50
	v_and_b32_e32 v107, 0xffff0000, v50
	v_lshlrev_b32_e32 v108, 16, v42
	v_and_b32_e32 v109, 0xffff0000, v42
	v_pk_mul_f32 v[106:107], v[96:97], v[106:107] op_sel_hi:[0,1]
	v_pk_fma_f32 v[98:99], v[10:11], v[106:107], v[108:109]
	v_lshlrev_b32_e32 v106, 16, v51
	v_and_b32_e32 v107, 0xffff0000, v51
	v_lshlrev_b32_e32 v108, 16, v43
	v_and_b32_e32 v109, 0xffff0000, v43
	v_pk_mul_f32 v[106:107], v[96:97], v[106:107] op_sel_hi:[0,1]
	v_pk_fma_f32 v[100:101], v[12:13], v[106:107], v[108:109]
	v_lshlrev_b32_e32 v106, 16, v52
	v_and_b32_e32 v107, 0xffff0000, v52
	v_lshlrev_b32_e32 v108, 16, v44
	v_and_b32_e32 v109, 0xffff0000, v44
	v_pk_mul_f32 v[106:107], v[96:97], v[106:107] op_sel_hi:[0,1]
	v_pk_fma_f32 v[102:103], v[14:15], v[106:107], v[108:109]
	v_lshlrev_b32_e32 v106, 16, v53
	v_and_b32_e32 v107, 0xffff0000, v53
	v_lshlrev_b32_e32 v108, 16, v45
	v_and_b32_e32 v109, 0xffff0000, v45
	v_pk_mul_f32 v[106:107], v[96:97], v[106:107] op_sel_hi:[0,1]
	v_pk_fma_f32 v[104:105], v[16:17], v[106:107], v[108:109]
	global_store_dwordx4 v23, v[98:101], s[6:7] nt
	global_store_dwordx4 v23, v[102:105], s[6:7] offset:16 nt
	v_lshlrev_b32_e32 v106, 16, v54
	v_and_b32_e32 v107, 0xffff0000, v54
	v_lshlrev_b32_e32 v108, 16, v46
	v_and_b32_e32 v109, 0xffff0000, v46
	v_pk_mul_f32 v[106:107], v[96:97], v[106:107] op_sel_hi:[0,1]
	v_pk_fma_f32 v[98:99], v[2:3], v[106:107], v[108:109]
	v_lshlrev_b32_e32 v106, 16, v55
	v_and_b32_e32 v107, 0xffff0000, v55
	v_lshlrev_b32_e32 v108, 16, v47
	v_and_b32_e32 v109, 0xffff0000, v47
	v_pk_mul_f32 v[106:107], v[96:97], v[106:107] op_sel_hi:[0,1]
	v_pk_fma_f32 v[100:101], v[4:5], v[106:107], v[108:109]
	v_lshlrev_b32_e32 v106, 16, v56
	v_and_b32_e32 v107, 0xffff0000, v56
	v_lshlrev_b32_e32 v108, 16, v48
	v_and_b32_e32 v109, 0xffff0000, v48
	v_pk_mul_f32 v[106:107], v[96:97], v[106:107] op_sel_hi:[0,1]
	v_pk_fma_f32 v[102:103], v[6:7], v[106:107], v[108:109]
	v_lshlrev_b32_e32 v106, 16, v57
	v_and_b32_e32 v107, 0xffff0000, v57
	v_lshlrev_b32_e32 v108, 16, v49
	v_and_b32_e32 v109, 0xffff0000, v49
	v_pk_mul_f32 v[106:107], v[96:97], v[106:107] op_sel_hi:[0,1]
	v_pk_fma_f32 v[104:105], v[8:9], v[106:107], v[108:109]
	global_store_dwordx4 v23, v[98:101], s[6:7] offset:2048 nt
	global_store_dwordx4 v23, v[102:105], s[6:7] offset:2064 nt
	s_waitcnt vmcnt(17)
; __device__ __forceinline__ float bflo(unsigned w) { return __uint_as_float(w << 16); }
; __device__ __forceinline__ float bfhi(unsigned w) { return __uint_as_float(w & 0xffff0000u); }
; __device__ __forceinline__ void resid_rows(bf16_t* R, const bf16_t* Y, const float* ssqY, const float* g, float* rstd_out, float* outf, bool wf32, int row_lo, int row_hi, int yoff, int gw, int NGW, int lane) {
;     ...
;         for (int k = 0; k < RP; ++k) { const int row = row0 + k * NGW; if (row < row_hi) {
;             const float rs = __builtin_amdgcn_rsqf(ssv[k] * (1.0f / DM) + RMS_EPS); float s = 0.f;
; #pragma unroll
;             for (int j = 0; j < 2; ++j) { const int c = 8 * lane + 512 * j; const u32x4 r = rr[k][j], o = oo[k][j]; const f32x4 ga = gv[j][0], gb = gv[j][1];
;                 f32x4 ya, yb; ya[0] = bflo(r.x) + bflo(o.x) * rs * ga[0]; ya[1] = bfhi(r.x) + bfhi(o.x) * rs * ga[1]; ya[2] = bflo(r.y) + bflo(o.y) * rs * ga[2]; ya[3] = bfhi(r.y) + bfhi(o.y) * rs * ga[3];
;                 yb[0] = bflo(r.z) + bflo(o.z) * rs * gb[0]; yb[1] = bfhi(r.z) + bfhi(o.z) * rs * gb[1]; yb[2] = bflo(r.w) + bflo(o.w) * rs * gb[2]; yb[3] = bfhi(r.w) + bfhi(o.w) * rs * gb[3];
;                 if (wf32) { *(f32x4*)(outf + (size_t)row * DM + c) = ya; *(f32x4*)(outf + (size_t)row * DM + c + 4) = yb; }
;                 s += (ya[0] * ya[0] + ya[1] * ya[1]) + (ya[2] * ya[2] + ya[3] * ya[3]) + (yb[0] * yb[0] + yb[1] * yb[1]) + (yb[2] * yb[2] + yb[3] * yb[3]);
;                 u32x4 w; w.x = pk2(ya[0], ya[1]); w.y = pk2(ya[2], ya[3]); w.z = pk2(yb[0], yb[1]); w.w = pk2(yb[2], yb[3]); *(u32x4*)(R + (size_t)row * DM + c) = w; }
	v_fmamk_f32 v96, v76, 0x3a800000, v244
	v_rsq_f32_e32 v96, v96
	v_add_u32_e32 v19, 0x400000, v19
	v_add_u32_e32 v23, 0x800000, v23
	v_lshlrev_b32_e32 v106, 16, v68
	v_and_b32_e32 v107, 0xffff0000, v68
	v_lshlrev_b32_e32 v108, 16, v60
	v_and_b32_e32 v109, 0xffff0000, v60
	v_pk_mul_f32 v[106:107], v[96:97], v[106:107] op_sel_hi:[0,1]
	v_pk_fma_f32 v[98:99], v[10:11], v[106:107], v[108:109]
	v_lshlrev_b32_e32 v106, 16, v69
	v_and_b32_e32 v107, 0xffff0000, v69
	v_lshlrev_b32_e32 v108, 16, v61
	v_and_b32_e32 v109, 0xffff0000, v61
	v_pk_mul_f32 v[106:107], v[96:97], v[106:107] op_sel_hi:[0,1]
	v_pk_fma_f32 v[100:101], v[12:13], v[106:107], v[108:109]
	v_lshlrev_b32_e32 v106, 16, v70
	v_and_b32_e32 v107, 0xffff0000, v70
	v_lshlrev_b32_e32 v108, 16, v62
	v_and_b32_e32 v109, 0xffff0000, v62
	v_pk_mul_f32 v[106:107], v[96:97], v[106:107] op_sel_hi:[0,1]
	v_pk_fma_f32 v[102:103], v[14:15], v[106:107], v[108:109]
	v_lshlrev_b32_e32 v106, 16, v71
	v_and_b32_e32 v107, 0xffff0000, v71
	v_lshlrev_b32_e32 v108, 16, v63
	v_and_b32_e32 v109, 0xffff0000, v63
	v_pk_mul_f32 v[106:107], v[96:97], v[106:107] op_sel_hi:[0,1]
	v_pk_fma_f32 v[104:105], v[16:17], v[106:107], v[108:109]
	global_store_dwordx4 v23, v[98:101], s[6:7] nt
	global_store_dwordx4 v23, v[102:105], s[6:7] offset:16 nt
	v_lshlrev_b32_e32 v106, 16, v72
	v_and_b32_e32 v107, 0xffff0000, v72
	v_lshlrev_b32_e32 v108, 16, v64
	v_and_b32_e32 v109, 0xffff0000, v64
	v_pk_mul_f32 v[106:107], v[96:97], v[106:107] op_sel_hi:[0,1]
	v_pk_fma_f32 v[98:99], v[2:3], v[106:107], v[108:109]
	v_lshlrev_b32_e32 v106, 16, v73
	v_and_b32_e32 v107, 0xffff0000, v73
	v_lshlrev_b32_e32 v108, 16, v65
	v_and_b32_e32 v109, 0xffff0000, v65
	v_pk_mul_f32 v[106:107], v[96:97], v[106:107] op_sel_hi:[0,1]
	v_pk_fma_f32 v[100:101], v[4:5], v[106:107], v[108:109]
	v_lshlrev_b32_e32 v106, 16, v74
	v_and_b32_e32 v107, 0xffff0000, v74
	v_lshlrev_b32_e32 v108, 16, v66
	v_and_b32_e32 v109, 0xffff0000, v66
	v_pk_mul_f32 v[106:107], v[96:97], v[106:107] op_sel_hi:[0,1]
	v_pk_fma_f32 v[102:103], v[6:7], v[106:107], v[108:109]
	v_lshlrev_b32_e32 v106, 16, v75
	v_and_b32_e32 v107, 0xffff0000, v75
	v_lshlrev_b32_e32 v108, 16, v67
	v_and_b32_e32 v109, 0xffff0000, v67
	v_pk_mul_f32 v[106:107], v[96:97], v[106:107] op_sel_hi:[0,1]
	v_pk_fma_f32 v[104:105], v[8:9], v[106:107], v[108:109]
	global_store_dwordx4 v23, v[98:101], s[6:7] offset:2048 nt
	global_store_dwordx4 v23, v[102:105], s[6:7] offset:2064 nt
	s_waitcnt vmcnt(12)
	v_fmamk_f32 v96, v94, 0x3a800000, v244
	v_rsq_f32_e32 v96, v96
	v_add_u32_e32 v19, 0x400000, v19
	v_add_u32_e32 v23, 0x800000, v23
	v_lshlrev_b32_e32 v106, 16, v86
	v_and_b32_e32 v107, 0xffff0000, v86
	v_lshlrev_b32_e32 v108, 16, v78
	v_and_b32_e32 v109, 0xffff0000, v78
	v_pk_mul_f32 v[106:107], v[96:97], v[106:107] op_sel_hi:[0,1]
	v_pk_fma_f32 v[98:99], v[10:11], v[106:107], v[108:109]
	v_lshlrev_b32_e32 v106, 16, v87
	v_and_b32_e32 v107, 0xffff0000, v87
	v_lshlrev_b32_e32 v108, 16, v79
	v_and_b32_e32 v109, 0xffff0000, v79
	v_pk_mul_f32 v[106:107], v[96:97], v[106:107] op_sel_hi:[0,1]
	v_pk_fma_f32 v[100:101], v[12:13], v[106:107], v[108:109]
	v_lshlrev_b32_e32 v106, 16, v88
	v_and_b32_e32 v107, 0xffff0000, v88
	v_lshlrev_b32_e32 v108, 16, v80
	v_and_b32_e32 v109, 0xffff0000, v80
	v_pk_mul_f32 v[106:107], v[96:97], v[106:107] op_sel_hi:[0,1]
	v_pk_fma_f32 v[102:103], v[14:15], v[106:107], v[108:109]
	v_lshlrev_b32_e32 v106, 16, v89
	v_and_b32_e32 v107, 0xffff0000, v89
	v_lshlrev_b32_e32 v108, 16, v81
	v_and_b32_e32 v109, 0xffff0000, v81
	v_pk_mul_f32 v[106:107], v[96:97], v[106:107] op_sel_hi:[0,1]
	v_pk_fma_f32 v[104:105], v[16:17], v[106:107], v[108:109]
	global_store_dwordx4 v23, v[98:101], s[6:7] nt
	global_store_dwordx4 v23, v[102:105], s[6:7] offset:16 nt
	v_lshlrev_b32_e32 v106, 16, v90
	v_and_b32_e32 v107, 0xffff0000, v90
	v_lshlrev_b32_e32 v108, 16, v82
	v_and_b32_e32 v109, 0xffff0000, v82
	v_pk_mul_f32 v[106:107], v[96:97], v[106:107] op_sel_hi:[0,1]
	v_pk_fma_f32 v[98:99], v[2:3], v[106:107], v[108:109]
	v_lshlrev_b32_e32 v106, 16, v91
	v_and_b32_e32 v107, 0xffff0000, v91
	v_lshlrev_b32_e32 v108, 16, v83
	v_and_b32_e32 v109, 0xffff0000, v83
	v_pk_mul_f32 v[106:107], v[96:97], v[106:107] op_sel_hi:[0,1]
	v_pk_fma_f32 v[100:101], v[4:5], v[106:107], v[108:109]
	v_lshlrev_b32_e32 v106, 16, v92
	v_and_b32_e32 v107, 0xffff0000, v92
	v_lshlrev_b32_e32 v108, 16, v84
	v_and_b32_e32 v109, 0xffff0000, v84
	v_pk_mul_f32 v[106:107], v[96:97], v[106:107] op_sel_hi:[0,1]
	v_pk_fma_f32 v[102:103], v[6:7], v[106:107], v[108:109]
	v_lshlrev_b32_e32 v106, 16, v93
	v_and_b32_e32 v107, 0xffff0000, v93
	v_lshlrev_b32_e32 v108, 16, v85
	v_and_b32_e32 v109, 0xffff0000, v85
	v_pk_mul_f32 v[106:107], v[96:97], v[106:107] op_sel_hi:[0,1]
	v_pk_fma_f32 v[104:105], v[8:9], v[106:107], v[108:109]
	global_store_dwordx4 v23, v[98:101], s[6:7] offset:2048 nt
	global_store_dwordx4 v23, v[102:105], s[6:7] offset:2064 nt
